# loop-edge edits: GEMM K-loop counter/pointer SALU in front of the loop-back barrier; attention row-max finish + rescale compare in front of the per-tile barrier (only the branches stay behind)
# baseline (speedup 1.0000x reference)
; #define PG8_STAGE(bufoff, gbase, voff) do { _Pragma("unroll") for (int _i = 0; _i < 2; ++_i) \
;         __builtin_amdgcn_global_load_lds((const unsigned*)((const char*)(gbase) + (voff)[_i]), (PG8_LAS unsigned*)(lds + (bufoff) + ldsw + _i * 8192), 16, 0, 0); } while (0)
; #define PG8_LDA(dst, b, h) do { _Pragma("unroll") for (int m = 0; m < 4; ++m) _Pragma("unroll") for (int k = 0; k < 2; ++k) dst[m][k] = *(const PG8_LAS bf16x8*)(lds + PG8_SA(b, h) + aoff + m * 2048 + k * 1024); } while (0)
; #define PG8_LDB(dst, b, h) do { _Pragma("unroll") for (int n = 0; n < 2; ++n) _Pragma("unroll") for (int k = 0; k < 2; ++k) dst[n][k] = *(const PG8_LAS bf16x8*)(lds + PG8_SB(b, h) + boff + n * 2048 + k * 1024); } while (0)
; #define PG8_MMA(ai, bj, At, Bt) do { __builtin_amdgcn_s_setprio(1); _Pragma("unroll") for (int m = 0; m < 4; ++m) _Pragma("unroll") for (int n = 0; n < 2; ++n) _Pragma("unroll") for (int k = 0; k < 2; ++k) \
;         acc[ai][bj][m][n] = __builtin_amdgcn_mfma_f32_16x16x32_bf16(Bt[n][k], At[m][k], acc[ai][bj][m][n], 0, 0, 0); __builtin_amdgcn_s_setprio(0); } while (0)
; #define PG8_WAIT_V(n) asm volatile("s_waitcnt vmcnt(" #n ")" ::: "memory")
; #define PG8_WAIT_L(n) asm volatile("s_waitcnt lgkmcnt(" #n ")" ::: "memory")
; #define PG8_BAR __builtin_amdgcn_s_barrier()
; #define PG8_SCHED __builtin_amdgcn_sched_barrier(0)
; template <class Epi, class Sched, bool ALIGN_EPI = false, bool SP2 = false>
; __device__ __forceinline__ void gemm_phase(PG8_LAS unsigned char* lds, const Gemm g, const Sched& S, const Epi& E) {
;     ...
;             PG8_LDB(B0, 0, 0); PG8_LDB(B1, 0, 1); PG8_SCHED; PG8_LDA(At, 0, 0); PG8_STAGE(PG8_SA(1, 1), a1 + hstep, voffA);
;             PG8_WAIT_V(8); PG8_WAIT_L(0); PG8_BAR; PG8_MMA(0, 0, At, B0); PG8_MMA(0, 1, At, B1); PG8_BAR; PG8_SCHED;
;             PG8_LDA(At, 0, 1); PG8_STAGE(PG8_SB(0, 0), b2, voffB); PG8_STAGE(PG8_SB(0, 1), b2 + hstep, voffB); PG8_STAGE(PG8_SA(0, 0), a2, voffA);
;             PG8_WAIT_V(8); PG8_WAIT_L(0); PG8_BAR; PG8_MMA(1, 0, At, B0); PG8_MMA(1, 1, At, B1); PG8_BAR; PG8_SCHED;
.LBB0_124:
	ds_read_b128 v[150:153], v161
	ds_read_b128 v[154:157], v161 offset:1024
	ds_read_b128 v[166:169], v161 offset:2048
	ds_read_b128 v[170:173], v161 offset:3072
	ds_read_b128 v[174:177], v162
	ds_read_b128 v[178:181], v162 offset:1024
	ds_read_b128 v[182:185], v162 offset:2048
	ds_read_b128 v[186:189], v162 offset:3072
	s_add_u32 s4, s36, 0xfff80080
	s_addc_u32 s5, s37, -1
	s_cmp_eq_u32 s69, 28
	s_cselect_b32 s41, s9, s5
	s_cselect_b32 s40, s27, s4
	s_cselect_b32 s39, s25, s68
	s_cselect_b32 s38, s35, s67
	s_add_i32 m0, s49, 0xc000
	ds_read_b128 v[190:193], v163
	ds_read_b128 v[194:197], v163 offset:1024
	ds_read_b128 v[198:201], v163 offset:2048
	ds_read_b128 v[202:205], v163 offset:3072
	ds_read_b128 v[206:209], v163 offset:4096
	ds_read_b128 v[210:213], v163 offset:5120
	ds_read_b128 v[214:217], v163 offset:6144
	ds_read_b128 v[218:221], v163 offset:7168
	global_load_lds_dwordx4 v140, s[36:37]
	s_add_i32 m0, s49, 0xe000
	s_nop 0
	global_load_lds_dwordx4 v142, s[36:37]
	s_waitcnt vmcnt(8)
	s_waitcnt lgkmcnt(0)
	s_barrier
	s_setprio 1
	s_waitcnt lgkmcnt(0)
	v_mfma_f32_16x16x32_bf16 v[126:129], v[150:153], v[190:193], v[126:129]
	v_mfma_f32_16x16x32_bf16 v[122:125], v[166:169], v[190:193], v[122:125]
	v_mfma_f32_16x16x32_bf16 v[110:113], v[150:153], v[198:201], v[110:113]
	v_mfma_f32_16x16x32_bf16 v[106:109], v[166:169], v[198:201], v[106:109]
	v_mfma_f32_16x16x32_bf16 v[94:97], v[150:153], v[206:209], v[94:97]
	v_mfma_f32_16x16x32_bf16 v[90:93], v[166:169], v[206:209], v[90:93]
	v_mfma_f32_16x16x32_bf16 v[78:81], v[150:153], v[214:217], v[78:81]
	v_mfma_f32_16x16x32_bf16 v[74:77], v[166:169], v[214:217], v[74:77]
	v_mfma_f32_16x16x32_bf16 v[126:129], v[154:157], v[194:197], v[126:129]
	v_mfma_f32_16x16x32_bf16 v[122:125], v[170:173], v[194:197], v[122:125]
	v_mfma_f32_16x16x32_bf16 v[110:113], v[154:157], v[202:205], v[110:113]
	v_mfma_f32_16x16x32_bf16 v[106:109], v[170:173], v[202:205], v[106:109]
	v_mfma_f32_16x16x32_bf16 v[94:97], v[154:157], v[210:213], v[94:97]
	v_mfma_f32_16x16x32_bf16 v[90:93], v[170:173], v[210:213], v[90:93]
	v_mfma_f32_16x16x32_bf16 v[78:81], v[154:157], v[218:221], v[78:81]
	v_mfma_f32_16x16x32_bf16 v[74:77], v[170:173], v[218:221], v[74:77]
	s_setprio 0
	s_setprio 1
	v_mfma_f32_16x16x32_bf16 v[118:121], v[174:177], v[190:193], v[118:121]
	v_mfma_f32_16x16x32_bf16 v[114:117], v[182:185], v[190:193], v[114:117]
	v_mfma_f32_16x16x32_bf16 v[102:105], v[174:177], v[198:201], v[102:105]
	v_mfma_f32_16x16x32_bf16 v[98:101], v[182:185], v[198:201], v[98:101]
	v_mfma_f32_16x16x32_bf16 v[86:89], v[174:177], v[206:209], v[86:89]
	v_mfma_f32_16x16x32_bf16 v[82:85], v[182:185], v[206:209], v[82:85]
	v_mfma_f32_16x16x32_bf16 v[70:73], v[174:177], v[214:217], v[70:73]
	v_mfma_f32_16x16x32_bf16 v[66:69], v[182:185], v[214:217], v[66:69]
	v_mfma_f32_16x16x32_bf16 v[118:121], v[178:181], v[194:197], v[118:121]
	v_mfma_f32_16x16x32_bf16 v[114:117], v[186:189], v[194:197], v[114:117]
	v_mfma_f32_16x16x32_bf16 v[102:105], v[178:181], v[202:205], v[102:105]
	v_mfma_f32_16x16x32_bf16 v[98:101], v[186:189], v[202:205], v[98:101]
	v_mfma_f32_16x16x32_bf16 v[86:89], v[178:181], v[210:213], v[86:89]
	v_mfma_f32_16x16x32_bf16 v[82:85], v[186:189], v[210:213], v[82:85]
	v_mfma_f32_16x16x32_bf16 v[70:73], v[178:181], v[218:221], v[70:73]
	v_mfma_f32_16x16x32_bf16 v[66:69], v[186:189], v[218:221], v[66:69]
	s_setprio 0
	s_barrier
	s_add_i32 s4, s64, s48
	s_mov_b32 m0, s4
	ds_read_b128 v[190:193], v163 offset:16384
	ds_read_b128 v[194:197], v163 offset:17408
	ds_read_b128 v[198:201], v163 offset:18432
	ds_read_b128 v[202:205], v163 offset:19456
	ds_read_b128 v[206:209], v163 offset:20480
	ds_read_b128 v[210:213], v163 offset:21504
	ds_read_b128 v[214:217], v163 offset:22528
	ds_read_b128 v[218:221], v163 offset:23552
	global_load_lds_dwordx4 v132, s[38:39]
	s_add_i32 m0, s4, 0x2000
	s_add_u32 s70, s38, 0x80000
	s_addc_u32 s71, s39, 0
	s_add_i32 s4, s65, s48
	global_load_lds_dwordx4 v136, s[38:39]
	s_mov_b32 m0, s4
	s_nop 0
	global_load_lds_dwordx4 v132, s[70:71]
	s_add_i32 m0, s4, 0x2000
	s_nop 0
	global_load_lds_dwordx4 v136, s[70:71]
	s_waitcnt vmcnt(6)
	s_waitcnt lgkmcnt(0)
	s_barrier
	s_setprio 1
	s_waitcnt lgkmcnt(0)
	v_mfma_f32_16x16x32_bf16 v[62:65], v[150:153], v[190:193], v[62:65]
	v_mfma_f32_16x16x32_bf16 v[58:61], v[166:169], v[190:193], v[58:61]
	v_mfma_f32_16x16x32_bf16 v[46:49], v[150:153], v[198:201], v[46:49]
	v_mfma_f32_16x16x32_bf16 v[42:45], v[166:169], v[198:201], v[42:45]
	v_mfma_f32_16x16x32_bf16 v[30:33], v[150:153], v[206:209], v[30:33]
	v_mfma_f32_16x16x32_bf16 v[26:29], v[166:169], v[206:209], v[26:29]
	v_mfma_f32_16x16x32_bf16 v[14:17], v[150:153], v[214:217], v[14:17]
	v_mfma_f32_16x16x32_bf16 v[10:13], v[166:169], v[214:217], v[10:13]
	v_mfma_f32_16x16x32_bf16 v[62:65], v[154:157], v[194:197], v[62:65]
	v_mfma_f32_16x16x32_bf16 v[58:61], v[170:173], v[194:197], v[58:61]
	v_mfma_f32_16x16x32_bf16 v[46:49], v[154:157], v[202:205], v[46:49]
	v_mfma_f32_16x16x32_bf16 v[42:45], v[170:173], v[202:205], v[42:45]
	v_mfma_f32_16x16x32_bf16 v[30:33], v[154:157], v[210:213], v[30:33]
	v_mfma_f32_16x16x32_bf16 v[26:29], v[170:173], v[210:213], v[26:29]
	v_mfma_f32_16x16x32_bf16 v[14:17], v[154:157], v[218:221], v[14:17]
	v_mfma_f32_16x16x32_bf16 v[10:13], v[170:173], v[218:221], v[10:13]
	s_setprio 0
	s_setprio 1
	v_mfma_f32_16x16x32_bf16 v[54:57], v[174:177], v[190:193], v[54:57]
	v_mfma_f32_16x16x32_bf16 v[50:53], v[182:185], v[190:193], v[50:53]
	v_mfma_f32_16x16x32_bf16 v[38:41], v[174:177], v[198:201], v[38:41]
	v_mfma_f32_16x16x32_bf16 v[34:37], v[182:185], v[198:201], v[34:37]
	v_mfma_f32_16x16x32_bf16 v[22:25], v[174:177], v[206:209], v[22:25]
	v_mfma_f32_16x16x32_bf16 v[18:21], v[182:185], v[206:209], v[18:21]
	v_mfma_f32_16x16x32_bf16 v[6:9], v[174:177], v[214:217], v[6:9]
	v_mfma_f32_16x16x32_bf16 v[2:5], v[182:185], v[214:217], v[2:5]
	v_mfma_f32_16x16x32_bf16 v[54:57], v[178:181], v[194:197], v[54:57]
	v_mfma_f32_16x16x32_bf16 v[50:53], v[186:189], v[194:197], v[50:53]
	v_mfma_f32_16x16x32_bf16 v[38:41], v[178:181], v[202:205], v[38:41]
	v_mfma_f32_16x16x32_bf16 v[34:37], v[186:189], v[202:205], v[34:37]
	v_mfma_f32_16x16x32_bf16 v[22:25], v[178:181], v[210:213], v[22:25]
	v_mfma_f32_16x16x32_bf16 v[18:21], v[186:189], v[210:213], v[18:21]
	v_mfma_f32_16x16x32_bf16 v[6:9], v[178:181], v[218:221], v[6:9]
	v_mfma_f32_16x16x32_bf16 v[2:5], v[186:189], v[218:221], v[2:5]
	s_setprio 0
	s_barrier
; #define PG8_STAGE(bufoff, gbase, voff) do { _Pragma("unroll") for (int _i = 0; _i < 2; ++_i) \
;         __builtin_amdgcn_global_load_lds((const unsigned*)((const char*)(gbase) + (voff)[_i]), (PG8_LAS unsigned*)(lds + (bufoff) + ldsw + _i * 8192), 16, 0, 0); } while (0)
; #define PG8_LDA(dst, b, h) do { _Pragma("unroll") for (int m = 0; m < 4; ++m) _Pragma("unroll") for (int k = 0; k < 2; ++k) dst[m][k] = *(const PG8_LAS bf16x8*)(lds + PG8_SA(b, h) + aoff + m * 2048 + k * 1024); } while (0)
; #define PG8_LDB(dst, b, h) do { _Pragma("unroll") for (int n = 0; n < 2; ++n) _Pragma("unroll") for (int k = 0; k < 2; ++k) dst[n][k] = *(const PG8_LAS bf16x8*)(lds + PG8_SB(b, h) + boff + n * 2048 + k * 1024); } while (0)
; #define PG8_MMA(ai, bj, At, Bt) do { __builtin_amdgcn_s_setprio(1); _Pragma("unroll") for (int m = 0; m < 4; ++m) _Pragma("unroll") for (int n = 0; n < 2; ++n) _Pragma("unroll") for (int k = 0; k < 2; ++k) \
;         acc[ai][bj][m][n] = __builtin_amdgcn_mfma_f32_16x16x32_bf16(Bt[n][k], At[m][k], acc[ai][bj][m][n], 0, 0, 0); __builtin_amdgcn_s_setprio(0); } while (0)
; #define PG8_WAIT_V(n) asm volatile("s_waitcnt vmcnt(" #n ")" ::: "memory")
; #define PG8_WAIT_L(n) asm volatile("s_waitcnt lgkmcnt(" #n ")" ::: "memory")
; #define PG8_BAR __builtin_amdgcn_s_barrier()
; #define PG8_SCHED __builtin_amdgcn_sched_barrier(0)
; template <class Epi, class Sched, bool ALIGN_EPI = false, bool SP2 = false>
; __device__ __forceinline__ void gemm_phase(PG8_LAS unsigned char* lds, const Gemm g, const Sched& S, const Epi& E) {
;     ...
;             PG8_LDB(B0, 1, 0); PG8_LDB(B1, 1, 1); PG8_SCHED; PG8_LDA(At, 1, 0); PG8_STAGE(PG8_SA(0, 1), a2 + hstep, voffA);
;             PG8_WAIT_V(8); PG8_WAIT_L(0); PG8_BAR; PG8_MMA(0, 0, At, B0); PG8_MMA(0, 1, At, B1); PG8_BAR; PG8_SCHED;
;             PG8_LDA(At, 1, 1); PG8_STAGE(PG8_SB(1, 0), b3, voffB); PG8_STAGE(PG8_SB(1, 1), b3 + hstep, voffB); PG8_STAGE(PG8_SA(1, 0), a3, voffA);
;             PG8_WAIT_V(8); PG8_WAIT_L(0); PG8_BAR; PG8_MMA(1, 0, At, B0); PG8_MMA(1, 1, At, B1); PG8_BAR; PG8_SCHED;
	s_add_i32 s4, 0, 0x18000
	v_add_u32_e32 v138, s4, v159
	s_add_i32 s5, 0, 0x1c000
	ds_read_b128 v[150:153], v138
	ds_read_b128 v[154:157], v138 offset:1024
	ds_read_b128 v[166:169], v138 offset:2048
	ds_read_b128 v[170:173], v138 offset:3072
	v_add_u32_e32 v138, s5, v159
	ds_read_b128 v[174:177], v138
	ds_read_b128 v[178:181], v138 offset:1024
	ds_read_b128 v[182:185], v138 offset:2048
	ds_read_b128 v[186:189], v138 offset:3072
	s_add_u32 s70, s40, 0x80000
	s_addc_u32 s71, s41, 0
	s_mov_b32 m0, s49
	s_nop 0
	global_load_lds_dwordx4 v130, s[40:41]
	s_mov_b32 m0, s50
	s_nop 0
	global_load_lds_dwordx4 v134, s[40:41]
	s_mov_b32 m0, s51
	ds_read_b128 v[190:193], v163 offset:32768
	ds_read_b128 v[194:197], v163 offset:33792
	ds_read_b128 v[198:201], v163 offset:34816
	ds_read_b128 v[202:205], v163 offset:35840
	ds_read_b128 v[206:209], v163 offset:36864
	ds_read_b128 v[210:213], v163 offset:37888
	ds_read_b128 v[214:217], v163 offset:38912
	ds_read_b128 v[218:221], v163 offset:39936
	global_load_lds_dwordx4 v130, s[70:71]
	s_mov_b32 m0, s52
	s_nop 0
	global_load_lds_dwordx4 v134, s[70:71]
	s_waitcnt vmcnt(8)
	s_waitcnt lgkmcnt(0)
	s_barrier
	s_setprio 1
	s_waitcnt lgkmcnt(0)
	v_mfma_f32_16x16x32_bf16 v[126:129], v[150:153], v[190:193], v[126:129]
	v_mfma_f32_16x16x32_bf16 v[122:125], v[166:169], v[190:193], v[122:125]
	v_mfma_f32_16x16x32_bf16 v[110:113], v[150:153], v[198:201], v[110:113]
	v_mfma_f32_16x16x32_bf16 v[106:109], v[166:169], v[198:201], v[106:109]
	v_mfma_f32_16x16x32_bf16 v[94:97], v[150:153], v[206:209], v[94:97]
	v_mfma_f32_16x16x32_bf16 v[90:93], v[166:169], v[206:209], v[90:93]
	v_mfma_f32_16x16x32_bf16 v[78:81], v[150:153], v[214:217], v[78:81]
	v_mfma_f32_16x16x32_bf16 v[74:77], v[166:169], v[214:217], v[74:77]
	v_mfma_f32_16x16x32_bf16 v[126:129], v[154:157], v[194:197], v[126:129]
	v_mfma_f32_16x16x32_bf16 v[122:125], v[170:173], v[194:197], v[122:125]
	v_mfma_f32_16x16x32_bf16 v[110:113], v[154:157], v[202:205], v[110:113]
	v_mfma_f32_16x16x32_bf16 v[106:109], v[170:173], v[202:205], v[106:109]
	v_mfma_f32_16x16x32_bf16 v[94:97], v[154:157], v[210:213], v[94:97]
	v_mfma_f32_16x16x32_bf16 v[90:93], v[170:173], v[210:213], v[90:93]
	v_mfma_f32_16x16x32_bf16 v[78:81], v[154:157], v[218:221], v[78:81]
	v_mfma_f32_16x16x32_bf16 v[74:77], v[170:173], v[218:221], v[74:77]
	s_setprio 0
	s_setprio 1
	v_mfma_f32_16x16x32_bf16 v[118:121], v[174:177], v[190:193], v[118:121]
	v_mfma_f32_16x16x32_bf16 v[114:117], v[182:185], v[190:193], v[114:117]
	v_mfma_f32_16x16x32_bf16 v[102:105], v[174:177], v[198:201], v[102:105]
	v_mfma_f32_16x16x32_bf16 v[98:101], v[182:185], v[198:201], v[98:101]
	v_mfma_f32_16x16x32_bf16 v[86:89], v[174:177], v[206:209], v[86:89]
	v_mfma_f32_16x16x32_bf16 v[82:85], v[182:185], v[206:209], v[82:85]
	v_mfma_f32_16x16x32_bf16 v[70:73], v[174:177], v[214:217], v[70:73]
	v_mfma_f32_16x16x32_bf16 v[66:69], v[182:185], v[214:217], v[66:69]
	v_mfma_f32_16x16x32_bf16 v[118:121], v[178:181], v[194:197], v[118:121]
	v_mfma_f32_16x16x32_bf16 v[114:117], v[186:189], v[194:197], v[114:117]
	v_mfma_f32_16x16x32_bf16 v[102:105], v[178:181], v[202:205], v[102:105]
	v_mfma_f32_16x16x32_bf16 v[98:101], v[186:189], v[202:205], v[98:101]
	v_mfma_f32_16x16x32_bf16 v[86:89], v[178:181], v[210:213], v[86:89]
	v_mfma_f32_16x16x32_bf16 v[82:85], v[186:189], v[210:213], v[82:85]
	v_mfma_f32_16x16x32_bf16 v[70:73], v[178:181], v[218:221], v[70:73]
	v_mfma_f32_16x16x32_bf16 v[66:69], v[186:189], v[218:221], v[66:69]
	s_setprio 0
	s_barrier
	s_add_i32 s4, s4, s48
	s_add_i32 m0, s4, 0xffffff80
	ds_read_b128 v[190:193], v163 offset:49152
	ds_read_b128 v[194:197], v163 offset:50176
	ds_read_b128 v[198:201], v163 offset:51200
	ds_read_b128 v[202:205], v163 offset:52224
	ds_read_b128 v[206:209], v163 offset:53248
	ds_read_b128 v[210:213], v163 offset:54272
	ds_read_b128 v[214:217], v163 offset:55296
	ds_read_b128 v[218:221], v163 offset:56320
	global_load_lds_dwordx4 v132, s[38:39] offset:128
	s_add_i32 m0, s4, 0x1f80
	s_nop 0
	global_load_lds_dwordx4 v136, s[38:39] offset:128
	s_add_u32 s38, s38, 0x80080
	s_addc_u32 s39, s39, 0
	s_add_i32 s4, s5, s48
	s_mov_b32 m0, s4
	s_nop 0
	global_load_lds_dwordx4 v132, s[38:39]
	s_add_i32 m0, s4, 0x2000
	s_nop 0
	global_load_lds_dwordx4 v136, s[38:39]
	s_add_i32 m0, s58, 0xffffff80
	s_nop 0
	global_load_lds_dwordx4 v130, s[40:41] offset:128
	s_add_i32 m0, s59, 0xffffff80
	s_nop 0
	global_load_lds_dwordx4 v134, s[40:41] offset:128
	s_waitcnt vmcnt(8)
	s_waitcnt lgkmcnt(0)
	s_barrier
	s_setprio 1
	s_waitcnt lgkmcnt(0)
	v_mfma_f32_16x16x32_bf16 v[62:65], v[150:153], v[190:193], v[62:65]
	v_mfma_f32_16x16x32_bf16 v[58:61], v[166:169], v[190:193], v[58:61]
	v_mfma_f32_16x16x32_bf16 v[46:49], v[150:153], v[198:201], v[46:49]
	v_mfma_f32_16x16x32_bf16 v[42:45], v[166:169], v[198:201], v[42:45]
	v_mfma_f32_16x16x32_bf16 v[30:33], v[150:153], v[206:209], v[30:33]
	v_mfma_f32_16x16x32_bf16 v[26:29], v[166:169], v[206:209], v[26:29]
	v_mfma_f32_16x16x32_bf16 v[14:17], v[150:153], v[214:217], v[14:17]
	v_mfma_f32_16x16x32_bf16 v[10:13], v[166:169], v[214:217], v[10:13]
	v_mfma_f32_16x16x32_bf16 v[62:65], v[154:157], v[194:197], v[62:65]
	v_mfma_f32_16x16x32_bf16 v[58:61], v[170:173], v[194:197], v[58:61]
	v_mfma_f32_16x16x32_bf16 v[46:49], v[154:157], v[202:205], v[46:49]
	v_mfma_f32_16x16x32_bf16 v[42:45], v[170:173], v[202:205], v[42:45]
	v_mfma_f32_16x16x32_bf16 v[30:33], v[154:157], v[210:213], v[30:33]
	v_mfma_f32_16x16x32_bf16 v[26:29], v[170:173], v[210:213], v[26:29]
	v_mfma_f32_16x16x32_bf16 v[14:17], v[154:157], v[218:221], v[14:17]
	v_mfma_f32_16x16x32_bf16 v[10:13], v[170:173], v[218:221], v[10:13]
	s_setprio 0
	s_setprio 1
	v_mfma_f32_16x16x32_bf16 v[54:57], v[174:177], v[190:193], v[54:57]
	v_mfma_f32_16x16x32_bf16 v[50:53], v[182:185], v[190:193], v[50:53]
	v_mfma_f32_16x16x32_bf16 v[38:41], v[174:177], v[198:201], v[38:41]
	v_mfma_f32_16x16x32_bf16 v[34:37], v[182:185], v[198:201], v[34:37]
	v_mfma_f32_16x16x32_bf16 v[22:25], v[174:177], v[206:209], v[22:25]
	v_mfma_f32_16x16x32_bf16 v[18:21], v[182:185], v[206:209], v[18:21]
	v_mfma_f32_16x16x32_bf16 v[6:9], v[174:177], v[214:217], v[6:9]
	v_mfma_f32_16x16x32_bf16 v[2:5], v[182:185], v[214:217], v[2:5]
	v_mfma_f32_16x16x32_bf16 v[54:57], v[178:181], v[194:197], v[54:57]
	v_mfma_f32_16x16x32_bf16 v[50:53], v[186:189], v[194:197], v[50:53]
	v_mfma_f32_16x16x32_bf16 v[38:41], v[178:181], v[202:205], v[38:41]
	v_mfma_f32_16x16x32_bf16 v[34:37], v[186:189], v[202:205], v[34:37]
	v_mfma_f32_16x16x32_bf16 v[22:25], v[178:181], v[210:213], v[22:25]
	v_mfma_f32_16x16x32_bf16 v[18:21], v[186:189], v[210:213], v[18:21]
	v_mfma_f32_16x16x32_bf16 v[6:9], v[178:181], v[218:221], v[6:9]
	v_mfma_f32_16x16x32_bf16 v[2:5], v[186:189], v[218:221], v[2:5]
	s_setprio 0
	s_add_i32 s69, s69, 2
	s_add_u32 s36, s36, 0x100
	s_addc_u32 s37, s37, 0
	s_add_u32 s67, s67, 0x100
	s_addc_u32 s68, s68, 0
	s_cmp_gt_u32 s69, 29
	s_barrier
	s_cbranch_scc0 .LBB0_124
	s_and_b64 vcc, exec, s[22:23]
	s_cbranch_vccz .LBB0_127
	s_barrier

; #define SB() __builtin_amdgcn_sched_barrier(0)
; #define MF32(a,b,c) __builtin_amdgcn_mfma_f32_32x32x16_bf16(a,b,c,0,0,0)
; #define EXP1(x) x=__builtin_amdgcn_exp2f((x)-mh_)
; __device__ __forceinline__ bf16x8 vfrag(lds_cptr vp,int i){ const s16x4 lo=vtr(vp+(i&3)*4096+(i>>2)*1024), hh=vtr(vp+(i&3)*4096+(i>>2)*1024+512); return (bf16x8){lo[0],lo[1],lo[2],lo[3],hh[0],hh[1],hh[2],hh[3]}; }
; __device__ __forceinline__ u32x4 packw(const f32x16&p,int base){ u32x4 w; w[0]=cvtpk_s(p[base],p[base+1]); w[1]=cvtpk_s(p[base+2],p[base+3]); w[2]=cvtpk_s(p[base+4],p[base+5]); w[3]=cvtpk_s(p[base+6],p[base+7]); return w; }
; template<int THRL,bool FIRST> __device__ __forceinline__ void step_main(f32x16&p0,f32x16&p1,f32x16&n0,f32x16&n1,St&S,lds_cptr kpn,lds_cptr qp,lds_cptr vp,float*wsf,int r32,int hi,float&rm){
;     ...
;   bf16x8 ka=KF(0),kb=KF(1),kc=KF(2),kd=KF(3),qa=QF(0),qb=QF(1);
;   decide<THRL,FIRST>(rm,S,wsf,r32,hi);
;   u32x4 pw0,pw1,pw2,pw3; const float mh_=S.mhat; const f32x16 z=f32x16{};
;   SB();
;   n0=MF32(ka,qa,z); ka=KF(4); EXP1(p0[0]);EXP1(p0[1]);EXP1(p0[2]); SB();
;   n1=MF32(kb,qa,z); kb=KF(5); qa=QF(2); EXP1(p0[3]);EXP1(p0[4]);EXP1(p0[5]); SB();
;   n0=MF32(kc,qb,n0);   kc=KF(6); EXP1(p0[6]);EXP1(p0[7]);EXP1(p0[8]); SB();
;   n1=MF32(kd,qb,n1);   kd=KF(7); qb=QF(3); EXP1(p0[9]);EXP1(p0[10]);EXP1(p0[11]); SB();
;   bf16x8 vfa=vfrag(vp,0);
;   n0=MF32(ka,qa,n0);   EXP1(p0[12]);EXP1(p0[13]);EXP1(p0[14]); pw0=packw(p0,0); SB();
;   bf16x8 vfb=vfrag(vp,1);
;   n1=MF32(kb,qa,n1);   EXP1(p0[15]);EXP1(p1[0]);EXP1(p1[1]); SB();
;   bf16x8 vfc=vfrag(vp,2);
;   n0=MF32(kc,qb,n0);   EXP1(p1[2]);EXP1(p1[3]);EXP1(p1[4]); pw1=packw(p0,8); SB();
;   bf16x8 vfd=vfrag(vp,3);
;   n1=MF32(kd,qb,n1);   EXP1(p1[5]);EXP1(p1[6]);EXP1(p1[7]); SB();
;     ...
;   float sa=p0[0]+p0[1];
;     ...
;   PVG(0,pw0,vfa,4, p0[2],p0[3],p0[4],p0[5],   do{EXP1(p1[8]);EXP1(p1[9]);}while(0));
;   PVG(1,pw0,vfb,5, p0[6],p0[7],p0[8],p0[9], do{EXP1(p1[10]);EXP1(p1[11]);}while(0));
;   PVG(2,pw0,vfc,6, p0[10],p0[11],p0[12],p0[13], do{EXP1(p1[12]);EXP1(p1[13]);}while(0));
;   PVG(3,pw0,vfd,7, p0[14],p0[15],p1[0],p1[1],   do{EXP1(p1[14]);EXP1(p1[15]);}while(0));
;   PVG(4,pw1,vfa,8, p1[2],p1[3],p1[4],p1[5],   pw2=packw(p1,0));
;   PVG(5,pw1,vfb,9, p1[6],p1[7],p1[8],p1[9], pw3=packw(p1,8));
;   PVG(6,pw1,vfc,10, p1[10],p1[11],p1[12],p1[13], do{}while(0));
;   PVG(7,pw1,vfd,11, p1[14],p1[15],0.f,0.f, do{}while(0));
.LBB0_275:
	s_waitcnt lgkmcnt(1)
	v_mfma_f32_32x32x16_bf16 v[98:113], v[218:221], v[214:217], 0
	ds_read_b128 v[178:181], v249 offset:20480
	v_sub_f32_e32 v82, v131, v247
	v_sub_f32_e32 v17, v130, v247
	v_exp_f32_e32 v190, v82
	v_sub_f32_e32 v82, v132, v247
	v_exp_f32_e32 v17, v17
	v_exp_f32_e32 v191, v82
	v_sub_f32_e32 v82, v133, v247
	v_exp_f32_e32 v192, v82
	v_sub_f32_e32 v82, v134, v247
	v_exp_f32_e32 v193, v82
	v_sub_f32_e32 v82, v135, v247
	v_exp_f32_e32 v194, v82
	v_mfma_f32_32x32x16_bf16 v[82:97], v[210:213], v[214:217], 0
	ds_read_b128 v[182:185], v249 offset:20992
	ds_read_b128 v[186:189], v248 offset:2048
	s_waitcnt lgkmcnt(3)
	v_mfma_f32_32x32x16_bf16 v[98:113], v[12:15], v[8:11], v[98:113]
	ds_read_b128 v[130:133], v249 offset:22528
	v_sub_f32_e32 v134, v136, v247
	v_exp_f32_e32 v195, v134
	v_sub_f32_e32 v134, v137, v247
	v_exp_f32_e32 v196, v134
	v_sub_f32_e32 v134, v138, v247
	v_exp_f32_e32 v197, v134
	v_mfma_f32_32x32x16_bf16 v[82:97], v[4:7], v[8:11], v[82:97]
	ds_read_b128 v[12:15], v249 offset:23040
	ds_read_b128 v[134:137], v248 offset:3072
	v_sub_f32_e32 v138, v139, v247
	v_exp_f32_e32 v198, v138
	v_sub_f32_e32 v138, v140, v247
	v_exp_f32_e32 v199, v138
	v_sub_f32_e32 v138, v141, v247
	v_exp_f32_e32 v200, v138
	s_waitcnt lgkmcnt(3)
	v_mfma_f32_32x32x16_bf16 v[98:113], v[178:181], v[186:189], v[98:113]
	ds_read_b64_tr_b16 v[4:5], v246 offset:40960
	ds_read_b64_tr_b16 v[6:7], v246 offset:41472
	v_sub_f32_e32 v8, v142, v247
	v_exp_f32_e32 v201, v8
	v_sub_f32_e32 v8, v143, v247
	v_exp_f32_e32 v202, v8
	v_sub_f32_e32 v8, v144, v247
	v_exp_f32_e32 v179, v8
	v_cvt_pk_bf16_f32 v8, v17, v190
	v_cvt_pk_bf16_f32 v9, v191, v192
	v_cvt_pk_bf16_f32 v10, v193, v194
	v_cvt_pk_bf16_f32 v11, v195, v196
	v_mfma_f32_32x32x16_bf16 v[82:97], v[182:185], v[186:189], v[82:97]
	ds_read_b64_tr_b16 v[138:139], v246 offset:45056
	ds_read_b64_tr_b16 v[140:141], v246 offset:45568
	v_sub_f32_e32 v114, v114, v247
	v_sub_f32_e32 v142, v145, v247
	v_exp_f32_e32 v181, v114
	v_sub_f32_e32 v114, v115, v247
	v_exp_f32_e32 v180, v142
	v_exp_f32_e32 v203, v114
	s_waitcnt lgkmcnt(4)
	v_mfma_f32_32x32x16_bf16 v[98:113], v[130:133], v[134:137], v[98:113]
	ds_read_b64_tr_b16 v[142:143], v246 offset:49152
	ds_read_b64_tr_b16 v[144:145], v246 offset:49664
	v_sub_f32_e32 v114, v116, v247
	v_exp_f32_e32 v182, v114
	v_sub_f32_e32 v114, v117, v247
	v_exp_f32_e32 v183, v114
	v_sub_f32_e32 v114, v118, v247
	v_exp_f32_e32 v184, v114
	v_cvt_pk_bf16_f32 v114, v197, v198
	v_cvt_pk_bf16_f32 v115, v199, v200
	v_cvt_pk_bf16_f32 v116, v201, v202
	v_cvt_pk_bf16_f32 v117, v179, v180
	v_mfma_f32_32x32x16_bf16 v[82:97], v[12:15], v[134:137], v[82:97]
	ds_read_b64_tr_b16 v[130:131], v246 offset:53248
	ds_read_b64_tr_b16 v[132:133], v246 offset:53760
	v_sub_f32_e32 v118, v119, v247
	v_exp_f32_e32 v185, v118
	v_sub_f32_e32 v118, v120, v247
	v_exp_f32_e32 v186, v118
	v_sub_f32_e32 v118, v121, v247
	v_exp_f32_e32 v187, v118
	s_waitcnt lgkmcnt(6)
	v_mfma_f32_32x32x16_bf16 v[18:33], v[8:11], v[4:7], v[18:33]
	ds_read_b64_tr_b16 v[12:13], v246 offset:41984
	ds_read_b64_tr_b16 v[14:15], v246 offset:42496
	v_sub_f32_e32 v118, v122, v247
	v_exp_f32_e32 v134, v118
	v_sub_f32_e32 v118, v123, v247
	v_exp_f32_e32 v135, v118
	s_waitcnt lgkmcnt(6)
	v_mfma_f32_32x32x16_bf16 v[34:49], v[8:11], v[138:141], v[34:49]
	ds_read_b64_tr_b16 v[4:5], v246 offset:46080
	ds_read_b64_tr_b16 v[6:7], v246 offset:46592
	v_sub_f32_e32 v118, v124, v247
	v_exp_f32_e32 v136, v118
	v_sub_f32_e32 v118, v125, v247
	v_exp_f32_e32 v137, v118
	s_waitcnt lgkmcnt(6)
	v_mfma_f32_32x32x16_bf16 v[50:65], v[8:11], v[142:145], v[50:65]
	ds_read_b64_tr_b16 v[118:119], v246 offset:50176
	ds_read_b64_tr_b16 v[120:121], v246 offset:50688
	v_sub_f32_e32 v122, v126, v247
	v_exp_f32_e32 v138, v122
	v_sub_f32_e32 v122, v127, v247
	v_exp_f32_e32 v139, v122
	s_waitcnt lgkmcnt(6)
	v_mfma_f32_32x32x16_bf16 v[66:81], v[8:11], v[130:133], v[66:81]
	ds_read_b64_tr_b16 v[122:123], v246 offset:54272
	ds_read_b64_tr_b16 v[124:125], v246 offset:54784
	v_sub_f32_e32 v126, v128, v247
	v_exp_f32_e32 v140, v126
	v_sub_f32_e32 v126, v129, v247
	v_exp_f32_e32 v141, v126
	s_waitcnt lgkmcnt(6)
	v_mfma_f32_32x32x16_bf16 v[18:33], v[114:117], v[12:15], v[18:33]
	ds_read_b64_tr_b16 v[8:9], v246 offset:43008
	ds_read_b64_tr_b16 v[10:11], v246 offset:43520
	v_cvt_pk_bf16_f32 v126, v181, v203
	v_cvt_pk_bf16_f32 v127, v182, v183
	v_cvt_pk_bf16_f32 v128, v184, v185
	v_cvt_pk_bf16_f32 v129, v186, v187
	s_waitcnt lgkmcnt(6)
	v_mfma_f32_32x32x16_bf16 v[34:49], v[114:117], v[4:7], v[34:49]
	ds_read_b64_tr_b16 v[12:13], v246 offset:47104
	ds_read_b64_tr_b16 v[14:15], v246 offset:47616
	v_cvt_pk_bf16_f32 v130, v134, v135
	v_cvt_pk_bf16_f32 v131, v136, v137
	v_cvt_pk_bf16_f32 v132, v138, v139
	v_cvt_pk_bf16_f32 v133, v140, v141
	s_waitcnt lgkmcnt(6)
	v_mfma_f32_32x32x16_bf16 v[50:65], v[114:117], v[118:121], v[50:65]
	ds_read_b64_tr_b16 v[4:5], v246 offset:51200
	ds_read_b64_tr_b16 v[6:7], v246 offset:51712
	s_waitcnt lgkmcnt(6)
	v_mfma_f32_32x32x16_bf16 v[66:81], v[114:117], v[122:125], v[66:81]
	ds_read_b64_tr_b16 v[118:119], v246 offset:55296
	ds_read_b64_tr_b16 v[120:121], v246 offset:55808
	s_waitcnt lgkmcnt(6)
; __device__ __forceinline__ float max3f(float a,float b,float c){float r;asm("v_max3_f32 %0, %1, %2, %3":"=v"(r):"v"(a),"v"(b),"v"(c));return r;}
; __device__ __forceinline__ float max2f(float a,float b){float r;asm("v_max_f32_e32 %0, %1, %2":"=v"(r):"v"(a),"v"(b));return r;}
; #define A128_WAITBAR() asm volatile("s_waitcnt vmcnt(0) lgkmcnt(0)\n\ts_barrier":::"memory")
;   #define PVG(i,PW,VF,NEXTI,X0,X1,Y0,Y1,EXTRA) do{ S.o[(i)&3]=MF32(__builtin_bit_cast(bf16x8,PW),VF,S.o[(i)&3]); if((NEXTI)<16){ VF=vfrag(vp,(NEXTI)<16?(NEXTI):0); } sa+=X0; sa+=X1; sa+=Y0; sa+=Y1; EXTRA; SB(); }while(0)
;   #define PINAB() asm volatile("":"+v"(ma),"+v"(mb))
;   #define ROT() do{ ks1=ks2; ks2=(ks2==2*KBUF)?0:ks2+KBUF; }while(0)
; template<int THRL,bool FIRST> __device__ __forceinline__ void step_main(f32x16&p0,f32x16&p1,f32x16&n0,f32x16&n1,St&S,lds_cptr kpn,lds_cptr qp,lds_cptr vp,float*wsf,int r32,int hi,float&rm){
;     ...
;   float ma,mb;
;     ...
;   PVG(8,pw2,vfa,12,0.f,0.f,0.f,0.f, do{ma=max3f(n0[0],n0[1],n1[0]);mb=max3f(n0[2],n0[3],n1[1]);PINAB();}while(0));
;   PVG(9,pw2,vfb,13,0.f,0.f,0.f,0.f, do{ma=max3f(ma,n1[2],n1[3]);mb=max3f(mb,n0[4],n0[5]);PINAB();}while(0));
;   PVG(10,pw2,vfc,14,0.f,0.f,0.f,0.f, do{ma=max3f(ma,n0[6],n0[7]);mb=max3f(mb,n1[4],n1[5]);PINAB();}while(0));
;   PVG(11,pw2,vfd,15,0.f,0.f,0.f,0.f, do{ma=max3f(ma,n1[6],n1[7]);mb=max3f(mb,n0[8],n0[9]);PINAB();}while(0));
;   PVG(12,pw3,vfa,16,0.f,0.f,0.f,0.f, do{ma=max3f(ma,n0[10],n0[11]);mb=max3f(mb,n1[8],n1[9]);PINAB();}while(0));
;   PVG(13,pw3,vfb,16,0.f,0.f,0.f,0.f, do{ma=max3f(ma,n1[10],n1[11]);mb=max3f(mb,n0[12],n0[13]);PINAB();}while(0));
;   PVG(14,pw3,vfc,16,0.f,0.f,0.f,0.f, do{ma=max3f(ma,n0[14],n0[15]);mb=max3f(mb,n1[12],n1[13]);PINAB();}while(0));
;   PVG(15,pw3,vfd,16,0.f,0.f,0.f,0.f, do{ma=max3f(ma,n1[14],n1[15]);ma=max2f(ma,mb);PINAB();}while(0));
;     ...
;   { auto rr=__builtin_amdgcn_permlane32_swap(__float_as_uint(ma),__float_as_uint(ma),false,false); rm=max2f(__uint_as_float(rr[0]),__uint_as_float(rr[1])); }
;     ...
;   S.l_reg+=sa;
; }
; template<int THRL> __device__ __forceinline__ void unit(int qb,const bf16*Q,const bf16*K,const bf16*V,bf16*O,char*shm){
;     ...
;     step_main<THRL,true>(pA0,pA1,pB0,pB1,S,kp0+ks1,qp,vp0,wsf,r32,hi,rm); A128_WAITBAR(); ROT();
;     DMA_K(3,ks2); DMA_V(2,0);
;     step_main<THRL,false>(pB0,pB1,pA0,pA1,S,kp0+ks1,qp,vp0+VBUF,wsf,r32,hi,rm); A128_WAITBAR(); ROT();
	v_mfma_f32_32x32x16_bf16 v[18:33], v[126:129], v[8:11], v[18:33]
	ds_read_b64_tr_b16 v[114:115], v246 offset:44032
	ds_read_b64_tr_b16 v[116:117], v246 offset:44544
	v_max3_f32 v122, v98, v99, v82
	v_max3_f32 v123, v100, v101, v83
	s_nop 0
	s_waitcnt lgkmcnt(6)
	v_mfma_f32_32x32x16_bf16 v[34:49], v[126:129], v[12:15], v[34:49]
	ds_read_b64_tr_b16 v[8:9], v246 offset:48128
	ds_read_b64_tr_b16 v[10:11], v246 offset:48640
	v_max3_f32 v122, v122, v84, v85
	v_max3_f32 v123, v123, v102, v103
	s_nop 0
	s_waitcnt lgkmcnt(6)
	v_mfma_f32_32x32x16_bf16 v[50:65], v[126:129], v[4:7], v[50:65]
	ds_read_b64_tr_b16 v[12:13], v246 offset:52224
	ds_read_b64_tr_b16 v[14:15], v246 offset:52736
	v_max3_f32 v122, v122, v104, v105
	v_max3_f32 v123, v123, v86, v87
	s_nop 0
	s_waitcnt lgkmcnt(6)
	v_mfma_f32_32x32x16_bf16 v[66:81], v[126:129], v[118:121], v[66:81]
	ds_read_b64_tr_b16 v[4:5], v246 offset:56320
	ds_read_b64_tr_b16 v[6:7], v246 offset:56832
	v_max3_f32 v122, v122, v88, v89
	v_max3_f32 v123, v123, v106, v107
	s_nop 0
	s_waitcnt lgkmcnt(6)
	v_mfma_f32_32x32x16_bf16 v[18:33], v[130:133], v[114:117], v[18:33]
	v_max3_f32 v118, v122, v108, v109
	v_max3_f32 v119, v123, v90, v91
	s_nop 0
	s_waitcnt lgkmcnt(4)
	v_mfma_f32_32x32x16_bf16 v[34:49], v[130:133], v[8:11], v[34:49]
	v_max3_f32 v114, v118, v92, v93
	v_max3_f32 v115, v119, v110, v111
	s_nop 0
	s_waitcnt lgkmcnt(2)
	v_mfma_f32_32x32x16_bf16 v[50:65], v[130:133], v[12:15], v[50:65]
	v_max3_f32 v8, v114, v112, v113
	v_max3_f32 v9, v115, v94, v95
	s_nop 0
	s_waitcnt lgkmcnt(0)
	v_mfma_f32_32x32x16_bf16 v[66:81], v[130:133], v[4:7], v[66:81]
	v_max3_f32 v8, v8, v96, v97
	s_nop 0
	v_max_f32_e32 v8, v8, v9
	s_nop 0
	s_nop 0
	v_mov_b32_e32 v4, v8
	s_nop 1
	v_permlane32_swap_b32_e32 v8, v4
	v_max_f32_e32 v178, v8, v4
	v_add_f32_e32 v4, v17, v190
	v_add_f32_e32 v4, v191, v4
	v_add_f32_e32 v4, v192, v4
	v_add_f32_e32 v4, v193, v4
	v_add_f32_e32 v4, v194, v4
	v_add_f32_e32 v4, v195, v4
	v_add_f32_e32 v4, v196, v4
	v_add_f32_e32 v4, v197, v4
	v_add_f32_e32 v4, v198, v4
	v_add_f32_e32 v4, v199, v4
	v_add_f32_e32 v4, v200, v4
	v_add_f32_e32 v4, v201, v4
	v_add_f32_e32 v4, v202, v4
	v_add_f32_e32 v4, v179, v4
	v_add_f32_e32 v4, v180, v4
	v_add_f32_e32 v4, v181, v4
	v_add_f32_e32 v4, v203, v4
	v_add_f32_e32 v4, v182, v4
	v_add_f32_e32 v4, v183, v4
	v_add_f32_e32 v4, v184, v4
	v_add_f32_e32 v4, v185, v4
	v_add_f32_e32 v4, v186, v4
	v_add_f32_e32 v4, v187, v4
	v_add_f32_e32 v4, v134, v4
	v_add_f32_e32 v4, v135, v4
	v_add_f32_e32 v4, v136, v4
	v_add_f32_e32 v4, v137, v4
	v_add_f32_e32 v4, v138, v4
	v_add_f32_e32 v4, v139, v4
	v_add_f32_e32 v4, v140, v4
	s_waitcnt vmcnt(0) lgkmcnt(0)
	s_barrier
	v_add_f32_e32 v4, v141, v4
	v_add_f32_e32 v4, 0, v4
	s_add_i32 s89, s85, -4
	v_add_f32_e32 v251, v16, v4
	v_cmp_gt_u32_e64 s[6:7], 32, v243
	s_mov_b32 s90, 2
	v_lshl_add_u32 v16, v242, 2, s78
	s_movk_i32 s88, 0x2000
	s_mov_b32 s91, 0
	s_mov_b64 s[50:51], s[30:31]
	s_mov_b64 s[58:59], s[28:29]
	v_sub_f32_e32 v146, 0, v247
	v_sub_f32_e32 v147, 0, v247
	v_sub_f32_e32 v148, 0, v247
	v_sub_f32_e32 v149, 0, v247
	v_sub_f32_e32 v150, 0, v247
	v_sub_f32_e32 v151, 0, v247
	v_sub_f32_e32 v152, 0, v247
	v_sub_f32_e32 v153, 0, v247
	v_sub_f32_e32 v154, 0, v247
	v_sub_f32_e32 v155, 0, v247
	v_sub_f32_e32 v156, 0, v247
	v_sub_f32_e32 v157, 0, v247
	v_sub_f32_e32 v158, 0, v247
	v_sub_f32_e32 v159, 0, v247
	v_sub_f32_e32 v160, 0, v247
	v_sub_f32_e32 v161, 0, v247
	v_sub_f32_e32 v82, v82, v247
	v_sub_f32_e32 v83, v83, v247
	v_sub_f32_e32 v84, v84, v247
	v_sub_f32_e32 v85, v85, v247
	v_sub_f32_e32 v86, v86, v247
	v_sub_f32_e32 v87, v87, v247
	v_sub_f32_e32 v88, v88, v247
	v_sub_f32_e32 v89, v89, v247
	v_sub_f32_e32 v90, v90, v247
	v_sub_f32_e32 v91, v91, v247
	v_sub_f32_e32 v92, v92, v247
	v_sub_f32_e32 v93, v93, v247
	v_sub_f32_e32 v94, v94, v247
	v_sub_f32_e32 v95, v95, v247
	v_sub_f32_e32 v96, v96, v247
	v_sub_f32_e32 v97, v97, v247
	v_sub_f32_e32 v98, v98, v247
	v_sub_f32_e32 v99, v99, v247
	v_sub_f32_e32 v100, v100, v247
	v_sub_f32_e32 v101, v101, v247
	v_sub_f32_e32 v102, v102, v247
	v_sub_f32_e32 v103, v103, v247
	v_sub_f32_e32 v104, v104, v247
	v_sub_f32_e32 v105, v105, v247
	v_sub_f32_e32 v106, v106, v247
	v_sub_f32_e32 v107, v107, v247
	v_sub_f32_e32 v108, v108, v247
	v_sub_f32_e32 v109, v109, v247
	v_sub_f32_e32 v110, v110, v247
	v_sub_f32_e32 v111, v111, v247
	v_sub_f32_e32 v112, v112, v247
	v_sub_f32_e32 v113, v113, v247
	v_sub_f32_e32 v178, v178, v247
	s_add_u32 s60, s58, 0xfff40000
	s_addc_u32 s61, s59, -1
	s_add_i32 s4, s88, s84
	s_mov_b32 s5, m0
	s_mov_b32 m0, s4
	s_nop 0
	global_load_lds_dwordx4 v252, s[60:61]
	s_mov_b32 m0, s5
	ds_read_b128 v[164:167], v248
	ds_read_b128 v[168:171], v248 offset:1024
	ds_read_b128 v[172:175], v248 offset:2048
	ds_read_b128 v[236:239], v248 offset:3072
	v_add_u32_e32 v240, s91, v249
	ds_read_b128 v[204:207], v240
	ds_read_b128 v[208:211], v240 offset:512
	ds_read_b128 v[212:215], v240 offset:2048
	ds_read_b128 v[216:219], v240 offset:2560
	ds_read_b128 v[220:223], v240 offset:4096
	ds_read_b128 v[224:227], v240 offset:4608
	ds_read_b128 v[228:231], v240 offset:6144
	ds_read_b128 v[232:235], v240 offset:6656
	s_waitcnt vmcnt(0) lgkmcnt(0)
	s_barrier
	v_mov_b32_e32 v126, v178
	v_cmp_lt_f32_e32 vcc, s69, v126
	s_branch .LBB0_278

; #define SB() __builtin_amdgcn_sched_barrier(0)
; #define MF32(a,b,c) __builtin_amdgcn_mfma_f32_32x32x16_bf16(a,b,c,0,0,0)
; #define EXP1(x) x=__builtin_amdgcn_exp2f((x)-mh_)
; __device__ __forceinline__ bf16x8 vfrag(lds_cptr vp,int i){ const s16x4 lo=vtr(vp+(i&3)*4096+(i>>2)*1024), hh=vtr(vp+(i&3)*4096+(i>>2)*1024+512); return (bf16x8){lo[0],lo[1],lo[2],lo[3],hh[0],hh[1],hh[2],hh[3]}; }
; __device__ __forceinline__ u32x4 packw(const f32x16&p,int base){ u32x4 w; w[0]=cvtpk_s(p[base],p[base+1]); w[1]=cvtpk_s(p[base+2],p[base+3]); w[2]=cvtpk_s(p[base+4],p[base+5]); w[3]=cvtpk_s(p[base+6],p[base+7]); return w; }
; template<int THRL,bool FIRST> __device__ __forceinline__ void step_main(f32x16&p0,f32x16&p1,f32x16&n0,f32x16&n1,St&S,lds_cptr kpn,lds_cptr qp,lds_cptr vp,float*wsf,int r32,int hi,float&rm){
;     ...
;   bf16x8 ka=KF(0),kb=KF(1),kc=KF(2),kd=KF(3),qa=QF(0),qb=QF(1);
;   decide<THRL,FIRST>(rm,S,wsf,r32,hi);
;   u32x4 pw0,pw1,pw2,pw3; const float mh_=S.mhat; const f32x16 z=f32x16{};
;   SB();
;   n0=MF32(ka,qa,z); ka=KF(4); EXP1(p0[0]);EXP1(p0[1]);EXP1(p0[2]); SB();
;   n1=MF32(kb,qa,z); kb=KF(5); qa=QF(2); EXP1(p0[3]);EXP1(p0[4]);EXP1(p0[5]); SB();
;   n0=MF32(kc,qb,n0);   kc=KF(6); EXP1(p0[6]);EXP1(p0[7]);EXP1(p0[8]); SB();
;   n1=MF32(kd,qb,n1);   kd=KF(7); qb=QF(3); EXP1(p0[9]);EXP1(p0[10]);EXP1(p0[11]); SB();
;   bf16x8 vfa=vfrag(vp,0);
;   n0=MF32(ka,qa,n0);   EXP1(p0[12]);EXP1(p0[13]);EXP1(p0[14]); pw0=packw(p0,0); SB();
;   bf16x8 vfb=vfrag(vp,1);
;   n1=MF32(kb,qa,n1);   EXP1(p0[15]);EXP1(p1[0]);EXP1(p1[1]); SB();
;   bf16x8 vfc=vfrag(vp,2);
;   n0=MF32(kc,qb,n0);   EXP1(p1[2]);EXP1(p1[3]);EXP1(p1[4]); pw1=packw(p0,8); SB();
;   bf16x8 vfd=vfrag(vp,3);
;   n1=MF32(kd,qb,n1);   EXP1(p1[5]);EXP1(p1[6]);EXP1(p1[7]); SB();
;     ...
;   float sa=p0[0]+p0[1];
;     ...
;   PVG(0,pw0,vfa,4, p0[2],p0[3],p0[4],p0[5],   do{EXP1(p1[8]);EXP1(p1[9]);}while(0));
;   PVG(1,pw0,vfb,5, p0[6],p0[7],p0[8],p0[9], do{EXP1(p1[10]);EXP1(p1[11]);}while(0));
;   PVG(2,pw0,vfc,6, p0[10],p0[11],p0[12],p0[13], do{EXP1(p1[12]);EXP1(p1[13]);}while(0));
;   PVG(3,pw0,vfd,7, p0[14],p0[15],p1[0],p1[1],   do{EXP1(p1[14]);EXP1(p1[15]);}while(0));
;   PVG(4,pw1,vfa,8, p1[2],p1[3],p1[4],p1[5],   pw2=packw(p1,0));
;   PVG(5,pw1,vfb,9, p1[6],p1[7],p1[8],p1[9], pw3=packw(p1,8));
;   PVG(6,pw1,vfc,10, p1[10],p1[11],p1[12],p1[13], do{}while(0));
;   PVG(7,pw1,vfd,11, p1[14],p1[15],0.f,0.f, do{}while(0));
.LBB0_277:
	s_add_i32 s4, s91, 0x2000
	s_cmpk_lg_i32 s91, 0x4000
	s_cselect_b32 s88, s4, 0
	s_add_i32 s90, s90, 2
	v_mfma_f32_32x32x16_bf16 v[98:113], v[204:207], v[164:167], v[146:161]
	s_add_i32 s4, s88, s84
	s_add_u32 s60, s58, 0xc0000
	s_addc_u32 s61, s59, 0
	s_mov_b32 s5, m0
	s_mov_b32 m0, s4
	s_nop 0
	global_load_lds_dwordx4 v252, s[60:61]
	s_mov_b32 m0, s5
	v_exp_f32_e32 v130, v130
	v_exp_f32_e32 v131, v131
	v_exp_f32_e32 v132, v132
	v_exp_f32_e32 v133, v133
	v_exp_f32_e32 v134, v134
	v_exp_f32_e32 v135, v135
	v_mfma_f32_32x32x16_bf16 v[82:97], v[208:211], v[164:167], v[146:161]
	s_add_u32 s60, s50, 0xc0000
	s_addc_u32 s61, s51, 0
	s_mov_b32 s4, m0
	s_mov_b32 m0, s80
	s_nop 0
	global_load_lds_dwordx4 v250, s[60:61]
	s_mov_b32 m0, s4
	v_mfma_f32_32x32x16_bf16 v[98:113], v[212:215], v[168:171], v[98:113]
	s_add_u32 s60, s50, 0xc0080
	s_addc_u32 s61, s51, 0
	s_mov_b32 s4, m0
	s_mov_b32 m0, s83
	s_nop 0
	global_load_lds_dwordx4 v250, s[60:61]
	s_mov_b32 m0, s4
	v_exp_f32_e32 v136, v136
	v_exp_f32_e32 v137, v137
	v_exp_f32_e32 v138, v138
	v_mfma_f32_32x32x16_bf16 v[82:97], v[216:219], v[168:171], v[82:97]
	v_exp_f32_e32 v139, v139
	v_exp_f32_e32 v140, v140
	v_exp_f32_e32 v141, v141
	v_mfma_f32_32x32x16_bf16 v[98:113], v[220:223], v[172:175], v[98:113]
	v_exp_f32_e32 v142, v142
	ds_read_b64_tr_b16 v[4:5], v246 offset:40960
	ds_read_b64_tr_b16 v[6:7], v246 offset:41472
	v_exp_f32_e32 v143, v143
	v_exp_f32_e32 v144, v144
	v_cvt_pk_bf16_f32 v8, v130, v131
	v_cvt_pk_bf16_f32 v9, v132, v133
	v_cvt_pk_bf16_f32 v10, v134, v135
	v_cvt_pk_bf16_f32 v11, v136, v137
	v_mfma_f32_32x32x16_bf16 v[82:97], v[224:227], v[172:175], v[82:97]
	ds_read_b64_tr_b16 v[178:179], v246 offset:45056
	ds_read_b64_tr_b16 v[180:181], v246 offset:45568
	v_exp_f32_e32 v145, v145
	v_exp_f32_e32 v114, v114
	v_exp_f32_e32 v115, v115
	v_mfma_f32_32x32x16_bf16 v[98:113], v[228:231], v[236:239], v[98:113]
	ds_read_b64_tr_b16 v[182:183], v246 offset:49152
	ds_read_b64_tr_b16 v[184:185], v246 offset:49664
	v_exp_f32_e32 v116, v116
	v_exp_f32_e32 v117, v117
	v_exp_f32_e32 v118, v118
	v_cvt_pk_bf16_f32 v186, v138, v139
	v_cvt_pk_bf16_f32 v187, v140, v141
	v_cvt_pk_bf16_f32 v188, v142, v143
	v_cvt_pk_bf16_f32 v189, v144, v145
	v_mfma_f32_32x32x16_bf16 v[82:97], v[232:235], v[236:239], v[82:97]
	v_add_u32_e32 v240, s91, v249
	ds_read_b64_tr_b16 v[190:191], v246 offset:53248
	ds_read_b64_tr_b16 v[192:193], v246 offset:53760
	v_exp_f32_e32 v119, v119
	v_exp_f32_e32 v120, v120
	v_exp_f32_e32 v121, v121
	s_waitcnt lgkmcnt(6)
	v_mfma_f32_32x32x16_bf16 v[18:33], v[8:11], v[4:7], v[18:33]
	ds_read_b64_tr_b16 v[12:13], v246 offset:41984
	ds_read_b64_tr_b16 v[14:15], v246 offset:42496
	ds_read_b128 v[204:207], v240
	v_add_f32_e32 v194, v130, v131
	v_exp_f32_e32 v122, v122
	v_exp_f32_e32 v123, v123
	v_add_f32_e32 v194, v132, v194
	v_add_f32_e32 v4, v133, v194
	v_add_f32_e32 v4, v134, v4
	v_add_f32_e32 v194, v135, v4
	s_waitcnt lgkmcnt(7)
	v_mfma_f32_32x32x16_bf16 v[34:49], v[8:11], v[178:181], v[34:49]
	ds_read_b64_tr_b16 v[4:5], v246 offset:46080
	ds_read_b64_tr_b16 v[6:7], v246 offset:46592
	ds_read_b128 v[208:211], v240 offset:512
	v_exp_f32_e32 v124, v124
	v_exp_f32_e32 v125, v125
	v_add_f32_e32 v194, v136, v194
	v_add_f32_e32 v178, v137, v194
	v_add_f32_e32 v178, v138, v178
	v_add_f32_e32 v194, v139, v178
	s_waitcnt lgkmcnt(8)
	v_mfma_f32_32x32x16_bf16 v[50:65], v[8:11], v[182:185], v[50:65]
	ds_read_b64_tr_b16 v[178:179], v246 offset:50176
	ds_read_b64_tr_b16 v[180:181], v246 offset:50688
	ds_read_b128 v[212:215], v240 offset:2048
	v_exp_f32_e32 v126, v126
	v_exp_f32_e32 v127, v127
	v_add_f32_e32 v194, v140, v194
	v_add_f32_e32 v182, v141, v194
	v_add_f32_e32 v182, v142, v182
	v_add_f32_e32 v194, v143, v182
	s_waitcnt lgkmcnt(9)
	v_mfma_f32_32x32x16_bf16 v[66:81], v[8:11], v[190:193], v[66:81]
	ds_read_b64_tr_b16 v[182:183], v246 offset:54272
	ds_read_b64_tr_b16 v[184:185], v246 offset:54784
	ds_read_b128 v[216:219], v240 offset:2560
	v_exp_f32_e32 v128, v128
	v_exp_f32_e32 v129, v129
	v_add_f32_e32 v194, v144, v194
	v_add_f32_e32 v8, v145, v194
	v_add_f32_e32 v8, v114, v8
	v_add_f32_e32 v190, v115, v8
	s_waitcnt lgkmcnt(10)
	v_mfma_f32_32x32x16_bf16 v[18:33], v[186:189], v[12:15], v[18:33]
	ds_read_b64_tr_b16 v[8:9], v246 offset:43008
	ds_read_b64_tr_b16 v[10:11], v246 offset:43520
	ds_read_b128 v[220:223], v240 offset:4096
	v_add_f32_e32 v190, v116, v190
	v_add_f32_e32 v190, v117, v190
	v_add_f32_e32 v190, v118, v190
	v_add_f32_e32 v194, v119, v190
	v_cvt_pk_bf16_f32 v12, v114, v115
	v_cvt_pk_bf16_f32 v13, v116, v117
	v_cvt_pk_bf16_f32 v14, v118, v119
	v_cvt_pk_bf16_f32 v15, v120, v121
	s_waitcnt lgkmcnt(10)
	v_mfma_f32_32x32x16_bf16 v[34:49], v[186:189], v[4:7], v[34:49]
	ds_read_b64_tr_b16 v[190:191], v246 offset:47104
	ds_read_b64_tr_b16 v[192:193], v246 offset:47616
	ds_read_b128 v[224:227], v240 offset:4608
	v_add_f32_e32 v194, v120, v194
	v_add_f32_e32 v194, v121, v194
	v_add_f32_e32 v194, v122, v194
	v_add_f32_e32 v198, v123, v194
	v_cvt_pk_bf16_f32 v4, v122, v123
	v_cvt_pk_bf16_f32 v5, v124, v125
	v_cvt_pk_bf16_f32 v6, v126, v127
	v_cvt_pk_bf16_f32 v7, v128, v129
	s_waitcnt lgkmcnt(10)
	v_mfma_f32_32x32x16_bf16 v[50:65], v[186:189], v[178:181], v[50:65]
	ds_read_b64_tr_b16 v[194:195], v246 offset:51200
	ds_read_b64_tr_b16 v[196:197], v246 offset:51712
	ds_read_b128 v[228:231], v240 offset:6144
	v_add_f32_e32 v198, v124, v198
	v_add_f32_e32 v198, v125, v198
	v_add_f32_e32 v198, v126, v198
	v_add_f32_e32 v198, v127, v198
	s_waitcnt lgkmcnt(10)
; __device__ __forceinline__ int crow(int r,int hi){return (r&3)+8*(r>>2)+4*hi;}
; __device__ __forceinline__ float max3f(float a,float b,float c){float r;asm("v_max3_f32 %0, %1, %2, %3":"=v"(r):"v"(a),"v"(b),"v"(c));return r;}
; __device__ __forceinline__ float max2f(float a,float b){float r;asm("v_max_f32_e32 %0, %1, %2":"=v"(r):"v"(a),"v"(b));return r;}
;   #define PVG(i,PW,VF,NEXTI,X0,X1,Y0,Y1,EXTRA) do{ S.o[(i)&3]=MF32(__builtin_bit_cast(bf16x8,PW),VF,S.o[(i)&3]); if((NEXTI)<16){ VF=vfrag(vp,(NEXTI)<16?(NEXTI):0); } sa+=X0; sa+=X1; sa+=Y0; sa+=Y1; EXTRA; SB(); }while(0)
; template<int THRL,bool FIRST> __device__ __forceinline__ void decide(float rm,St&S,float*wsf,int r32,int hi){
;   if(FIRST){ S.mhat=rm; }
;   else if(__any(rm-S.mhat>(float)THRL)){
;     const float dl=__builtin_fmaxf(rm-S.mhat,0.f); S.mhat+=dl;
;     const float f=__builtin_amdgcn_exp2f(-dl); S.l_reg*=f; if(hi==0)wsf[r32]=f;
;     asm volatile("s_waitcnt lgkmcnt(0)":::"memory");
;     #pragma unroll
;     for(int r=0;r<16;++r){ const float fr=wsf[crow(r,hi)];
;       #pragma unroll
;       for(int d=0;d<4;++d)S.o[d][r]*=fr; }
;   }
; template<int THRL,bool FIRST> __device__ __forceinline__ void step_main(f32x16&p0,f32x16&p1,f32x16&n0,f32x16&n1,St&S,lds_cptr kpn,lds_cptr qp,lds_cptr vp,float*wsf,int r32,int hi,float&rm){
;     ...
;   float ma,mb;
;     ...
;   PVG(8,pw2,vfa,12,0.f,0.f,0.f,0.f, do{ma=max3f(n0[0],n0[1],n1[0]);mb=max3f(n0[2],n0[3],n1[1]);PINAB();}while(0));
;   PVG(9,pw2,vfb,13,0.f,0.f,0.f,0.f, do{ma=max3f(ma,n1[2],n1[3]);mb=max3f(mb,n0[4],n0[5]);PINAB();}while(0));
;   PVG(10,pw2,vfc,14,0.f,0.f,0.f,0.f, do{ma=max3f(ma,n0[6],n0[7]);mb=max3f(mb,n1[4],n1[5]);PINAB();}while(0));
;   PVG(11,pw2,vfd,15,0.f,0.f,0.f,0.f, do{ma=max3f(ma,n1[6],n1[7]);mb=max3f(mb,n0[8],n0[9]);PINAB();}while(0));
;   PVG(12,pw3,vfa,16,0.f,0.f,0.f,0.f, do{ma=max3f(ma,n0[10],n0[11]);mb=max3f(mb,n1[8],n1[9]);PINAB();}while(0));
;   PVG(13,pw3,vfb,16,0.f,0.f,0.f,0.f, do{ma=max3f(ma,n1[10],n1[11]);mb=max3f(mb,n0[12],n0[13]);PINAB();}while(0));
;   PVG(14,pw3,vfc,16,0.f,0.f,0.f,0.f, do{ma=max3f(ma,n0[14],n0[15]);mb=max3f(mb,n1[12],n1[13]);PINAB();}while(0));
;   PVG(15,pw3,vfd,16,0.f,0.f,0.f,0.f, do{ma=max3f(ma,n1[14],n1[15]);ma=max2f(ma,mb);PINAB();}while(0));
;     ...
;   { auto rr=__builtin_amdgcn_permlane32_swap(__float_as_uint(ma),__float_as_uint(ma),false,false); rm=max2f(__uint_as_float(rr[0]),__uint_as_float(rr[1])); }
	v_mfma_f32_32x32x16_bf16 v[66:81], v[186:189], v[182:185], v[66:81]
	ds_read_b64_tr_b16 v[178:179], v246 offset:55296
	ds_read_b64_tr_b16 v[180:181], v246 offset:55808
	ds_read_b128 v[232:235], v240 offset:6656
	v_add_f32_e32 v198, v128, v198
	v_add_f32_e32 v198, v129, v198
	v_add_f32_e32 v198, 0, v198
	s_waitcnt lgkmcnt(10)
	v_mfma_f32_32x32x16_bf16 v[18:33], v[12:15], v[8:11], v[18:33]
	ds_read_b64_tr_b16 v[182:183], v246 offset:44032
	ds_read_b64_tr_b16 v[184:185], v246 offset:44544
	v_max3_f32 v186, v98, v99, v82
	v_max3_f32 v187, v100, v101, v83
	s_nop 0
	s_waitcnt lgkmcnt(9)
	v_mfma_f32_32x32x16_bf16 v[34:49], v[12:15], v[190:193], v[34:49]
	ds_read_b64_tr_b16 v[8:9], v246 offset:48128
	ds_read_b64_tr_b16 v[10:11], v246 offset:48640
	v_max3_f32 v199, v186, v84, v85
	v_max3_f32 v200, v187, v102, v103
	s_nop 0
	s_waitcnt lgkmcnt(8)
	v_mfma_f32_32x32x16_bf16 v[50:65], v[12:15], v[194:197], v[50:65]
	ds_read_b64_tr_b16 v[186:187], v246 offset:52224
	ds_read_b64_tr_b16 v[188:189], v246 offset:52736
	v_max3_f32 v199, v199, v104, v105
	v_max3_f32 v200, v200, v86, v87
	s_nop 0
	s_waitcnt lgkmcnt(7)
	v_mfma_f32_32x32x16_bf16 v[66:81], v[12:15], v[178:181], v[66:81]
	ds_read_b64_tr_b16 v[190:191], v246 offset:56320
	ds_read_b64_tr_b16 v[192:193], v246 offset:56832
	v_max3_f32 v194, v199, v88, v89
	v_max3_f32 v195, v200, v106, v107
	s_nop 0
	s_waitcnt lgkmcnt(6)
	v_mfma_f32_32x32x16_bf16 v[18:33], v[4:7], v[182:185], v[18:33]
	v_max3_f32 v12, v194, v108, v109
	v_max3_f32 v13, v195, v90, v91
	s_nop 0
	s_waitcnt lgkmcnt(4)
	v_mfma_f32_32x32x16_bf16 v[34:49], v[4:7], v[8:11], v[34:49]
	v_max3_f32 v12, v12, v92, v93
	v_max3_f32 v13, v13, v110, v111
	s_nop 0
	s_waitcnt lgkmcnt(2)
	v_mfma_f32_32x32x16_bf16 v[50:65], v[4:7], v[186:189], v[50:65]
	v_max3_f32 v8, v12, v112, v113
	v_max3_f32 v9, v13, v94, v95
	s_nop 0
	s_waitcnt lgkmcnt(0)
	v_mfma_f32_32x32x16_bf16 v[66:81], v[4:7], v[190:193], v[66:81]
	v_max3_f32 v8, v8, v96, v97
	s_nop 0
	v_max_f32_e32 v8, v8, v9
	s_nop 0
	s_add_u32 s58, s58, 0x180000
	s_addc_u32 s59, s59, 0
	s_add_u32 s50, s50, 0x180000
	s_addc_u32 s51, s51, 0
	v_mov_b32_e32 v4, v8
	v_add_f32_e32 v251, v17, v198
	s_cmp_lt_u32 s90, s89
	v_permlane32_swap_b32_e32 v8, v4
	v_max_f32_e32 v178, v8, v4
	v_mov_b32_e32 v126, v178
	v_cmp_lt_f32_e32 vcc, s69, v126
	s_waitcnt vmcnt(0) lgkmcnt(0)
	s_barrier
	s_cbranch_scc0 .LBB0_285
.LBB0_278:
	s_cbranch_vccz .LBB0_282
	v_max_f32_e32 v126, v126, v126
	v_max_f32_e32 v126, 0, v126
	v_exp_f32_e64 v127, -v126
	s_and_saveexec_b64 s[60:61], s[6:7]
	ds_write_b32 v16, v127
	s_or_b64 exec, exec, s[60:61]
	s_waitcnt lgkmcnt(0)
	v_add_u32_e32 v140, s78, v2
	ds_read_b128 v[128:131], v140 offset:64
	ds_read_b128 v[132:135], v140 offset:96
	ds_read_b128 v[136:139], v140
	ds_read_b128 v[140:143], v140 offset:32
	v_add_f32_e32 v247, v247, v126
	v_sub_f32_e32 v146, v146, v126
	v_sub_f32_e32 v147, v147, v126
	v_sub_f32_e32 v148, v148, v126
	v_sub_f32_e32 v149, v149, v126
	v_sub_f32_e32 v150, v150, v126
	v_sub_f32_e32 v151, v151, v126
	v_sub_f32_e32 v152, v152, v126
	v_sub_f32_e32 v153, v153, v126
	v_sub_f32_e32 v154, v154, v126
	v_sub_f32_e32 v155, v155, v126
	v_sub_f32_e32 v156, v156, v126
	v_sub_f32_e32 v157, v157, v126
	v_sub_f32_e32 v158, v158, v126
	v_sub_f32_e32 v159, v159, v126
	v_sub_f32_e32 v160, v160, v126
	v_sub_f32_e32 v161, v161, v126
	v_sub_f32_e32 v82, v82, v126
	v_sub_f32_e32 v83, v83, v126
	v_sub_f32_e32 v84, v84, v126
	v_sub_f32_e32 v85, v85, v126
	v_sub_f32_e32 v86, v86, v126
	v_sub_f32_e32 v87, v87, v126
	v_sub_f32_e32 v88, v88, v126
	v_sub_f32_e32 v89, v89, v126
	v_sub_f32_e32 v90, v90, v126
	v_sub_f32_e32 v91, v91, v126
	v_sub_f32_e32 v92, v92, v126
	v_sub_f32_e32 v93, v93, v126
	v_sub_f32_e32 v94, v94, v126
	v_sub_f32_e32 v95, v95, v126
	v_sub_f32_e32 v96, v96, v126
	v_sub_f32_e32 v97, v97, v126
	v_sub_f32_e32 v98, v98, v126
	v_sub_f32_e32 v99, v99, v126
	v_sub_f32_e32 v100, v100, v126
	v_sub_f32_e32 v101, v101, v126
	v_sub_f32_e32 v102, v102, v126
	v_sub_f32_e32 v103, v103, v126
	v_sub_f32_e32 v104, v104, v126
	v_sub_f32_e32 v105, v105, v126
	v_sub_f32_e32 v106, v106, v126
	v_sub_f32_e32 v107, v107, v126
	v_sub_f32_e32 v108, v108, v126
	v_sub_f32_e32 v109, v109, v126
	v_sub_f32_e32 v110, v110, v126
	v_sub_f32_e32 v111, v111, v126
	v_sub_f32_e32 v112, v112, v126
	v_sub_f32_e32 v113, v113, v126
	v_mul_f32_e32 v251, v251, v127
	s_waitcnt lgkmcnt(2)
	v_pk_mul_f32 v[30:31], v[30:31], v[132:133]
	v_pk_mul_f32 v[26:27], v[26:27], v[128:129]
	s_waitcnt lgkmcnt(0)
	v_pk_mul_f32 v[22:23], v[22:23], v[140:141]
	v_pk_mul_f32 v[32:33], v[32:33], v[134:135]
	v_pk_mul_f32 v[28:29], v[28:29], v[130:131]
	v_pk_mul_f32 v[24:25], v[24:25], v[142:143]
	v_pk_mul_f32 v[20:21], v[20:21], v[138:139]
	v_pk_mul_f32 v[18:19], v[18:19], v[136:137]
	v_pk_mul_f32 v[46:47], v[46:47], v[132:133]
	v_pk_mul_f32 v[42:43], v[42:43], v[128:129]
	v_pk_mul_f32 v[38:39], v[38:39], v[140:141]
	v_pk_mul_f32 v[48:49], v[48:49], v[134:135]
	v_pk_mul_f32 v[44:45], v[44:45], v[130:131]
	v_pk_mul_f32 v[40:41], v[40:41], v[142:143]
	v_pk_mul_f32 v[36:37], v[36:37], v[138:139]
	v_pk_mul_f32 v[34:35], v[34:35], v[136:137]
	v_pk_mul_f32 v[62:63], v[62:63], v[132:133]
	v_pk_mul_f32 v[58:59], v[58:59], v[128:129]
	v_pk_mul_f32 v[54:55], v[54:55], v[140:141]
	v_pk_mul_f32 v[64:65], v[64:65], v[134:135]
	v_pk_mul_f32 v[60:61], v[60:61], v[130:131]
	v_pk_mul_f32 v[56:57], v[56:57], v[142:143]
	v_pk_mul_f32 v[52:53], v[52:53], v[138:139]
	v_pk_mul_f32 v[50:51], v[50:51], v[136:137]
	v_pk_mul_f32 v[78:79], v[78:79], v[132:133]
	v_pk_mul_f32 v[74:75], v[74:75], v[128:129]
	v_pk_mul_f32 v[70:71], v[70:71], v[140:141]
	v_pk_mul_f32 v[80:81], v[80:81], v[134:135]
	v_pk_mul_f32 v[76:77], v[76:77], v[130:131]
	v_pk_mul_f32 v[72:73], v[72:73], v[142:143]
	v_pk_mul_f32 v[68:69], v[68:69], v[138:139]
	v_pk_mul_f32 v[66:67], v[66:67], v[136:137]
; #define SB() __builtin_amdgcn_sched_barrier(0)
; #define MF32(a,b,c) __builtin_amdgcn_mfma_f32_32x32x16_bf16(a,b,c,0,0,0)
; #define EXP1(x) x=__builtin_amdgcn_exp2f((x)-mh_)
; __device__ __forceinline__ bf16x8 vfrag(lds_cptr vp,int i){ const s16x4 lo=vtr(vp+(i&3)*4096+(i>>2)*1024), hh=vtr(vp+(i&3)*4096+(i>>2)*1024+512); return (bf16x8){lo[0],lo[1],lo[2],lo[3],hh[0],hh[1],hh[2],hh[3]}; }
; __device__ __forceinline__ u32x4 packw(const f32x16&p,int base){ u32x4 w; w[0]=cvtpk_s(p[base],p[base+1]); w[1]=cvtpk_s(p[base+2],p[base+3]); w[2]=cvtpk_s(p[base+4],p[base+5]); w[3]=cvtpk_s(p[base+6],p[base+7]); return w; }
; template<int THRL,bool FIRST> __device__ __forceinline__ void step_main(f32x16&p0,f32x16&p1,f32x16&n0,f32x16&n1,St&S,lds_cptr kpn,lds_cptr qp,lds_cptr vp,float*wsf,int r32,int hi,float&rm){
;     ...
;   bf16x8 ka=KF(0),kb=KF(1),kc=KF(2),kd=KF(3),qa=QF(0),qb=QF(1);
;   decide<THRL,FIRST>(rm,S,wsf,r32,hi);
;   u32x4 pw0,pw1,pw2,pw3; const float mh_=S.mhat; const f32x16 z=f32x16{};
;   SB();
;   n0=MF32(ka,qa,z); ka=KF(4); EXP1(p0[0]);EXP1(p0[1]);EXP1(p0[2]); SB();
;   n1=MF32(kb,qa,z); kb=KF(5); qa=QF(2); EXP1(p0[3]);EXP1(p0[4]);EXP1(p0[5]); SB();
;   n0=MF32(kc,qb,n0);   kc=KF(6); EXP1(p0[6]);EXP1(p0[7]);EXP1(p0[8]); SB();
;   n1=MF32(kd,qb,n1);   kd=KF(7); qb=QF(3); EXP1(p0[9]);EXP1(p0[10]);EXP1(p0[11]); SB();
;   bf16x8 vfa=vfrag(vp,0);
;   n0=MF32(ka,qa,n0);   EXP1(p0[12]);EXP1(p0[13]);EXP1(p0[14]); pw0=packw(p0,0); SB();
;   bf16x8 vfb=vfrag(vp,1);
;   n1=MF32(kb,qa,n1);   EXP1(p0[15]);EXP1(p1[0]);EXP1(p1[1]); SB();
;   bf16x8 vfc=vfrag(vp,2);
;   n0=MF32(kc,qb,n0);   EXP1(p1[2]);EXP1(p1[3]);EXP1(p1[4]); pw1=packw(p0,8); SB();
;   bf16x8 vfd=vfrag(vp,3);
;   n1=MF32(kd,qb,n1);   EXP1(p1[5]);EXP1(p1[6]);EXP1(p1[7]); SB();
;     ...
;   float sa=p0[0]+p0[1];
;     ...
;   PVG(0,pw0,vfa,4, p0[2],p0[3],p0[4],p0[5],   do{EXP1(p1[8]);EXP1(p1[9]);}while(0));
;   PVG(1,pw0,vfb,5, p0[6],p0[7],p0[8],p0[9], do{EXP1(p1[10]);EXP1(p1[11]);}while(0));
;   PVG(2,pw0,vfc,6, p0[10],p0[11],p0[12],p0[13], do{EXP1(p1[12]);EXP1(p1[13]);}while(0));
;   PVG(3,pw0,vfd,7, p0[14],p0[15],p1[0],p1[1],   do{EXP1(p1[14]);EXP1(p1[15]);}while(0));
;   PVG(4,pw1,vfa,8, p1[2],p1[3],p1[4],p1[5],   pw2=packw(p1,0));
;   PVG(5,pw1,vfb,9, p1[6],p1[7],p1[8],p1[9], pw3=packw(p1,8));
;   PVG(6,pw1,vfc,10, p1[10],p1[11],p1[12],p1[13], do{}while(0));
;   PVG(7,pw1,vfd,11, p1[14],p1[15],0.f,0.f, do{}while(0));
.LBB0_282:
	s_add_i32 s4, s88, 0x2000
	s_cmpk_lg_i32 s88, 0x4000
	s_cselect_b32 s91, s4, 0
	v_mfma_f32_32x32x16_bf16 v[130:145], v[204:207], v[164:167], v[146:161]
	s_add_i32 s4, s91, s84
	s_mov_b32 s5, m0
	s_mov_b32 m0, s4
	s_nop 0
	global_load_lds_dwordx4 v252, s[58:59]
	s_mov_b32 m0, s5
	v_exp_f32_e32 v190, v98
	v_exp_f32_e32 v191, v99
	v_exp_f32_e32 v192, v100
	v_mfma_f32_32x32x16_bf16 v[114:129], v[208:211], v[164:167], v[146:161]
	s_mov_b32 s4, m0
	s_mov_b32 m0, s79
	s_nop 0
	global_load_lds_dwordx4 v250, s[50:51]
	s_mov_b32 m0, s4
	v_exp_f32_e32 v193, v101
	v_exp_f32_e32 v194, v102
	v_exp_f32_e32 v195, v103
	v_mfma_f32_32x32x16_bf16 v[130:145], v[212:215], v[168:171], v[130:145]
	s_add_u32 s60, s50, 0x80
	s_addc_u32 s61, s51, 0
	s_mov_b32 s4, m0
	s_mov_b32 m0, s41
	s_nop 0
	global_load_lds_dwordx4 v250, s[60:61]
	s_mov_b32 m0, s4
	v_exp_f32_e32 v196, v104
	v_exp_f32_e32 v197, v105
	v_exp_f32_e32 v198, v106
	v_mfma_f32_32x32x16_bf16 v[114:129], v[216:219], v[168:171], v[114:129]
	v_exp_f32_e32 v17, v107
	v_exp_f32_e32 v199, v108
	v_exp_f32_e32 v200, v109
	v_mfma_f32_32x32x16_bf16 v[130:145], v[220:223], v[172:175], v[130:145]
	v_exp_f32_e32 v201, v110
	ds_read_b64_tr_b16 v[4:5], v246 offset:24576
	ds_read_b64_tr_b16 v[6:7], v246 offset:25088
	v_exp_f32_e32 v202, v111
	v_exp_f32_e32 v178, v112
	v_cvt_pk_bf16_f32 v8, v190, v191
	v_cvt_pk_bf16_f32 v9, v192, v193
	v_cvt_pk_bf16_f32 v10, v194, v195
	v_cvt_pk_bf16_f32 v11, v196, v197
	v_mfma_f32_32x32x16_bf16 v[114:129], v[224:227], v[172:175], v[114:129]
	ds_read_b64_tr_b16 v[106:107], v246 offset:28672
	ds_read_b64_tr_b16 v[108:109], v246 offset:29184
	v_exp_f32_e32 v180, v82
	v_exp_f32_e32 v179, v113
	v_exp_f32_e32 v181, v83
	v_mfma_f32_32x32x16_bf16 v[130:145], v[228:231], v[236:239], v[130:145]
	ds_read_b64_tr_b16 v[110:111], v246 offset:32768
	ds_read_b64_tr_b16 v[112:113], v246 offset:33280
	v_exp_f32_e32 v182, v84
	v_exp_f32_e32 v183, v85
	v_exp_f32_e32 v184, v86
	v_cvt_pk_bf16_f32 v82, v198, v17
	v_cvt_pk_bf16_f32 v83, v199, v200
	v_cvt_pk_bf16_f32 v84, v201, v202
	v_cvt_pk_bf16_f32 v85, v178, v179
	v_mfma_f32_32x32x16_bf16 v[114:129], v[232:235], v[236:239], v[114:129]
	v_add_u32_e32 v240, s88, v249
	ds_read_b64_tr_b16 v[98:99], v246 offset:36864
	ds_read_b64_tr_b16 v[100:101], v246 offset:37376
	v_exp_f32_e32 v185, v87
	v_exp_f32_e32 v186, v88
	v_exp_f32_e32 v187, v89
	s_waitcnt lgkmcnt(6)
	v_mfma_f32_32x32x16_bf16 v[18:33], v[8:11], v[4:7], v[18:33]
	ds_read_b128 v[204:207], v240
	v_add_f32_e32 v86, v190, v191
	ds_read_b64_tr_b16 v[12:13], v246 offset:25600
	ds_read_b64_tr_b16 v[14:15], v246 offset:26112
	v_add_f32_e32 v86, v192, v86
	v_exp_f32_e32 v103, v91
	v_add_f32_e32 v4, v193, v86
	v_add_f32_e32 v4, v194, v4
	v_add_f32_e32 v86, v195, v4
	v_exp_f32_e32 v102, v90
	s_waitcnt lgkmcnt(7)
	v_mfma_f32_32x32x16_bf16 v[34:49], v[8:11], v[106:109], v[34:49]
	ds_read_b64_tr_b16 v[4:5], v246 offset:29696
	ds_read_b64_tr_b16 v[6:7], v246 offset:30208
	ds_read_b128 v[208:211], v240 offset:512
	v_add_f32_e32 v86, v196, v86
	v_add_f32_e32 v86, v197, v86
	v_add_f32_e32 v86, v198, v86
	v_exp_f32_e32 v104, v92
	v_add_f32_e32 v17, v17, v86
	v_exp_f32_e32 v105, v93
	s_waitcnt lgkmcnt(8)
	v_mfma_f32_32x32x16_bf16 v[50:65], v[8:11], v[110:113], v[50:65]
	ds_read_b64_tr_b16 v[86:87], v246 offset:33792
	ds_read_b64_tr_b16 v[88:89], v246 offset:34304
	ds_read_b128 v[212:215], v240 offset:2048
	v_add_f32_e32 v17, v199, v17
	v_add_f32_e32 v17, v200, v17
	v_add_f32_e32 v17, v201, v17
	v_exp_f32_e32 v106, v94
	v_add_f32_e32 v17, v202, v17
	v_exp_f32_e32 v107, v95
	s_waitcnt lgkmcnt(9)
	v_mfma_f32_32x32x16_bf16 v[66:81], v[8:11], v[98:101], v[66:81]
	ds_read_b64_tr_b16 v[90:91], v246 offset:37888
	ds_read_b64_tr_b16 v[92:93], v246 offset:38400
	ds_read_b128 v[216:219], v240 offset:2560
	v_add_f32_e32 v17, v178, v17
	v_add_f32_e32 v8, v179, v17
	v_add_f32_e32 v8, v180, v8
	v_exp_f32_e32 v108, v96
	v_add_f32_e32 v17, v181, v8
	v_exp_f32_e32 v109, v97
	s_waitcnt lgkmcnt(9)
; __device__ __forceinline__ float max3f(float a,float b,float c){float r;asm("v_max3_f32 %0, %1, %2, %3":"=v"(r):"v"(a),"v"(b),"v"(c));return r;}
; __device__ __forceinline__ float max2f(float a,float b){float r;asm("v_max_f32_e32 %0, %1, %2":"=v"(r):"v"(a),"v"(b));return r;}
;   #define PVG(i,PW,VF,NEXTI,X0,X1,Y0,Y1,EXTRA) do{ S.o[(i)&3]=MF32(__builtin_bit_cast(bf16x8,PW),VF,S.o[(i)&3]); if((NEXTI)<16){ VF=vfrag(vp,(NEXTI)<16?(NEXTI):0); } sa+=X0; sa+=X1; sa+=Y0; sa+=Y1; EXTRA; SB(); }while(0)
;   #define PINAB() asm volatile("":"+v"(ma),"+v"(mb))
; template<int THRL,bool FIRST> __device__ __forceinline__ void decide(float rm,St&S,float*wsf,int r32,int hi){
;     ...
;   else if(__any(rm-S.mhat>(float)THRL)){
;     const float dl=__builtin_fmaxf(rm-S.mhat,0.f); S.mhat+=dl;
;     const float f=__builtin_amdgcn_exp2f(-dl); S.l_reg*=f; if(hi==0)wsf[r32]=f;
; template<int THRL,bool FIRST> __device__ __forceinline__ void step_main(f32x16&p0,f32x16&p1,f32x16&n0,f32x16&n1,St&S,lds_cptr kpn,lds_cptr qp,lds_cptr vp,float*wsf,int r32,int hi,float&rm){
;     ...
;   PVG(8,pw2,vfa,12,0.f,0.f,0.f,0.f, do{ma=max3f(n0[0],n0[1],n1[0]);mb=max3f(n0[2],n0[3],n1[1]);PINAB();}while(0));
;   PVG(9,pw2,vfb,13,0.f,0.f,0.f,0.f, do{ma=max3f(ma,n1[2],n1[3]);mb=max3f(mb,n0[4],n0[5]);PINAB();}while(0));
;   PVG(10,pw2,vfc,14,0.f,0.f,0.f,0.f, do{ma=max3f(ma,n0[6],n0[7]);mb=max3f(mb,n1[4],n1[5]);PINAB();}while(0));
;   PVG(11,pw2,vfd,15,0.f,0.f,0.f,0.f, do{ma=max3f(ma,n1[6],n1[7]);mb=max3f(mb,n0[8],n0[9]);PINAB();}while(0));
;   PVG(12,pw3,vfa,16,0.f,0.f,0.f,0.f, do{ma=max3f(ma,n0[10],n0[11]);mb=max3f(mb,n1[8],n1[9]);PINAB();}while(0));
;   PVG(13,pw3,vfb,16,0.f,0.f,0.f,0.f, do{ma=max3f(ma,n1[10],n1[11]);mb=max3f(mb,n0[12],n0[13]);PINAB();}while(0));
;   PVG(14,pw3,vfc,16,0.f,0.f,0.f,0.f, do{ma=max3f(ma,n0[14],n0[15]);mb=max3f(mb,n1[12],n1[13]);PINAB();}while(0));
;   PVG(15,pw3,vfd,16,0.f,0.f,0.f,0.f, do{ma=max3f(ma,n1[14],n1[15]);ma=max2f(ma,mb);PINAB();}while(0));
;     ...
;   { auto rr=__builtin_amdgcn_permlane32_swap(__float_as_uint(ma),__float_as_uint(ma),false,false); rm=max2f(__uint_as_float(rr[0]),__uint_as_float(rr[1])); }
	v_mfma_f32_32x32x16_bf16 v[18:33], v[82:85], v[12:15], v[18:33]
	ds_read_b64_tr_b16 v[8:9], v246 offset:26624
	ds_read_b64_tr_b16 v[10:11], v246 offset:27136
	ds_read_b128 v[220:223], v240 offset:4096
	v_add_f32_e32 v17, v182, v17
	v_add_f32_e32 v17, v183, v17
	v_add_f32_e32 v17, v184, v17
	v_add_f32_e32 v17, v185, v17
	v_cvt_pk_bf16_f32 v12, v180, v181
	v_cvt_pk_bf16_f32 v13, v182, v183
	v_cvt_pk_bf16_f32 v14, v184, v185
	v_cvt_pk_bf16_f32 v15, v186, v187
	s_waitcnt lgkmcnt(10)
	v_mfma_f32_32x32x16_bf16 v[34:49], v[82:85], v[4:7], v[34:49]
	ds_read_b64_tr_b16 v[94:95], v246 offset:30720
	ds_read_b64_tr_b16 v[96:97], v246 offset:31232
	ds_read_b128 v[224:227], v240 offset:4608
	v_add_f32_e32 v17, v186, v17
	v_add_f32_e32 v17, v187, v17
	v_add_f32_e32 v17, v102, v17
	v_add_f32_e32 v17, v103, v17
	v_cvt_pk_bf16_f32 v4, v102, v103
	v_cvt_pk_bf16_f32 v5, v104, v105
	v_cvt_pk_bf16_f32 v6, v106, v107
	v_cvt_pk_bf16_f32 v7, v108, v109
	s_waitcnt lgkmcnt(10)
	v_mfma_f32_32x32x16_bf16 v[50:65], v[82:85], v[86:89], v[50:65]
	ds_read_b64_tr_b16 v[98:99], v246 offset:34816
	ds_read_b64_tr_b16 v[100:101], v246 offset:35328
	ds_read_b128 v[228:231], v240 offset:6144
	v_add_f32_e32 v17, v104, v17
	v_add_f32_e32 v17, v105, v17
	v_add_f32_e32 v17, v106, v17
	v_add_f32_e32 v17, v107, v17
	s_waitcnt lgkmcnt(10)
	v_mfma_f32_32x32x16_bf16 v[66:81], v[82:85], v[90:93], v[66:81]
	ds_read_b64_tr_b16 v[86:87], v246 offset:38912
	ds_read_b64_tr_b16 v[88:89], v246 offset:39424
	ds_read_b128 v[232:235], v240 offset:6656
	v_add_f32_e32 v17, v108, v17
	v_add_f32_e32 v17, v109, v17
	v_add_f32_e32 v17, 0, v17
	s_waitcnt lgkmcnt(10)
	v_mfma_f32_32x32x16_bf16 v[18:33], v[12:15], v[8:11], v[18:33]
	ds_read_b64_tr_b16 v[82:83], v246 offset:27648
	ds_read_b64_tr_b16 v[84:85], v246 offset:28160
	v_max3_f32 v90, v130, v131, v114
	v_max3_f32 v91, v132, v133, v115
	s_nop 0
	s_waitcnt lgkmcnt(9)
	v_mfma_f32_32x32x16_bf16 v[34:49], v[12:15], v[94:97], v[34:49]
	ds_read_b64_tr_b16 v[8:9], v246 offset:31744
	ds_read_b64_tr_b16 v[10:11], v246 offset:32256
	v_max3_f32 v102, v90, v116, v117
	v_max3_f32 v103, v91, v134, v135
	s_nop 0
	s_waitcnt lgkmcnt(8)
	v_mfma_f32_32x32x16_bf16 v[50:65], v[12:15], v[98:101], v[50:65]
	ds_read_b64_tr_b16 v[90:91], v246 offset:35840
	ds_read_b64_tr_b16 v[92:93], v246 offset:36352
	v_max3_f32 v102, v102, v136, v137
	v_max3_f32 v103, v103, v118, v119
	s_nop 0
	s_waitcnt lgkmcnt(7)
	v_mfma_f32_32x32x16_bf16 v[66:81], v[12:15], v[86:89], v[66:81]
	ds_read_b64_tr_b16 v[94:95], v246 offset:39936
	ds_read_b64_tr_b16 v[96:97], v246 offset:40448
	v_max3_f32 v98, v102, v120, v121
	v_max3_f32 v99, v103, v138, v139
	s_nop 0
	s_waitcnt lgkmcnt(6)
	v_mfma_f32_32x32x16_bf16 v[18:33], v[4:7], v[82:85], v[18:33]
	v_max3_f32 v12, v98, v140, v141
	v_max3_f32 v13, v99, v122, v123
	s_nop 0
	s_waitcnt lgkmcnt(4)
	v_mfma_f32_32x32x16_bf16 v[34:49], v[4:7], v[8:11], v[34:49]
	v_max3_f32 v12, v12, v124, v125
	v_max3_f32 v13, v13, v142, v143
	s_nop 0
	s_waitcnt lgkmcnt(2)
	v_mfma_f32_32x32x16_bf16 v[50:65], v[4:7], v[90:93], v[50:65]
	v_max3_f32 v8, v12, v144, v145
	v_max3_f32 v9, v13, v126, v127
	s_nop 0
	s_waitcnt lgkmcnt(0)
	v_mfma_f32_32x32x16_bf16 v[66:81], v[4:7], v[94:97], v[66:81]
	v_max3_f32 v8, v8, v128, v129
	s_nop 0
	v_max_f32_e32 v8, v8, v9
	s_nop 0
	v_mov_b32_e32 v162, v8
	v_mov_b32_e32 v163, v8
	v_add_f32_e32 v17, v251, v17
	s_nop 0
	v_permlane32_swap_b32_e32 v162, v163
	v_max_f32_e32 v94, v162, v163
	v_cmp_lt_f32_e32 vcc, s69, v94
	s_waitcnt vmcnt(0) lgkmcnt(0)
	s_barrier
	s_cbranch_vccz .LBB0_277
	v_max_f32_e32 v94, v94, v94
	v_max_f32_e32 v94, 0, v94
	v_exp_f32_e64 v95, -v94
	s_and_saveexec_b64 s[60:61], s[6:7]
	s_cbranch_execz .LBB0_276
	ds_write_b32 v16, v95
	s_branch .LBB0_276

; #define SB() __builtin_amdgcn_sched_barrier(0)
; #define MF32(a,b,c) __builtin_amdgcn_mfma_f32_32x32x16_bf16(a,b,c,0,0,0)
; #define EXP1(x) x=__builtin_amdgcn_exp2f((x)-mh_)
; __device__ __forceinline__ bf16x8 vfrag(lds_cptr vp,int i){ const s16x4 lo=vtr(vp+(i&3)*4096+(i>>2)*1024), hh=vtr(vp+(i&3)*4096+(i>>2)*1024+512); return (bf16x8){lo[0],lo[1],lo[2],lo[3],hh[0],hh[1],hh[2],hh[3]}; }
; __device__ __forceinline__ u32x4 packw(const f32x16&p,int base){ u32x4 w; w[0]=cvtpk_s(p[base],p[base+1]); w[1]=cvtpk_s(p[base+2],p[base+3]); w[2]=cvtpk_s(p[base+4],p[base+5]); w[3]=cvtpk_s(p[base+6],p[base+7]); return w; }
; template<int THRL,bool FIRST> __device__ __forceinline__ void step_main(f32x16&p0,f32x16&p1,f32x16&n0,f32x16&n1,St&S,lds_cptr kpn,lds_cptr qp,lds_cptr vp,float*wsf,int r32,int hi,float&rm){
;     ...
;   bf16x8 ka=KF(0),kb=KF(1),kc=KF(2),kd=KF(3),qa=QF(0),qb=QF(1);
;   decide<THRL,FIRST>(rm,S,wsf,r32,hi);
;   u32x4 pw0,pw1,pw2,pw3; const float mh_=S.mhat; const f32x16 z=f32x16{};
;   SB();
;   n0=MF32(ka,qa,z); ka=KF(4); EXP1(p0[0]);EXP1(p0[1]);EXP1(p0[2]); SB();
;   n1=MF32(kb,qa,z); kb=KF(5); qa=QF(2); EXP1(p0[3]);EXP1(p0[4]);EXP1(p0[5]); SB();
;   n0=MF32(kc,qb,n0);   kc=KF(6); EXP1(p0[6]);EXP1(p0[7]);EXP1(p0[8]); SB();
;   n1=MF32(kd,qb,n1);   kd=KF(7); qb=QF(3); EXP1(p0[9]);EXP1(p0[10]);EXP1(p0[11]); SB();
;   bf16x8 vfa=vfrag(vp,0);
;   n0=MF32(ka,qa,n0);   EXP1(p0[12]);EXP1(p0[13]);EXP1(p0[14]); pw0=packw(p0,0); SB();
;   bf16x8 vfb=vfrag(vp,1);
;   n1=MF32(kb,qa,n1);   EXP1(p0[15]);EXP1(p1[0]);EXP1(p1[1]); SB();
;   bf16x8 vfc=vfrag(vp,2);
;   n0=MF32(kc,qb,n0);   EXP1(p1[2]);EXP1(p1[3]);EXP1(p1[4]); pw1=packw(p0,8); SB();
;   bf16x8 vfd=vfrag(vp,3);
;   n1=MF32(kd,qb,n1);   EXP1(p1[5]);EXP1(p1[6]);EXP1(p1[7]); SB();
;     ...
;   float sa=p0[0]+p0[1];
;     ...
;   PVG(0,pw0,vfa,4, p0[2],p0[3],p0[4],p0[5],   do{EXP1(p1[8]);EXP1(p1[9]);}while(0));
;   PVG(1,pw0,vfb,5, p0[6],p0[7],p0[8],p0[9], do{EXP1(p1[10]);EXP1(p1[11]);}while(0));
;   PVG(2,pw0,vfc,6, p0[10],p0[11],p0[12],p0[13], do{EXP1(p1[12]);EXP1(p1[13]);}while(0));
;   PVG(3,pw0,vfd,7, p0[14],p0[15],p1[0],p1[1],   do{EXP1(p1[14]);EXP1(p1[15]);}while(0));
;   PVG(4,pw1,vfa,8, p1[2],p1[3],p1[4],p1[5],   pw2=packw(p1,0));
;   PVG(5,pw1,vfb,9, p1[6],p1[7],p1[8],p1[9], pw3=packw(p1,8));
;   PVG(6,pw1,vfc,10, p1[10],p1[11],p1[12],p1[13], do{}while(0));
;   PVG(7,pw1,vfd,11, p1[14],p1[15],0.f,0.f, do{}while(0));
.LBB0_433:
	s_waitcnt lgkmcnt(1)
	v_mfma_f32_32x32x16_bf16 v[98:113], v[218:221], v[214:217], 0
	ds_read_b128 v[178:181], v249 offset:20480
	v_sub_f32_e32 v82, v131, v247
	v_sub_f32_e32 v17, v130, v247
	v_exp_f32_e32 v190, v82
	v_sub_f32_e32 v82, v132, v247
	v_exp_f32_e32 v17, v17
	v_exp_f32_e32 v191, v82
	v_sub_f32_e32 v82, v133, v247
	v_exp_f32_e32 v192, v82
	v_sub_f32_e32 v82, v134, v247
	v_exp_f32_e32 v193, v82
	v_sub_f32_e32 v82, v135, v247
	v_exp_f32_e32 v194, v82
	v_mfma_f32_32x32x16_bf16 v[82:97], v[210:213], v[214:217], 0
	ds_read_b128 v[182:185], v249 offset:20992
	ds_read_b128 v[186:189], v248 offset:2048
	s_waitcnt lgkmcnt(3)
	v_mfma_f32_32x32x16_bf16 v[98:113], v[12:15], v[8:11], v[98:113]
	ds_read_b128 v[130:133], v249 offset:22528
	v_sub_f32_e32 v134, v136, v247
	v_exp_f32_e32 v195, v134
	v_sub_f32_e32 v134, v137, v247
	v_exp_f32_e32 v196, v134
	v_sub_f32_e32 v134, v138, v247
	v_exp_f32_e32 v197, v134
	v_mfma_f32_32x32x16_bf16 v[82:97], v[4:7], v[8:11], v[82:97]
	ds_read_b128 v[12:15], v249 offset:23040
	ds_read_b128 v[134:137], v248 offset:3072
	v_sub_f32_e32 v138, v139, v247
	v_exp_f32_e32 v198, v138
	v_sub_f32_e32 v138, v140, v247
	v_exp_f32_e32 v199, v138
	v_sub_f32_e32 v138, v141, v247
	v_exp_f32_e32 v200, v138
	s_waitcnt lgkmcnt(3)
	v_mfma_f32_32x32x16_bf16 v[98:113], v[178:181], v[186:189], v[98:113]
	ds_read_b64_tr_b16 v[4:5], v246 offset:40960
	ds_read_b64_tr_b16 v[6:7], v246 offset:41472
	v_sub_f32_e32 v8, v142, v247
	v_exp_f32_e32 v201, v8
	v_sub_f32_e32 v8, v143, v247
	v_exp_f32_e32 v202, v8
	v_sub_f32_e32 v8, v144, v247
	v_exp_f32_e32 v179, v8
	v_cvt_pk_bf16_f32 v8, v17, v190
	v_cvt_pk_bf16_f32 v9, v191, v192
	v_cvt_pk_bf16_f32 v10, v193, v194
	v_cvt_pk_bf16_f32 v11, v195, v196
	v_mfma_f32_32x32x16_bf16 v[82:97], v[182:185], v[186:189], v[82:97]
	ds_read_b64_tr_b16 v[138:139], v246 offset:45056
	ds_read_b64_tr_b16 v[140:141], v246 offset:45568
	v_sub_f32_e32 v114, v114, v247
	v_sub_f32_e32 v142, v145, v247
	v_exp_f32_e32 v181, v114
	v_sub_f32_e32 v114, v115, v247
	v_exp_f32_e32 v180, v142
	v_exp_f32_e32 v203, v114
	s_waitcnt lgkmcnt(4)
	v_mfma_f32_32x32x16_bf16 v[98:113], v[130:133], v[134:137], v[98:113]
	ds_read_b64_tr_b16 v[142:143], v246 offset:49152
	ds_read_b64_tr_b16 v[144:145], v246 offset:49664
	v_sub_f32_e32 v114, v116, v247
	v_exp_f32_e32 v182, v114
	v_sub_f32_e32 v114, v117, v247
	v_exp_f32_e32 v183, v114
	v_sub_f32_e32 v114, v118, v247
	v_exp_f32_e32 v184, v114
	v_cvt_pk_bf16_f32 v114, v197, v198
	v_cvt_pk_bf16_f32 v115, v199, v200
	v_cvt_pk_bf16_f32 v116, v201, v202
	v_cvt_pk_bf16_f32 v117, v179, v180
	v_mfma_f32_32x32x16_bf16 v[82:97], v[12:15], v[134:137], v[82:97]
	ds_read_b64_tr_b16 v[130:131], v246 offset:53248
	ds_read_b64_tr_b16 v[132:133], v246 offset:53760
	v_sub_f32_e32 v118, v119, v247
	v_exp_f32_e32 v185, v118
	v_sub_f32_e32 v118, v120, v247
	v_exp_f32_e32 v186, v118
	v_sub_f32_e32 v118, v121, v247
	v_exp_f32_e32 v187, v118
	s_waitcnt lgkmcnt(6)
	v_mfma_f32_32x32x16_bf16 v[18:33], v[8:11], v[4:7], v[18:33]
	ds_read_b64_tr_b16 v[12:13], v246 offset:41984
	ds_read_b64_tr_b16 v[14:15], v246 offset:42496
	v_sub_f32_e32 v118, v122, v247
	v_exp_f32_e32 v134, v118
	v_sub_f32_e32 v118, v123, v247
	v_exp_f32_e32 v135, v118
	s_waitcnt lgkmcnt(6)
	v_mfma_f32_32x32x16_bf16 v[34:49], v[8:11], v[138:141], v[34:49]
	ds_read_b64_tr_b16 v[4:5], v246 offset:46080
	ds_read_b64_tr_b16 v[6:7], v246 offset:46592
	v_sub_f32_e32 v118, v124, v247
	v_exp_f32_e32 v136, v118
	v_sub_f32_e32 v118, v125, v247
	v_exp_f32_e32 v137, v118
	s_waitcnt lgkmcnt(6)
	v_mfma_f32_32x32x16_bf16 v[50:65], v[8:11], v[142:145], v[50:65]
	ds_read_b64_tr_b16 v[118:119], v246 offset:50176
	ds_read_b64_tr_b16 v[120:121], v246 offset:50688
	v_sub_f32_e32 v122, v126, v247
	v_exp_f32_e32 v138, v122
	v_sub_f32_e32 v122, v127, v247
	v_exp_f32_e32 v139, v122
	s_waitcnt lgkmcnt(6)
	v_mfma_f32_32x32x16_bf16 v[66:81], v[8:11], v[130:133], v[66:81]
	ds_read_b64_tr_b16 v[122:123], v246 offset:54272
	ds_read_b64_tr_b16 v[124:125], v246 offset:54784
	v_sub_f32_e32 v126, v128, v247
	v_exp_f32_e32 v140, v126
	v_sub_f32_e32 v126, v129, v247
	v_exp_f32_e32 v141, v126
	s_waitcnt lgkmcnt(6)
	v_mfma_f32_32x32x16_bf16 v[18:33], v[114:117], v[12:15], v[18:33]
	ds_read_b64_tr_b16 v[8:9], v246 offset:43008
	ds_read_b64_tr_b16 v[10:11], v246 offset:43520
	v_cvt_pk_bf16_f32 v126, v181, v203
	v_cvt_pk_bf16_f32 v127, v182, v183
	v_cvt_pk_bf16_f32 v128, v184, v185
	v_cvt_pk_bf16_f32 v129, v186, v187
	s_waitcnt lgkmcnt(6)
	v_mfma_f32_32x32x16_bf16 v[34:49], v[114:117], v[4:7], v[34:49]
	ds_read_b64_tr_b16 v[12:13], v246 offset:47104
	ds_read_b64_tr_b16 v[14:15], v246 offset:47616
	v_cvt_pk_bf16_f32 v130, v134, v135
	v_cvt_pk_bf16_f32 v131, v136, v137
	v_cvt_pk_bf16_f32 v132, v138, v139
	v_cvt_pk_bf16_f32 v133, v140, v141
	s_waitcnt lgkmcnt(6)
	v_mfma_f32_32x32x16_bf16 v[50:65], v[114:117], v[118:121], v[50:65]
	ds_read_b64_tr_b16 v[4:5], v246 offset:51200
	ds_read_b64_tr_b16 v[6:7], v246 offset:51712
	s_waitcnt lgkmcnt(6)
	v_mfma_f32_32x32x16_bf16 v[66:81], v[114:117], v[122:125], v[66:81]
	ds_read_b64_tr_b16 v[118:119], v246 offset:55296
	ds_read_b64_tr_b16 v[120:121], v246 offset:55808
	s_waitcnt lgkmcnt(6)
; __device__ __forceinline__ float max3f(float a,float b,float c){float r;asm("v_max3_f32 %0, %1, %2, %3":"=v"(r):"v"(a),"v"(b),"v"(c));return r;}
; __device__ __forceinline__ float max2f(float a,float b){float r;asm("v_max_f32_e32 %0, %1, %2":"=v"(r):"v"(a),"v"(b));return r;}
; #define A128_WAITBAR() asm volatile("s_waitcnt vmcnt(0) lgkmcnt(0)\n\ts_barrier":::"memory")
;   #define PVG(i,PW,VF,NEXTI,X0,X1,Y0,Y1,EXTRA) do{ S.o[(i)&3]=MF32(__builtin_bit_cast(bf16x8,PW),VF,S.o[(i)&3]); if((NEXTI)<16){ VF=vfrag(vp,(NEXTI)<16?(NEXTI):0); } sa+=X0; sa+=X1; sa+=Y0; sa+=Y1; EXTRA; SB(); }while(0)
;   #define PINAB() asm volatile("":"+v"(ma),"+v"(mb))
;   #define ROT() do{ ks1=ks2; ks2=(ks2==2*KBUF)?0:ks2+KBUF; }while(0)
; template<int THRL,bool FIRST> __device__ __forceinline__ void step_main(f32x16&p0,f32x16&p1,f32x16&n0,f32x16&n1,St&S,lds_cptr kpn,lds_cptr qp,lds_cptr vp,float*wsf,int r32,int hi,float&rm){
;     ...
;   float ma,mb;
;     ...
;   PVG(8,pw2,vfa,12,0.f,0.f,0.f,0.f, do{ma=max3f(n0[0],n0[1],n1[0]);mb=max3f(n0[2],n0[3],n1[1]);PINAB();}while(0));
;   PVG(9,pw2,vfb,13,0.f,0.f,0.f,0.f, do{ma=max3f(ma,n1[2],n1[3]);mb=max3f(mb,n0[4],n0[5]);PINAB();}while(0));
;   PVG(10,pw2,vfc,14,0.f,0.f,0.f,0.f, do{ma=max3f(ma,n0[6],n0[7]);mb=max3f(mb,n1[4],n1[5]);PINAB();}while(0));
;   PVG(11,pw2,vfd,15,0.f,0.f,0.f,0.f, do{ma=max3f(ma,n1[6],n1[7]);mb=max3f(mb,n0[8],n0[9]);PINAB();}while(0));
;   PVG(12,pw3,vfa,16,0.f,0.f,0.f,0.f, do{ma=max3f(ma,n0[10],n0[11]);mb=max3f(mb,n1[8],n1[9]);PINAB();}while(0));
;   PVG(13,pw3,vfb,16,0.f,0.f,0.f,0.f, do{ma=max3f(ma,n1[10],n1[11]);mb=max3f(mb,n0[12],n0[13]);PINAB();}while(0));
;   PVG(14,pw3,vfc,16,0.f,0.f,0.f,0.f, do{ma=max3f(ma,n0[14],n0[15]);mb=max3f(mb,n1[12],n1[13]);PINAB();}while(0));
;   PVG(15,pw3,vfd,16,0.f,0.f,0.f,0.f, do{ma=max3f(ma,n1[14],n1[15]);ma=max2f(ma,mb);PINAB();}while(0));
;     ...
;   { auto rr=__builtin_amdgcn_permlane32_swap(__float_as_uint(ma),__float_as_uint(ma),false,false); rm=max2f(__uint_as_float(rr[0]),__uint_as_float(rr[1])); }
;     ...
;   S.l_reg+=sa;
; }
; template<int THRL> __device__ __forceinline__ void unit(int qb,const bf16*Q,const bf16*K,const bf16*V,bf16*O,char*shm){
;     ...
;     step_main<THRL,true>(pA0,pA1,pB0,pB1,S,kp0+ks1,qp,vp0,wsf,r32,hi,rm); A128_WAITBAR(); ROT();
;     DMA_K(3,ks2); DMA_V(2,0);
;     step_main<THRL,false>(pB0,pB1,pA0,pA1,S,kp0+ks1,qp,vp0+VBUF,wsf,r32,hi,rm); A128_WAITBAR(); ROT();
	v_mfma_f32_32x32x16_bf16 v[18:33], v[126:129], v[8:11], v[18:33]
	ds_read_b64_tr_b16 v[114:115], v246 offset:44032
	ds_read_b64_tr_b16 v[116:117], v246 offset:44544
	v_max3_f32 v122, v98, v99, v82
	v_max3_f32 v123, v100, v101, v83
	s_nop 0
	s_waitcnt lgkmcnt(6)
	v_mfma_f32_32x32x16_bf16 v[34:49], v[126:129], v[12:15], v[34:49]
	ds_read_b64_tr_b16 v[8:9], v246 offset:48128
	ds_read_b64_tr_b16 v[10:11], v246 offset:48640
	v_max3_f32 v122, v122, v84, v85
	v_max3_f32 v123, v123, v102, v103
	s_nop 0
	s_waitcnt lgkmcnt(6)
	v_mfma_f32_32x32x16_bf16 v[50:65], v[126:129], v[4:7], v[50:65]
	ds_read_b64_tr_b16 v[12:13], v246 offset:52224
	ds_read_b64_tr_b16 v[14:15], v246 offset:52736
	v_max3_f32 v122, v122, v104, v105
	v_max3_f32 v123, v123, v86, v87
	s_nop 0
	s_waitcnt lgkmcnt(6)
	v_mfma_f32_32x32x16_bf16 v[66:81], v[126:129], v[118:121], v[66:81]
	ds_read_b64_tr_b16 v[4:5], v246 offset:56320
	ds_read_b64_tr_b16 v[6:7], v246 offset:56832
	v_max3_f32 v122, v122, v88, v89
	v_max3_f32 v123, v123, v106, v107
	s_nop 0
	s_waitcnt lgkmcnt(6)
	v_mfma_f32_32x32x16_bf16 v[18:33], v[130:133], v[114:117], v[18:33]
	v_max3_f32 v118, v122, v108, v109
	v_max3_f32 v119, v123, v90, v91
	s_nop 0
	s_waitcnt lgkmcnt(4)
	v_mfma_f32_32x32x16_bf16 v[34:49], v[130:133], v[8:11], v[34:49]
	v_max3_f32 v114, v118, v92, v93
	v_max3_f32 v115, v119, v110, v111
	s_nop 0
	s_waitcnt lgkmcnt(2)
	v_mfma_f32_32x32x16_bf16 v[50:65], v[130:133], v[12:15], v[50:65]
	v_max3_f32 v8, v114, v112, v113
	v_max3_f32 v9, v115, v94, v95
	s_nop 0
	s_waitcnt lgkmcnt(0)
	v_mfma_f32_32x32x16_bf16 v[66:81], v[130:133], v[4:7], v[66:81]
	v_max3_f32 v8, v8, v96, v97
	s_nop 0
	v_max_f32_e32 v8, v8, v9
	s_nop 0
	s_nop 0
	v_mov_b32_e32 v4, v8
	s_nop 1
	v_permlane32_swap_b32_e32 v8, v4
	v_max_f32_e32 v178, v8, v4
	v_add_f32_e32 v4, v17, v190
	v_add_f32_e32 v4, v191, v4
	v_add_f32_e32 v4, v192, v4
	v_add_f32_e32 v4, v193, v4
	v_add_f32_e32 v4, v194, v4
	v_add_f32_e32 v4, v195, v4
	v_add_f32_e32 v4, v196, v4
	v_add_f32_e32 v4, v197, v4
	v_add_f32_e32 v4, v198, v4
	v_add_f32_e32 v4, v199, v4
	v_add_f32_e32 v4, v200, v4
	v_add_f32_e32 v4, v201, v4
	v_add_f32_e32 v4, v202, v4
	v_add_f32_e32 v4, v179, v4
	v_add_f32_e32 v4, v180, v4
	v_add_f32_e32 v4, v181, v4
	v_add_f32_e32 v4, v203, v4
	v_add_f32_e32 v4, v182, v4
	v_add_f32_e32 v4, v183, v4
	v_add_f32_e32 v4, v184, v4
	v_add_f32_e32 v4, v185, v4
	v_add_f32_e32 v4, v186, v4
	v_add_f32_e32 v4, v187, v4
	v_add_f32_e32 v4, v134, v4
	v_add_f32_e32 v4, v135, v4
	v_add_f32_e32 v4, v136, v4
	v_add_f32_e32 v4, v137, v4
	v_add_f32_e32 v4, v138, v4
	v_add_f32_e32 v4, v139, v4
	v_add_f32_e32 v4, v140, v4
	s_waitcnt vmcnt(0) lgkmcnt(0)
	s_barrier
	v_add_f32_e32 v4, v141, v4
	v_add_f32_e32 v4, 0, v4
	s_add_i32 s87, s83, -4
	v_add_f32_e32 v251, v16, v4
	v_cmp_gt_u32_e64 s[6:7], 32, v243
	s_mov_b32 s88, 2
	v_lshl_add_u32 v16, v242, 2, s76
	s_movk_i32 s86, 0x2000
	s_mov_b32 s89, 0
	s_mov_b64 s[48:49], s[34:35]
	s_mov_b64 s[50:51], s[30:31]
	v_sub_f32_e32 v146, 0, v247
	v_sub_f32_e32 v147, 0, v247
	v_sub_f32_e32 v148, 0, v247
	v_sub_f32_e32 v149, 0, v247
	v_sub_f32_e32 v150, 0, v247
	v_sub_f32_e32 v151, 0, v247
	v_sub_f32_e32 v152, 0, v247
	v_sub_f32_e32 v153, 0, v247
	v_sub_f32_e32 v154, 0, v247
	v_sub_f32_e32 v155, 0, v247
	v_sub_f32_e32 v156, 0, v247
	v_sub_f32_e32 v157, 0, v247
	v_sub_f32_e32 v158, 0, v247
	v_sub_f32_e32 v159, 0, v247
	v_sub_f32_e32 v160, 0, v247
	v_sub_f32_e32 v161, 0, v247
	v_sub_f32_e32 v82, v82, v247
	v_sub_f32_e32 v83, v83, v247
	v_sub_f32_e32 v84, v84, v247
	v_sub_f32_e32 v85, v85, v247
	v_sub_f32_e32 v86, v86, v247
	v_sub_f32_e32 v87, v87, v247
	v_sub_f32_e32 v88, v88, v247
	v_sub_f32_e32 v89, v89, v247
	v_sub_f32_e32 v90, v90, v247
	v_sub_f32_e32 v91, v91, v247
	v_sub_f32_e32 v92, v92, v247
	v_sub_f32_e32 v93, v93, v247
	v_sub_f32_e32 v94, v94, v247
	v_sub_f32_e32 v95, v95, v247
	v_sub_f32_e32 v96, v96, v247
	v_sub_f32_e32 v97, v97, v247
	v_sub_f32_e32 v98, v98, v247
	v_sub_f32_e32 v99, v99, v247
	v_sub_f32_e32 v100, v100, v247
	v_sub_f32_e32 v101, v101, v247
	v_sub_f32_e32 v102, v102, v247
	v_sub_f32_e32 v103, v103, v247
	v_sub_f32_e32 v104, v104, v247
	v_sub_f32_e32 v105, v105, v247
	v_sub_f32_e32 v106, v106, v247
	v_sub_f32_e32 v107, v107, v247
	v_sub_f32_e32 v108, v108, v247
	v_sub_f32_e32 v109, v109, v247
	v_sub_f32_e32 v110, v110, v247
	v_sub_f32_e32 v111, v111, v247
	v_sub_f32_e32 v112, v112, v247
	v_sub_f32_e32 v113, v113, v247
	v_sub_f32_e32 v178, v178, v247
	s_add_u32 s58, s50, 0xfff40000
	s_addc_u32 s59, s51, -1
	s_add_i32 s4, s86, s80
	s_mov_b32 s5, m0
	s_mov_b32 m0, s4
	s_nop 0
	global_load_lds_dwordx4 v252, s[58:59]
	s_mov_b32 m0, s5
	ds_read_b128 v[164:167], v248
	ds_read_b128 v[168:171], v248 offset:1024
	ds_read_b128 v[172:175], v248 offset:2048
	ds_read_b128 v[236:239], v248 offset:3072
	v_add_u32_e32 v240, s89, v249
	ds_read_b128 v[204:207], v240
	ds_read_b128 v[208:211], v240 offset:512
	ds_read_b128 v[212:215], v240 offset:2048
	ds_read_b128 v[216:219], v240 offset:2560
	ds_read_b128 v[220:223], v240 offset:4096
	ds_read_b128 v[224:227], v240 offset:4608
	ds_read_b128 v[228:231], v240 offset:6144
	ds_read_b128 v[232:235], v240 offset:6656
	s_waitcnt vmcnt(0) lgkmcnt(0)
	s_barrier
	v_mov_b32_e32 v126, v178
	v_cmp_lt_f32_e32 vcc, s67, v126
	s_branch .LBB0_436

; #define A128_WAITBAR() asm volatile("s_waitcnt vmcnt(0) lgkmcnt(0)\n\ts_barrier":::"memory")
; #define SB() __builtin_amdgcn_sched_barrier(0)
; #define MF32(a,b,c) __builtin_amdgcn_mfma_f32_32x32x16_bf16(a,b,c,0,0,0)
; #define EXP1(x) x=__builtin_amdgcn_exp2f((x)-mh_)
;   #define KF(i) LDSQ(kpn+((i)>>1)*2048+((i)&1)*512)
; template<int THRL,bool FIRST> __device__ __forceinline__ void step_main(f32x16&p0,f32x16&p1,f32x16&n0,f32x16&n1,St&S,lds_cptr kpn,lds_cptr qp,lds_cptr vp,float*wsf,int r32,int hi,float&rm){
;     ...
;   bf16x8 ka=KF(0),kb=KF(1),kc=KF(2),kd=KF(3),qa=QF(0),qb=QF(1);
;   decide<THRL,FIRST>(rm,S,wsf,r32,hi);
;   u32x4 pw0,pw1,pw2,pw3; const float mh_=S.mhat; const f32x16 z=f32x16{};
;   SB();
;   n0=MF32(ka,qa,z); ka=KF(4); EXP1(p0[0]);EXP1(p0[1]);EXP1(p0[2]); SB();
;   n1=MF32(kb,qa,z); kb=KF(5); qa=QF(2); EXP1(p0[3]);EXP1(p0[4]);EXP1(p0[5]); SB();
;   n0=MF32(kc,qb,n0);   kc=KF(6); EXP1(p0[6]);EXP1(p0[7]);EXP1(p0[8]); SB();
;   n1=MF32(kd,qb,n1);   kd=KF(7); qb=QF(3); EXP1(p0[9]);EXP1(p0[10]);EXP1(p0[11]); SB();
;   bf16x8 vfa=vfrag(vp,0);
;   n0=MF32(ka,qa,n0);   EXP1(p0[12]);EXP1(p0[13]);EXP1(p0[14]); pw0=packw(p0,0); SB();
;   bf16x8 vfb=vfrag(vp,1);
;   n1=MF32(kb,qa,n1);   EXP1(p0[15]);EXP1(p1[0]);EXP1(p1[1]); SB();
;   bf16x8 vfc=vfrag(vp,2);
;   n0=MF32(kc,qb,n0);   EXP1(p1[2]);EXP1(p1[3]);EXP1(p1[4]); pw1=packw(p0,8); SB();
;   bf16x8 vfd=vfrag(vp,3);
;   n1=MF32(kd,qb,n1);   EXP1(p1[5]);EXP1(p1[6]);EXP1(p1[7]); SB();
;     ...
;   float sa=p0[0]+p0[1];
;     ...
;   PVG(0,pw0,vfa,4, p0[2],p0[3],p0[4],p0[5],   do{EXP1(p1[8]);EXP1(p1[9]);}while(0));
;   PVG(1,pw0,vfb,5, p0[6],p0[7],p0[8],p0[9], do{EXP1(p1[10]);EXP1(p1[11]);}while(0));
;   PVG(2,pw0,vfc,6, p0[10],p0[11],p0[12],p0[13], do{EXP1(p1[12]);EXP1(p1[13]);}while(0));
;   PVG(3,pw0,vfd,7, p0[14],p0[15],p1[0],p1[1],   do{EXP1(p1[14]);EXP1(p1[15]);}while(0));
;   PVG(4,pw1,vfa,8, p1[2],p1[3],p1[4],p1[5],   pw2=packw(p1,0));
;   PVG(5,pw1,vfb,9, p1[6],p1[7],p1[8],p1[9], pw3=packw(p1,8));
; template<int THRL> __device__ __forceinline__ void unit(int qb,const bf16*Q,const bf16*K,const bf16*V,bf16*O,char*shm){
;     ...
;       DMA_K(t+2,ks2); DMA_V(t+1,VBUF);
;       step_main<THRL,false>(pA0,pA1,pB0,pB1,S,kp0+ks1,qp,vp0,wsf,r32,hi,rm); A128_WAITBAR(); ROT();
;       DMA_K(t+3,ks2); DMA_V(t+2,0);
;       step_main<THRL,false>(pB0,pB1,pA0,pA1,S,kp0+ks1,qp,vp0+VBUF,wsf,r32,hi,rm); A128_WAITBAR(); ROT();
.LBB0_435:
	s_add_i32 s4, s89, 0x2000
	s_cmpk_lg_i32 s89, 0x4000
	s_cselect_b32 s86, s4, 0
	s_add_i32 s88, s88, 2
	v_mfma_f32_32x32x16_bf16 v[98:113], v[204:207], v[164:167], v[146:161]
	s_add_i32 s4, s86, s80
	s_add_u32 s58, s50, 0xc0000
	s_addc_u32 s59, s51, 0
	s_mov_b32 s5, m0
	s_mov_b32 m0, s4
	s_nop 0
	global_load_lds_dwordx4 v252, s[58:59]
	s_mov_b32 m0, s5
	v_exp_f32_e32 v130, v130
	v_exp_f32_e32 v131, v131
	v_exp_f32_e32 v132, v132
	v_exp_f32_e32 v133, v133
	v_exp_f32_e32 v134, v134
	v_exp_f32_e32 v135, v135
	v_mfma_f32_32x32x16_bf16 v[82:97], v[208:211], v[164:167], v[146:161]
	s_add_u32 s58, s48, 0xc0000
	s_addc_u32 s59, s49, 0
	s_mov_b32 s4, m0
	s_mov_b32 m0, s78
	s_nop 0
	global_load_lds_dwordx4 v250, s[58:59]
	s_mov_b32 m0, s4
	v_mfma_f32_32x32x16_bf16 v[98:113], v[212:215], v[168:171], v[98:113]
	s_add_u32 s58, s48, 0xc0080
	s_addc_u32 s59, s49, 0
	s_mov_b32 s4, m0
	s_mov_b32 m0, s79
	s_nop 0
	global_load_lds_dwordx4 v250, s[58:59]
	s_mov_b32 m0, s4
	v_exp_f32_e32 v136, v136
	v_exp_f32_e32 v137, v137
	v_exp_f32_e32 v138, v138
	v_mfma_f32_32x32x16_bf16 v[82:97], v[216:219], v[168:171], v[82:97]
	v_exp_f32_e32 v139, v139
	v_exp_f32_e32 v140, v140
	v_exp_f32_e32 v141, v141
	v_mfma_f32_32x32x16_bf16 v[98:113], v[220:223], v[172:175], v[98:113]
	v_exp_f32_e32 v142, v142
	ds_read_b64_tr_b16 v[4:5], v246 offset:40960
	ds_read_b64_tr_b16 v[6:7], v246 offset:41472
	v_exp_f32_e32 v143, v143
	v_exp_f32_e32 v144, v144
	v_cvt_pk_bf16_f32 v8, v130, v131
	v_cvt_pk_bf16_f32 v9, v132, v133
	v_cvt_pk_bf16_f32 v10, v134, v135
	v_cvt_pk_bf16_f32 v11, v136, v137
	v_mfma_f32_32x32x16_bf16 v[82:97], v[224:227], v[172:175], v[82:97]
	ds_read_b64_tr_b16 v[178:179], v246 offset:45056
	ds_read_b64_tr_b16 v[180:181], v246 offset:45568
	v_exp_f32_e32 v145, v145
	v_exp_f32_e32 v114, v114
	v_exp_f32_e32 v115, v115
	v_mfma_f32_32x32x16_bf16 v[98:113], v[228:231], v[236:239], v[98:113]
	ds_read_b64_tr_b16 v[182:183], v246 offset:49152
	ds_read_b64_tr_b16 v[184:185], v246 offset:49664
	v_exp_f32_e32 v116, v116
	v_exp_f32_e32 v117, v117
	v_exp_f32_e32 v118, v118
	v_cvt_pk_bf16_f32 v186, v138, v139
	v_cvt_pk_bf16_f32 v187, v140, v141
	v_cvt_pk_bf16_f32 v188, v142, v143
	v_cvt_pk_bf16_f32 v189, v144, v145
	v_mfma_f32_32x32x16_bf16 v[82:97], v[232:235], v[236:239], v[82:97]
	v_add_u32_e32 v240, s89, v249
	ds_read_b64_tr_b16 v[190:191], v246 offset:53248
	ds_read_b64_tr_b16 v[192:193], v246 offset:53760
	v_exp_f32_e32 v119, v119
	v_exp_f32_e32 v120, v120
	v_exp_f32_e32 v121, v121
	s_waitcnt lgkmcnt(6)
	v_mfma_f32_32x32x16_bf16 v[18:33], v[8:11], v[4:7], v[18:33]
	ds_read_b64_tr_b16 v[12:13], v246 offset:41984
	ds_read_b64_tr_b16 v[14:15], v246 offset:42496
	ds_read_b128 v[204:207], v240
	v_add_f32_e32 v194, v130, v131
	v_exp_f32_e32 v122, v122
	v_exp_f32_e32 v123, v123
	v_add_f32_e32 v194, v132, v194
	v_add_f32_e32 v4, v133, v194
	v_add_f32_e32 v4, v134, v4
	v_add_f32_e32 v194, v135, v4
	s_waitcnt lgkmcnt(7)
	v_mfma_f32_32x32x16_bf16 v[34:49], v[8:11], v[178:181], v[34:49]
	ds_read_b64_tr_b16 v[4:5], v246 offset:46080
	ds_read_b64_tr_b16 v[6:7], v246 offset:46592
	ds_read_b128 v[208:211], v240 offset:512
	v_exp_f32_e32 v124, v124
	v_exp_f32_e32 v125, v125
	v_add_f32_e32 v194, v136, v194
	v_add_f32_e32 v178, v137, v194
	v_add_f32_e32 v178, v138, v178
	v_add_f32_e32 v194, v139, v178
	s_waitcnt lgkmcnt(8)
	v_mfma_f32_32x32x16_bf16 v[50:65], v[8:11], v[182:185], v[50:65]
	ds_read_b64_tr_b16 v[178:179], v246 offset:50176
	ds_read_b64_tr_b16 v[180:181], v246 offset:50688
	ds_read_b128 v[212:215], v240 offset:2048
	v_exp_f32_e32 v126, v126
	v_exp_f32_e32 v127, v127
	v_add_f32_e32 v194, v140, v194
	v_add_f32_e32 v182, v141, v194
	v_add_f32_e32 v182, v142, v182
	v_add_f32_e32 v194, v143, v182
	s_waitcnt lgkmcnt(9)
	v_mfma_f32_32x32x16_bf16 v[66:81], v[8:11], v[190:193], v[66:81]
	ds_read_b64_tr_b16 v[182:183], v246 offset:54272
	ds_read_b64_tr_b16 v[184:185], v246 offset:54784
	ds_read_b128 v[216:219], v240 offset:2560
	v_exp_f32_e32 v128, v128
	v_exp_f32_e32 v129, v129
	v_add_f32_e32 v194, v144, v194
	v_add_f32_e32 v8, v145, v194
	v_add_f32_e32 v8, v114, v8
	v_add_f32_e32 v190, v115, v8
	s_waitcnt lgkmcnt(10)
	v_mfma_f32_32x32x16_bf16 v[18:33], v[186:189], v[12:15], v[18:33]
	ds_read_b64_tr_b16 v[8:9], v246 offset:43008
	ds_read_b64_tr_b16 v[10:11], v246 offset:43520
	ds_read_b128 v[220:223], v240 offset:4096
	v_add_f32_e32 v190, v116, v190
	v_add_f32_e32 v190, v117, v190
	v_add_f32_e32 v190, v118, v190
	v_add_f32_e32 v194, v119, v190
	v_cvt_pk_bf16_f32 v12, v114, v115
	v_cvt_pk_bf16_f32 v13, v116, v117
	v_cvt_pk_bf16_f32 v14, v118, v119
	v_cvt_pk_bf16_f32 v15, v120, v121
	s_waitcnt lgkmcnt(10)
	v_mfma_f32_32x32x16_bf16 v[34:49], v[186:189], v[4:7], v[34:49]
	ds_read_b64_tr_b16 v[190:191], v246 offset:47104
	ds_read_b64_tr_b16 v[192:193], v246 offset:47616
	ds_read_b128 v[224:227], v240 offset:4608
	v_add_f32_e32 v194, v120, v194
	v_add_f32_e32 v194, v121, v194
	v_add_f32_e32 v194, v122, v194
	v_add_f32_e32 v198, v123, v194
	v_cvt_pk_bf16_f32 v4, v122, v123
	v_cvt_pk_bf16_f32 v5, v124, v125
	v_cvt_pk_bf16_f32 v6, v126, v127
	v_cvt_pk_bf16_f32 v7, v128, v129
	s_waitcnt lgkmcnt(10)
	v_mfma_f32_32x32x16_bf16 v[50:65], v[186:189], v[178:181], v[50:65]
	ds_read_b64_tr_b16 v[194:195], v246 offset:51200
	ds_read_b64_tr_b16 v[196:197], v246 offset:51712
	ds_read_b128 v[228:231], v240 offset:6144
	v_add_f32_e32 v198, v124, v198
	v_add_f32_e32 v198, v125, v198
	v_add_f32_e32 v198, v126, v198
	v_add_f32_e32 v198, v127, v198
	s_waitcnt lgkmcnt(10)
; __device__ __forceinline__ int crow(int r,int hi){return (r&3)+8*(r>>2)+4*hi;}
; __device__ __forceinline__ float max3f(float a,float b,float c){float r;asm("v_max3_f32 %0, %1, %2, %3":"=v"(r):"v"(a),"v"(b),"v"(c));return r;}
; __device__ __forceinline__ float max2f(float a,float b){float r;asm("v_max_f32_e32 %0, %1, %2":"=v"(r):"v"(a),"v"(b));return r;}
;   #define PVG(i,PW,VF,NEXTI,X0,X1,Y0,Y1,EXTRA) do{ S.o[(i)&3]=MF32(__builtin_bit_cast(bf16x8,PW),VF,S.o[(i)&3]); if((NEXTI)<16){ VF=vfrag(vp,(NEXTI)<16?(NEXTI):0); } sa+=X0; sa+=X1; sa+=Y0; sa+=Y1; EXTRA; SB(); }while(0)
; template<int THRL,bool FIRST> __device__ __forceinline__ void decide(float rm,St&S,float*wsf,int r32,int hi){
;     ...
;   else if(__any(rm-S.mhat>(float)THRL)){
;     const float dl=__builtin_fmaxf(rm-S.mhat,0.f); S.mhat+=dl;
;     const float f=__builtin_amdgcn_exp2f(-dl); S.l_reg*=f; if(hi==0)wsf[r32]=f;
;     asm volatile("s_waitcnt lgkmcnt(0)":::"memory");
;     #pragma unroll
;     for(int r=0;r<16;++r){ const float fr=wsf[crow(r,hi)];
;       #pragma unroll
;       for(int d=0;d<4;++d)S.o[d][r]*=fr; }
;   }
; template<int THRL,bool FIRST> __device__ __forceinline__ void step_main(f32x16&p0,f32x16&p1,f32x16&n0,f32x16&n1,St&S,lds_cptr kpn,lds_cptr qp,lds_cptr vp,float*wsf,int r32,int hi,float&rm){
;     ...
;   float ma,mb;
;     ...
;   PVG(8,pw2,vfa,12,0.f,0.f,0.f,0.f, do{ma=max3f(n0[0],n0[1],n1[0]);mb=max3f(n0[2],n0[3],n1[1]);PINAB();}while(0));
;   PVG(9,pw2,vfb,13,0.f,0.f,0.f,0.f, do{ma=max3f(ma,n1[2],n1[3]);mb=max3f(mb,n0[4],n0[5]);PINAB();}while(0));
;   PVG(10,pw2,vfc,14,0.f,0.f,0.f,0.f, do{ma=max3f(ma,n0[6],n0[7]);mb=max3f(mb,n1[4],n1[5]);PINAB();}while(0));
;   PVG(11,pw2,vfd,15,0.f,0.f,0.f,0.f, do{ma=max3f(ma,n1[6],n1[7]);mb=max3f(mb,n0[8],n0[9]);PINAB();}while(0));
;   PVG(12,pw3,vfa,16,0.f,0.f,0.f,0.f, do{ma=max3f(ma,n0[10],n0[11]);mb=max3f(mb,n1[8],n1[9]);PINAB();}while(0));
;   PVG(13,pw3,vfb,16,0.f,0.f,0.f,0.f, do{ma=max3f(ma,n1[10],n1[11]);mb=max3f(mb,n0[12],n0[13]);PINAB();}while(0));
;   PVG(14,pw3,vfc,16,0.f,0.f,0.f,0.f, do{ma=max3f(ma,n0[14],n0[15]);mb=max3f(mb,n1[12],n1[13]);PINAB();}while(0));
;   PVG(15,pw3,vfd,16,0.f,0.f,0.f,0.f, do{ma=max3f(ma,n1[14],n1[15]);ma=max2f(ma,mb);PINAB();}while(0));
;     ...
;   { auto rr=__builtin_amdgcn_permlane32_swap(__float_as_uint(ma),__float_as_uint(ma),false,false); rm=max2f(__uint_as_float(rr[0]),__uint_as_float(rr[1])); }
;     ...
;   S.l_reg+=sa;
	v_mfma_f32_32x32x16_bf16 v[66:81], v[186:189], v[182:185], v[66:81]
	ds_read_b64_tr_b16 v[178:179], v246 offset:55296
	ds_read_b64_tr_b16 v[180:181], v246 offset:55808
	ds_read_b128 v[232:235], v240 offset:6656
	v_add_f32_e32 v198, v128, v198
	v_add_f32_e32 v198, v129, v198
	v_add_f32_e32 v198, 0, v198
	s_waitcnt lgkmcnt(10)
	v_mfma_f32_32x32x16_bf16 v[18:33], v[12:15], v[8:11], v[18:33]
	ds_read_b64_tr_b16 v[182:183], v246 offset:44032
	ds_read_b64_tr_b16 v[184:185], v246 offset:44544
	v_max3_f32 v186, v98, v99, v82
	v_max3_f32 v187, v100, v101, v83
	s_nop 0
	s_waitcnt lgkmcnt(9)
	v_mfma_f32_32x32x16_bf16 v[34:49], v[12:15], v[190:193], v[34:49]
	ds_read_b64_tr_b16 v[8:9], v246 offset:48128
	ds_read_b64_tr_b16 v[10:11], v246 offset:48640
	v_max3_f32 v199, v186, v84, v85
	v_max3_f32 v200, v187, v102, v103
	s_nop 0
	s_waitcnt lgkmcnt(8)
	v_mfma_f32_32x32x16_bf16 v[50:65], v[12:15], v[194:197], v[50:65]
	ds_read_b64_tr_b16 v[186:187], v246 offset:52224
	ds_read_b64_tr_b16 v[188:189], v246 offset:52736
	v_max3_f32 v199, v199, v104, v105
	v_max3_f32 v200, v200, v86, v87
	s_nop 0
	s_waitcnt lgkmcnt(7)
	v_mfma_f32_32x32x16_bf16 v[66:81], v[12:15], v[178:181], v[66:81]
	ds_read_b64_tr_b16 v[190:191], v246 offset:56320
	ds_read_b64_tr_b16 v[192:193], v246 offset:56832
	v_max3_f32 v194, v199, v88, v89
	v_max3_f32 v195, v200, v106, v107
	s_nop 0
	s_waitcnt lgkmcnt(6)
	v_mfma_f32_32x32x16_bf16 v[18:33], v[4:7], v[182:185], v[18:33]
	v_max3_f32 v12, v194, v108, v109
	v_max3_f32 v13, v195, v90, v91
	s_nop 0
	s_waitcnt lgkmcnt(4)
	v_mfma_f32_32x32x16_bf16 v[34:49], v[4:7], v[8:11], v[34:49]
	v_max3_f32 v12, v12, v92, v93
	v_max3_f32 v13, v13, v110, v111
	s_nop 0
	s_waitcnt lgkmcnt(2)
	v_mfma_f32_32x32x16_bf16 v[50:65], v[4:7], v[186:189], v[50:65]
	v_max3_f32 v8, v12, v112, v113
	v_max3_f32 v9, v13, v94, v95
	s_nop 0
	s_waitcnt lgkmcnt(0)
	v_mfma_f32_32x32x16_bf16 v[66:81], v[4:7], v[190:193], v[66:81]
	v_max3_f32 v8, v8, v96, v97
	s_nop 0
	v_max_f32_e32 v8, v8, v9
	s_nop 0
	s_add_u32 s50, s50, 0x180000
	s_addc_u32 s51, s51, 0
	s_add_u32 s48, s48, 0x180000
	s_addc_u32 s49, s49, 0
	v_mov_b32_e32 v4, v8
	v_add_f32_e32 v251, v17, v198
	s_cmp_lt_u32 s88, s87
	v_permlane32_swap_b32_e32 v8, v4
	v_max_f32_e32 v178, v8, v4
	v_mov_b32_e32 v126, v178
	v_cmp_lt_f32_e32 vcc, s67, v126
	s_waitcnt vmcnt(0) lgkmcnt(0)
	s_barrier
	s_cbranch_scc0 .LBB0_443
.LBB0_436:
	s_cbranch_vccz .LBB0_440
	v_max_f32_e32 v126, v126, v126
	v_max_f32_e32 v126, 0, v126
	v_exp_f32_e64 v127, -v126
	s_and_saveexec_b64 s[58:59], s[6:7]
	ds_write_b32 v16, v127
	s_or_b64 exec, exec, s[58:59]
	s_waitcnt lgkmcnt(0)
	v_add_u32_e32 v140, s76, v2
	ds_read_b128 v[128:131], v140 offset:64
	ds_read_b128 v[132:135], v140 offset:96
	ds_read_b128 v[136:139], v140
	ds_read_b128 v[140:143], v140 offset:32
	v_add_f32_e32 v247, v247, v126
	v_sub_f32_e32 v146, v146, v126
	v_sub_f32_e32 v147, v147, v126
	v_sub_f32_e32 v148, v148, v126
	v_sub_f32_e32 v149, v149, v126
	v_sub_f32_e32 v150, v150, v126
	v_sub_f32_e32 v151, v151, v126
	v_sub_f32_e32 v152, v152, v126
	v_sub_f32_e32 v153, v153, v126
	v_sub_f32_e32 v154, v154, v126
	v_sub_f32_e32 v155, v155, v126
	v_sub_f32_e32 v156, v156, v126
	v_sub_f32_e32 v157, v157, v126
	v_sub_f32_e32 v158, v158, v126
	v_sub_f32_e32 v159, v159, v126
	v_sub_f32_e32 v160, v160, v126
	v_sub_f32_e32 v161, v161, v126
	v_sub_f32_e32 v82, v82, v126
	v_sub_f32_e32 v83, v83, v126
	v_sub_f32_e32 v84, v84, v126
	v_sub_f32_e32 v85, v85, v126
	v_sub_f32_e32 v86, v86, v126
	v_sub_f32_e32 v87, v87, v126
	v_sub_f32_e32 v88, v88, v126
	v_sub_f32_e32 v89, v89, v126
	v_sub_f32_e32 v90, v90, v126
	v_sub_f32_e32 v91, v91, v126
	v_sub_f32_e32 v92, v92, v126
	v_sub_f32_e32 v93, v93, v126
	v_sub_f32_e32 v94, v94, v126
	v_sub_f32_e32 v95, v95, v126
	v_sub_f32_e32 v96, v96, v126
	v_sub_f32_e32 v97, v97, v126
	v_sub_f32_e32 v98, v98, v126
	v_sub_f32_e32 v99, v99, v126
	v_sub_f32_e32 v100, v100, v126
	v_sub_f32_e32 v101, v101, v126
	v_sub_f32_e32 v102, v102, v126
	v_sub_f32_e32 v103, v103, v126
	v_sub_f32_e32 v104, v104, v126
	v_sub_f32_e32 v105, v105, v126
	v_sub_f32_e32 v106, v106, v126
	v_sub_f32_e32 v107, v107, v126
	v_sub_f32_e32 v108, v108, v126
	v_sub_f32_e32 v109, v109, v126
	v_sub_f32_e32 v110, v110, v126
	v_sub_f32_e32 v111, v111, v126
	v_sub_f32_e32 v112, v112, v126
	v_sub_f32_e32 v113, v113, v126
	v_mul_f32_e32 v251, v251, v127
	s_waitcnt lgkmcnt(2)
	v_pk_mul_f32 v[30:31], v[30:31], v[132:133]
	v_pk_mul_f32 v[26:27], v[26:27], v[128:129]
	s_waitcnt lgkmcnt(0)
	v_pk_mul_f32 v[22:23], v[22:23], v[140:141]
	v_pk_mul_f32 v[32:33], v[32:33], v[134:135]
	v_pk_mul_f32 v[28:29], v[28:29], v[130:131]
	v_pk_mul_f32 v[24:25], v[24:25], v[142:143]
	v_pk_mul_f32 v[20:21], v[20:21], v[138:139]
	v_pk_mul_f32 v[18:19], v[18:19], v[136:137]
	v_pk_mul_f32 v[46:47], v[46:47], v[132:133]
	v_pk_mul_f32 v[42:43], v[42:43], v[128:129]
	v_pk_mul_f32 v[38:39], v[38:39], v[140:141]
	v_pk_mul_f32 v[48:49], v[48:49], v[134:135]
	v_pk_mul_f32 v[44:45], v[44:45], v[130:131]
	v_pk_mul_f32 v[40:41], v[40:41], v[142:143]
	v_pk_mul_f32 v[36:37], v[36:37], v[138:139]
	v_pk_mul_f32 v[34:35], v[34:35], v[136:137]
	v_pk_mul_f32 v[62:63], v[62:63], v[132:133]
	v_pk_mul_f32 v[58:59], v[58:59], v[128:129]
	v_pk_mul_f32 v[54:55], v[54:55], v[140:141]
	v_pk_mul_f32 v[64:65], v[64:65], v[134:135]
	v_pk_mul_f32 v[60:61], v[60:61], v[130:131]
	v_pk_mul_f32 v[56:57], v[56:57], v[142:143]
	v_pk_mul_f32 v[52:53], v[52:53], v[138:139]
	v_pk_mul_f32 v[50:51], v[50:51], v[136:137]
	v_pk_mul_f32 v[78:79], v[78:79], v[132:133]
	v_pk_mul_f32 v[74:75], v[74:75], v[128:129]
	v_pk_mul_f32 v[70:71], v[70:71], v[140:141]
	v_pk_mul_f32 v[80:81], v[80:81], v[134:135]
	v_pk_mul_f32 v[76:77], v[76:77], v[130:131]
	v_pk_mul_f32 v[72:73], v[72:73], v[142:143]
	v_pk_mul_f32 v[68:69], v[68:69], v[138:139]
	v_pk_mul_f32 v[66:67], v[66:67], v[136:137]
; #define A128_WAITBAR() asm volatile("s_waitcnt vmcnt(0) lgkmcnt(0)\n\ts_barrier":::"memory")
; #define SB() __builtin_amdgcn_sched_barrier(0)
; #define MF32(a,b,c) __builtin_amdgcn_mfma_f32_32x32x16_bf16(a,b,c,0,0,0)
; #define EXP1(x) x=__builtin_amdgcn_exp2f((x)-mh_)
;   #define KF(i) LDSQ(kpn+((i)>>1)*2048+((i)&1)*512)
; template<int THRL,bool FIRST> __device__ __forceinline__ void step_main(f32x16&p0,f32x16&p1,f32x16&n0,f32x16&n1,St&S,lds_cptr kpn,lds_cptr qp,lds_cptr vp,float*wsf,int r32,int hi,float&rm){
;     ...
;   bf16x8 ka=KF(0),kb=KF(1),kc=KF(2),kd=KF(3),qa=QF(0),qb=QF(1);
;   decide<THRL,FIRST>(rm,S,wsf,r32,hi);
;   u32x4 pw0,pw1,pw2,pw3; const float mh_=S.mhat; const f32x16 z=f32x16{};
;   SB();
;   n0=MF32(ka,qa,z); ka=KF(4); EXP1(p0[0]);EXP1(p0[1]);EXP1(p0[2]); SB();
;   n1=MF32(kb,qa,z); kb=KF(5); qa=QF(2); EXP1(p0[3]);EXP1(p0[4]);EXP1(p0[5]); SB();
;   n0=MF32(kc,qb,n0);   kc=KF(6); EXP1(p0[6]);EXP1(p0[7]);EXP1(p0[8]); SB();
;   n1=MF32(kd,qb,n1);   kd=KF(7); qb=QF(3); EXP1(p0[9]);EXP1(p0[10]);EXP1(p0[11]); SB();
;   bf16x8 vfa=vfrag(vp,0);
;   n0=MF32(ka,qa,n0);   EXP1(p0[12]);EXP1(p0[13]);EXP1(p0[14]); pw0=packw(p0,0); SB();
;   bf16x8 vfb=vfrag(vp,1);
;   n1=MF32(kb,qa,n1);   EXP1(p0[15]);EXP1(p1[0]);EXP1(p1[1]); SB();
;   bf16x8 vfc=vfrag(vp,2);
;   n0=MF32(kc,qb,n0);   EXP1(p1[2]);EXP1(p1[3]);EXP1(p1[4]); pw1=packw(p0,8); SB();
;   bf16x8 vfd=vfrag(vp,3);
;   n1=MF32(kd,qb,n1);   EXP1(p1[5]);EXP1(p1[6]);EXP1(p1[7]); SB();
;     ...
;   float sa=p0[0]+p0[1];
;     ...
;   PVG(0,pw0,vfa,4, p0[2],p0[3],p0[4],p0[5],   do{EXP1(p1[8]);EXP1(p1[9]);}while(0));
;   PVG(1,pw0,vfb,5, p0[6],p0[7],p0[8],p0[9], do{EXP1(p1[10]);EXP1(p1[11]);}while(0));
;   PVG(2,pw0,vfc,6, p0[10],p0[11],p0[12],p0[13], do{EXP1(p1[12]);EXP1(p1[13]);}while(0));
;   PVG(3,pw0,vfd,7, p0[14],p0[15],p1[0],p1[1],   do{EXP1(p1[14]);EXP1(p1[15]);}while(0));
;   PVG(4,pw1,vfa,8, p1[2],p1[3],p1[4],p1[5],   pw2=packw(p1,0));
;   PVG(5,pw1,vfb,9, p1[6],p1[7],p1[8],p1[9], pw3=packw(p1,8));
; template<int THRL> __device__ __forceinline__ void unit(int qb,const bf16*Q,const bf16*K,const bf16*V,bf16*O,char*shm){
;     ...
;       DMA_K(t+2,ks2); DMA_V(t+1,VBUF);
;       step_main<THRL,false>(pA0,pA1,pB0,pB1,S,kp0+ks1,qp,vp0,wsf,r32,hi,rm); A128_WAITBAR(); ROT();
;       DMA_K(t+3,ks2); DMA_V(t+2,0);
;       step_main<THRL,false>(pB0,pB1,pA0,pA1,S,kp0+ks1,qp,vp0+VBUF,wsf,r32,hi,rm); A128_WAITBAR(); ROT();
.LBB0_440:
	s_add_i32 s4, s86, 0x2000
	s_cmpk_lg_i32 s86, 0x4000
	s_cselect_b32 s89, s4, 0
	v_mfma_f32_32x32x16_bf16 v[130:145], v[204:207], v[164:167], v[146:161]
	s_add_i32 s4, s89, s80
	s_mov_b32 s5, m0
	s_mov_b32 m0, s4
	s_nop 0
	global_load_lds_dwordx4 v252, s[50:51]
	s_mov_b32 m0, s5
	v_exp_f32_e32 v190, v98
	v_exp_f32_e32 v191, v99
	v_exp_f32_e32 v192, v100
	v_mfma_f32_32x32x16_bf16 v[114:129], v[208:211], v[164:167], v[146:161]
	s_mov_b32 s4, m0
	s_mov_b32 m0, s77
	s_nop 0
	global_load_lds_dwordx4 v250, s[48:49]
	s_mov_b32 m0, s4
	v_exp_f32_e32 v193, v101
	v_exp_f32_e32 v194, v102
	v_exp_f32_e32 v195, v103
	v_mfma_f32_32x32x16_bf16 v[130:145], v[212:215], v[168:171], v[130:145]
	s_add_u32 s58, s48, 0x80
	s_addc_u32 s59, s49, 0
	s_mov_b32 s4, m0
	s_mov_b32 m0, s39
	s_nop 0
	global_load_lds_dwordx4 v250, s[58:59]
	s_mov_b32 m0, s4
	v_exp_f32_e32 v196, v104
	v_exp_f32_e32 v197, v105
	v_exp_f32_e32 v198, v106
	v_mfma_f32_32x32x16_bf16 v[114:129], v[216:219], v[168:171], v[114:129]
	v_exp_f32_e32 v17, v107
	v_exp_f32_e32 v199, v108
	v_exp_f32_e32 v200, v109
	v_mfma_f32_32x32x16_bf16 v[130:145], v[220:223], v[172:175], v[130:145]
	v_exp_f32_e32 v201, v110
	ds_read_b64_tr_b16 v[4:5], v246 offset:24576
	ds_read_b64_tr_b16 v[6:7], v246 offset:25088
	v_exp_f32_e32 v202, v111
	v_exp_f32_e32 v178, v112
	v_cvt_pk_bf16_f32 v8, v190, v191
	v_cvt_pk_bf16_f32 v9, v192, v193
	v_cvt_pk_bf16_f32 v10, v194, v195
	v_cvt_pk_bf16_f32 v11, v196, v197
	v_mfma_f32_32x32x16_bf16 v[114:129], v[224:227], v[172:175], v[114:129]
	ds_read_b64_tr_b16 v[106:107], v246 offset:28672
	ds_read_b64_tr_b16 v[108:109], v246 offset:29184
	v_exp_f32_e32 v180, v82
	v_exp_f32_e32 v179, v113
	v_exp_f32_e32 v181, v83
	v_mfma_f32_32x32x16_bf16 v[130:145], v[228:231], v[236:239], v[130:145]
	ds_read_b64_tr_b16 v[110:111], v246 offset:32768
	ds_read_b64_tr_b16 v[112:113], v246 offset:33280
	v_exp_f32_e32 v182, v84
	v_exp_f32_e32 v183, v85
	v_exp_f32_e32 v184, v86
	v_cvt_pk_bf16_f32 v82, v198, v17
	v_cvt_pk_bf16_f32 v83, v199, v200
	v_cvt_pk_bf16_f32 v84, v201, v202
	v_cvt_pk_bf16_f32 v85, v178, v179
	v_mfma_f32_32x32x16_bf16 v[114:129], v[232:235], v[236:239], v[114:129]
	v_add_u32_e32 v240, s86, v249
	ds_read_b64_tr_b16 v[98:99], v246 offset:36864
	ds_read_b64_tr_b16 v[100:101], v246 offset:37376
	v_exp_f32_e32 v185, v87
	v_exp_f32_e32 v186, v88
	v_exp_f32_e32 v187, v89
	s_waitcnt lgkmcnt(6)
	v_mfma_f32_32x32x16_bf16 v[18:33], v[8:11], v[4:7], v[18:33]
	ds_read_b128 v[204:207], v240
	v_add_f32_e32 v86, v190, v191
	ds_read_b64_tr_b16 v[12:13], v246 offset:25600
	ds_read_b64_tr_b16 v[14:15], v246 offset:26112
	v_add_f32_e32 v86, v192, v86
	v_exp_f32_e32 v103, v91
	v_add_f32_e32 v4, v193, v86
	v_add_f32_e32 v4, v194, v4
	v_add_f32_e32 v86, v195, v4
	v_exp_f32_e32 v102, v90
	s_waitcnt lgkmcnt(7)
	v_mfma_f32_32x32x16_bf16 v[34:49], v[8:11], v[106:109], v[34:49]
	ds_read_b64_tr_b16 v[4:5], v246 offset:29696
	ds_read_b64_tr_b16 v[6:7], v246 offset:30208
	ds_read_b128 v[208:211], v240 offset:512
	v_add_f32_e32 v86, v196, v86
	v_add_f32_e32 v86, v197, v86
	v_add_f32_e32 v86, v198, v86
	v_exp_f32_e32 v104, v92
	v_add_f32_e32 v17, v17, v86
	v_exp_f32_e32 v105, v93
	s_waitcnt lgkmcnt(8)
	v_mfma_f32_32x32x16_bf16 v[50:65], v[8:11], v[110:113], v[50:65]
	ds_read_b64_tr_b16 v[86:87], v246 offset:33792
	ds_read_b64_tr_b16 v[88:89], v246 offset:34304
	ds_read_b128 v[212:215], v240 offset:2048
	v_add_f32_e32 v17, v199, v17
	v_add_f32_e32 v17, v200, v17
	v_add_f32_e32 v17, v201, v17
	v_exp_f32_e32 v106, v94
	v_add_f32_e32 v17, v202, v17
	v_exp_f32_e32 v107, v95
	s_waitcnt lgkmcnt(9)
	v_mfma_f32_32x32x16_bf16 v[66:81], v[8:11], v[98:101], v[66:81]
	ds_read_b64_tr_b16 v[90:91], v246 offset:37888
	ds_read_b64_tr_b16 v[92:93], v246 offset:38400
	ds_read_b128 v[216:219], v240 offset:2560
	v_add_f32_e32 v17, v178, v17
	v_add_f32_e32 v8, v179, v17
	v_add_f32_e32 v8, v180, v8
	v_exp_f32_e32 v108, v96
	v_add_f32_e32 v17, v181, v8
	v_exp_f32_e32 v109, v97
	s_waitcnt lgkmcnt(9)
; __device__ __forceinline__ float max3f(float a,float b,float c){float r;asm("v_max3_f32 %0, %1, %2, %3":"=v"(r):"v"(a),"v"(b),"v"(c));return r;}
; __device__ __forceinline__ float max2f(float a,float b){float r;asm("v_max_f32_e32 %0, %1, %2":"=v"(r):"v"(a),"v"(b));return r;}
;   #define PVG(i,PW,VF,NEXTI,X0,X1,Y0,Y1,EXTRA) do{ S.o[(i)&3]=MF32(__builtin_bit_cast(bf16x8,PW),VF,S.o[(i)&3]); if((NEXTI)<16){ VF=vfrag(vp,(NEXTI)<16?(NEXTI):0); } sa+=X0; sa+=X1; sa+=Y0; sa+=Y1; EXTRA; SB(); }while(0)
;   #define PINAB() asm volatile("":"+v"(ma),"+v"(mb))
; template<int THRL,bool FIRST> __device__ __forceinline__ void decide(float rm,St&S,float*wsf,int r32,int hi){
;     ...
;   else if(__any(rm-S.mhat>(float)THRL)){
;     const float dl=__builtin_fmaxf(rm-S.mhat,0.f); S.mhat+=dl;
;     const float f=__builtin_amdgcn_exp2f(-dl); S.l_reg*=f; if(hi==0)wsf[r32]=f;
;     asm volatile("s_waitcnt lgkmcnt(0)":::"memory");
;     #pragma unroll
; template<int THRL,bool FIRST> __device__ __forceinline__ void step_main(f32x16&p0,f32x16&p1,f32x16&n0,f32x16&n1,St&S,lds_cptr kpn,lds_cptr qp,lds_cptr vp,float*wsf,int r32,int hi,float&rm){
;     ...
;   float ma,mb;
;     ...
;   PVG(8,pw2,vfa,12,0.f,0.f,0.f,0.f, do{ma=max3f(n0[0],n0[1],n1[0]);mb=max3f(n0[2],n0[3],n1[1]);PINAB();}while(0));
;   PVG(9,pw2,vfb,13,0.f,0.f,0.f,0.f, do{ma=max3f(ma,n1[2],n1[3]);mb=max3f(mb,n0[4],n0[5]);PINAB();}while(0));
;   PVG(10,pw2,vfc,14,0.f,0.f,0.f,0.f, do{ma=max3f(ma,n0[6],n0[7]);mb=max3f(mb,n1[4],n1[5]);PINAB();}while(0));
;   PVG(11,pw2,vfd,15,0.f,0.f,0.f,0.f, do{ma=max3f(ma,n1[6],n1[7]);mb=max3f(mb,n0[8],n0[9]);PINAB();}while(0));
;   PVG(12,pw3,vfa,16,0.f,0.f,0.f,0.f, do{ma=max3f(ma,n0[10],n0[11]);mb=max3f(mb,n1[8],n1[9]);PINAB();}while(0));
;   PVG(13,pw3,vfb,16,0.f,0.f,0.f,0.f, do{ma=max3f(ma,n1[10],n1[11]);mb=max3f(mb,n0[12],n0[13]);PINAB();}while(0));
;   PVG(14,pw3,vfc,16,0.f,0.f,0.f,0.f, do{ma=max3f(ma,n0[14],n0[15]);mb=max3f(mb,n1[12],n1[13]);PINAB();}while(0));
;   PVG(15,pw3,vfd,16,0.f,0.f,0.f,0.f, do{ma=max3f(ma,n1[14],n1[15]);ma=max2f(ma,mb);PINAB();}while(0));
;     ...
;   { auto rr=__builtin_amdgcn_permlane32_swap(__float_as_uint(ma),__float_as_uint(ma),false,false); rm=max2f(__uint_as_float(rr[0]),__uint_as_float(rr[1])); }
;     ...
;   S.l_reg+=sa;
	v_mfma_f32_32x32x16_bf16 v[18:33], v[82:85], v[12:15], v[18:33]
	ds_read_b64_tr_b16 v[8:9], v246 offset:26624
	ds_read_b64_tr_b16 v[10:11], v246 offset:27136
	ds_read_b128 v[220:223], v240 offset:4096
	v_add_f32_e32 v17, v182, v17
	v_add_f32_e32 v17, v183, v17
	v_add_f32_e32 v17, v184, v17
	v_add_f32_e32 v17, v185, v17
	v_cvt_pk_bf16_f32 v12, v180, v181
	v_cvt_pk_bf16_f32 v13, v182, v183
	v_cvt_pk_bf16_f32 v14, v184, v185
	v_cvt_pk_bf16_f32 v15, v186, v187
	s_waitcnt lgkmcnt(10)
	v_mfma_f32_32x32x16_bf16 v[34:49], v[82:85], v[4:7], v[34:49]
	ds_read_b64_tr_b16 v[94:95], v246 offset:30720
	ds_read_b64_tr_b16 v[96:97], v246 offset:31232
	ds_read_b128 v[224:227], v240 offset:4608
	v_add_f32_e32 v17, v186, v17
	v_add_f32_e32 v17, v187, v17
	v_add_f32_e32 v17, v102, v17
	v_add_f32_e32 v17, v103, v17
	v_cvt_pk_bf16_f32 v4, v102, v103
	v_cvt_pk_bf16_f32 v5, v104, v105
	v_cvt_pk_bf16_f32 v6, v106, v107
	v_cvt_pk_bf16_f32 v7, v108, v109
	s_waitcnt lgkmcnt(10)
	v_mfma_f32_32x32x16_bf16 v[50:65], v[82:85], v[86:89], v[50:65]
	ds_read_b64_tr_b16 v[98:99], v246 offset:34816
	ds_read_b64_tr_b16 v[100:101], v246 offset:35328
	ds_read_b128 v[228:231], v240 offset:6144
	v_add_f32_e32 v17, v104, v17
	v_add_f32_e32 v17, v105, v17
	v_add_f32_e32 v17, v106, v17
	v_add_f32_e32 v17, v107, v17
	s_waitcnt lgkmcnt(10)
	v_mfma_f32_32x32x16_bf16 v[66:81], v[82:85], v[90:93], v[66:81]
	ds_read_b64_tr_b16 v[86:87], v246 offset:38912
	ds_read_b64_tr_b16 v[88:89], v246 offset:39424
	ds_read_b128 v[232:235], v240 offset:6656
	v_add_f32_e32 v17, v108, v17
	v_add_f32_e32 v17, v109, v17
	v_add_f32_e32 v17, 0, v17
	s_waitcnt lgkmcnt(10)
	v_mfma_f32_32x32x16_bf16 v[18:33], v[12:15], v[8:11], v[18:33]
	ds_read_b64_tr_b16 v[82:83], v246 offset:27648
	ds_read_b64_tr_b16 v[84:85], v246 offset:28160
	v_max3_f32 v90, v130, v131, v114
	v_max3_f32 v91, v132, v133, v115
	s_nop 0
	s_waitcnt lgkmcnt(9)
	v_mfma_f32_32x32x16_bf16 v[34:49], v[12:15], v[94:97], v[34:49]
	ds_read_b64_tr_b16 v[8:9], v246 offset:31744
	ds_read_b64_tr_b16 v[10:11], v246 offset:32256
	v_max3_f32 v102, v90, v116, v117
	v_max3_f32 v103, v91, v134, v135
	s_nop 0
	s_waitcnt lgkmcnt(8)
	v_mfma_f32_32x32x16_bf16 v[50:65], v[12:15], v[98:101], v[50:65]
	ds_read_b64_tr_b16 v[90:91], v246 offset:35840
	ds_read_b64_tr_b16 v[92:93], v246 offset:36352
	v_max3_f32 v102, v102, v136, v137
	v_max3_f32 v103, v103, v118, v119
	s_nop 0
	s_waitcnt lgkmcnt(7)
	v_mfma_f32_32x32x16_bf16 v[66:81], v[12:15], v[86:89], v[66:81]
	ds_read_b64_tr_b16 v[94:95], v246 offset:39936
	ds_read_b64_tr_b16 v[96:97], v246 offset:40448
	v_max3_f32 v98, v102, v120, v121
	v_max3_f32 v99, v103, v138, v139
	s_nop 0
	s_waitcnt lgkmcnt(6)
	v_mfma_f32_32x32x16_bf16 v[18:33], v[4:7], v[82:85], v[18:33]
	v_max3_f32 v12, v98, v140, v141
	v_max3_f32 v13, v99, v122, v123
	s_nop 0
	s_waitcnt lgkmcnt(4)
	v_mfma_f32_32x32x16_bf16 v[34:49], v[4:7], v[8:11], v[34:49]
	v_max3_f32 v12, v12, v124, v125
	v_max3_f32 v13, v13, v142, v143
	s_nop 0
	s_waitcnt lgkmcnt(2)
	v_mfma_f32_32x32x16_bf16 v[50:65], v[4:7], v[90:93], v[50:65]
	v_max3_f32 v8, v12, v144, v145
	v_max3_f32 v9, v13, v126, v127
	s_nop 0
	s_waitcnt lgkmcnt(0)
	v_mfma_f32_32x32x16_bf16 v[66:81], v[4:7], v[94:97], v[66:81]
	v_max3_f32 v8, v8, v128, v129
	s_nop 0
	v_max_f32_e32 v8, v8, v9
	s_nop 0
	v_mov_b32_e32 v162, v8
	v_mov_b32_e32 v163, v8
	v_add_f32_e32 v17, v251, v17
	s_nop 0
	v_permlane32_swap_b32_e32 v162, v163
	v_max_f32_e32 v94, v162, v163
	v_cmp_lt_f32_e32 vcc, s67, v94
	s_waitcnt vmcnt(0) lgkmcnt(0)
	s_barrier
	s_cbranch_vccz .LBB0_435
	v_max_f32_e32 v94, v94, v94
	v_max_f32_e32 v94, 0, v94
	v_exp_f32_e64 v95, -v94
	s_and_saveexec_b64 s[58:59], s[6:7]
	s_cbranch_execz .LBB0_434
	ds_write_b32 v16, v95
	s_branch .LBB0_434

; #define PG8_STAGE(bufoff, gbase, voff) do { _Pragma("unroll") for (int _i = 0; _i < 2; ++_i) \
;         __builtin_amdgcn_global_load_lds((const unsigned*)((const char*)(gbase) + (voff)[_i]), (PG8_LAS unsigned*)(lds + (bufoff) + ldsw + _i * 8192), 16, 0, 0); } while (0)
; #define PG8_LDA(dst, b, h) do { _Pragma("unroll") for (int m = 0; m < 4; ++m) _Pragma("unroll") for (int k = 0; k < 2; ++k) dst[m][k] = *(const PG8_LAS bf16x8*)(lds + PG8_SA(b, h) + aoff + m * 2048 + k * 1024); } while (0)
; #define PG8_LDB(dst, b, h) do { _Pragma("unroll") for (int n = 0; n < 2; ++n) _Pragma("unroll") for (int k = 0; k < 2; ++k) dst[n][k] = *(const PG8_LAS bf16x8*)(lds + PG8_SB(b, h) + boff + n * 2048 + k * 1024); } while (0)
; #define PG8_MMA(ai, bj, At, Bt) do { __builtin_amdgcn_s_setprio(1); _Pragma("unroll") for (int m = 0; m < 4; ++m) _Pragma("unroll") for (int n = 0; n < 2; ++n) _Pragma("unroll") for (int k = 0; k < 2; ++k) \
;         acc[ai][bj][m][n] = __builtin_amdgcn_mfma_f32_16x16x32_bf16(Bt[n][k], At[m][k], acc[ai][bj][m][n], 0, 0, 0); __builtin_amdgcn_s_setprio(0); } while (0)
; #define PG8_WAIT_V(n) asm volatile("s_waitcnt vmcnt(" #n ")" ::: "memory")
; #define PG8_WAIT_L(n) asm volatile("s_waitcnt lgkmcnt(" #n ")" ::: "memory")
; #define PG8_BAR __builtin_amdgcn_s_barrier()
; #define PG8_SCHED __builtin_amdgcn_sched_barrier(0)
; template <class Epi, class Sched, bool ALIGN_EPI = false, bool SP2 = false>
; __device__ __forceinline__ void gemm_phase(PG8_LAS unsigned char* lds, const Gemm g, const Sched& S, const Epi& E) {
;     ...
;             PG8_LDB(B0, 0, 0); PG8_LDB(B1, 0, 1); PG8_SCHED; PG8_LDA(At, 0, 0); PG8_STAGE(PG8_SA(1, 1), a1 + hstep, voffA);
;             PG8_WAIT_V(8); PG8_WAIT_L(0); PG8_BAR; PG8_MMA(0, 0, At, B0); PG8_MMA(0, 1, At, B1); PG8_BAR; PG8_SCHED;
;             PG8_LDA(At, 0, 1); PG8_STAGE(PG8_SB(0, 0), b2, voffB); PG8_STAGE(PG8_SB(0, 1), b2 + hstep, voffB); PG8_STAGE(PG8_SA(0, 0), a2, voffA);
;             PG8_WAIT_V(8); PG8_WAIT_L(0); PG8_BAR; PG8_MMA(1, 0, At, B0); PG8_MMA(1, 1, At, B1); PG8_BAR; PG8_SCHED;
.LBB0_763:
	ds_read_b128 v[154:157], v150
	ds_read_b128 v[158:161], v150 offset:1024
	ds_read_b128 v[162:165], v150 offset:2048
	ds_read_b128 v[166:169], v150 offset:3072
	ds_read_b128 v[170:173], v151
	ds_read_b128 v[174:177], v151 offset:1024
	ds_read_b128 v[178:181], v151 offset:2048
	ds_read_b128 v[182:185], v151 offset:3072
	s_add_u32 s4, s40, 0xfff80080
	s_addc_u32 s5, s41, -1
	s_cmp_eq_u32 s78, 28
	s_cselect_b32 s51, s31, s5
	s_cselect_b32 s50, s74, s4
	s_cselect_b32 s49, s29, s77
	s_cselect_b32 s48, s75, s76
	s_add_i32 m0, s39, 0xc000
	ds_read_b128 v[186:189], v152
	ds_read_b128 v[190:193], v152 offset:1024
	ds_read_b128 v[194:197], v152 offset:2048
	ds_read_b128 v[198:201], v152 offset:3072
	ds_read_b128 v[202:205], v152 offset:4096
	ds_read_b128 v[206:209], v152 offset:5120
	ds_read_b128 v[210:213], v152 offset:6144
	ds_read_b128 v[214:217], v152 offset:7168
	global_load_lds_dwordx4 v138, s[40:41]
	s_add_i32 m0, s39, 0xe000
	s_nop 0
	global_load_lds_dwordx4 v140, s[40:41]
	s_waitcnt vmcnt(8)
	s_waitcnt lgkmcnt(0)
	s_barrier
	s_setprio 1
	s_waitcnt lgkmcnt(0)
	v_mfma_f32_16x16x32_bf16 v[126:129], v[154:157], v[186:189], v[126:129]
	v_mfma_f32_16x16x32_bf16 v[122:125], v[162:165], v[186:189], v[122:125]
	v_mfma_f32_16x16x32_bf16 v[114:117], v[154:157], v[194:197], v[114:117]
	v_mfma_f32_16x16x32_bf16 v[106:109], v[162:165], v[194:197], v[106:109]
	v_mfma_f32_16x16x32_bf16 v[98:101], v[154:157], v[202:205], v[98:101]
	v_mfma_f32_16x16x32_bf16 v[90:93], v[162:165], v[202:205], v[90:93]
	v_mfma_f32_16x16x32_bf16 v[82:85], v[154:157], v[210:213], v[82:85]
	v_mfma_f32_16x16x32_bf16 v[74:77], v[162:165], v[210:213], v[74:77]
	v_mfma_f32_16x16x32_bf16 v[126:129], v[158:161], v[190:193], v[126:129]
	v_mfma_f32_16x16x32_bf16 v[122:125], v[166:169], v[190:193], v[122:125]
	v_mfma_f32_16x16x32_bf16 v[114:117], v[158:161], v[198:201], v[114:117]
	v_mfma_f32_16x16x32_bf16 v[106:109], v[166:169], v[198:201], v[106:109]
	v_mfma_f32_16x16x32_bf16 v[98:101], v[158:161], v[206:209], v[98:101]
	v_mfma_f32_16x16x32_bf16 v[90:93], v[166:169], v[206:209], v[90:93]
	v_mfma_f32_16x16x32_bf16 v[82:85], v[158:161], v[214:217], v[82:85]
	v_mfma_f32_16x16x32_bf16 v[74:77], v[166:169], v[214:217], v[74:77]
	s_setprio 0
	s_setprio 1
	v_mfma_f32_16x16x32_bf16 v[118:121], v[170:173], v[186:189], v[118:121]
	v_mfma_f32_16x16x32_bf16 v[110:113], v[178:181], v[186:189], v[110:113]
	v_mfma_f32_16x16x32_bf16 v[102:105], v[170:173], v[194:197], v[102:105]
	v_mfma_f32_16x16x32_bf16 v[94:97], v[178:181], v[194:197], v[94:97]
	v_mfma_f32_16x16x32_bf16 v[86:89], v[170:173], v[202:205], v[86:89]
	v_mfma_f32_16x16x32_bf16 v[78:81], v[178:181], v[202:205], v[78:81]
	v_mfma_f32_16x16x32_bf16 v[70:73], v[170:173], v[210:213], v[70:73]
	v_mfma_f32_16x16x32_bf16 v[66:69], v[178:181], v[210:213], v[66:69]
	v_mfma_f32_16x16x32_bf16 v[118:121], v[174:177], v[190:193], v[118:121]
	v_mfma_f32_16x16x32_bf16 v[110:113], v[182:185], v[190:193], v[110:113]
	v_mfma_f32_16x16x32_bf16 v[102:105], v[174:177], v[198:201], v[102:105]
	v_mfma_f32_16x16x32_bf16 v[94:97], v[182:185], v[198:201], v[94:97]
	v_mfma_f32_16x16x32_bf16 v[86:89], v[174:177], v[206:209], v[86:89]
	v_mfma_f32_16x16x32_bf16 v[78:81], v[182:185], v[206:209], v[78:81]
	v_mfma_f32_16x16x32_bf16 v[70:73], v[174:177], v[214:217], v[70:73]
	v_mfma_f32_16x16x32_bf16 v[66:69], v[182:185], v[214:217], v[66:69]
	s_setprio 0
	s_barrier
	s_add_i32 s4, s67, s58
	s_mov_b32 m0, s4
	ds_read_b128 v[186:189], v152 offset:16384
	ds_read_b128 v[190:193], v152 offset:17408
	ds_read_b128 v[194:197], v152 offset:18432
	ds_read_b128 v[198:201], v152 offset:19456
	ds_read_b128 v[202:205], v152 offset:20480
	ds_read_b128 v[206:209], v152 offset:21504
	ds_read_b128 v[210:213], v152 offset:22528
	ds_read_b128 v[214:217], v152 offset:23552
	global_load_lds_dwordx4 v132, s[48:49]
	s_add_i32 m0, s4, 0x2000
	s_add_u32 s4, s48, 0x80000
	s_addc_u32 s5, s49, 0
	s_add_i32 s79, s68, s58
	global_load_lds_dwordx4 v136, s[48:49]
	s_mov_b32 m0, s79
	s_nop 0
	global_load_lds_dwordx4 v132, s[4:5]
	s_add_i32 m0, s79, 0x2000
	s_nop 0
	global_load_lds_dwordx4 v136, s[4:5]
	s_waitcnt vmcnt(6)
	s_waitcnt lgkmcnt(0)
	s_barrier
	s_setprio 1
	s_waitcnt lgkmcnt(0)
	v_mfma_f32_16x16x32_bf16 v[62:65], v[154:157], v[186:189], v[62:65]
	v_mfma_f32_16x16x32_bf16 v[58:61], v[162:165], v[186:189], v[58:61]
	v_mfma_f32_16x16x32_bf16 v[50:53], v[154:157], v[194:197], v[50:53]
	v_mfma_f32_16x16x32_bf16 v[42:45], v[162:165], v[194:197], v[42:45]
	v_mfma_f32_16x16x32_bf16 v[34:37], v[154:157], v[202:205], v[34:37]
	v_mfma_f32_16x16x32_bf16 v[26:29], v[162:165], v[202:205], v[26:29]
	v_mfma_f32_16x16x32_bf16 v[18:21], v[154:157], v[210:213], v[18:21]
	v_mfma_f32_16x16x32_bf16 v[10:13], v[162:165], v[210:213], v[10:13]
	v_mfma_f32_16x16x32_bf16 v[62:65], v[158:161], v[190:193], v[62:65]
	v_mfma_f32_16x16x32_bf16 v[58:61], v[166:169], v[190:193], v[58:61]
	v_mfma_f32_16x16x32_bf16 v[50:53], v[158:161], v[198:201], v[50:53]
	v_mfma_f32_16x16x32_bf16 v[42:45], v[166:169], v[198:201], v[42:45]
	v_mfma_f32_16x16x32_bf16 v[34:37], v[158:161], v[206:209], v[34:37]
	v_mfma_f32_16x16x32_bf16 v[26:29], v[166:169], v[206:209], v[26:29]
	v_mfma_f32_16x16x32_bf16 v[18:21], v[158:161], v[214:217], v[18:21]
	v_mfma_f32_16x16x32_bf16 v[10:13], v[166:169], v[214:217], v[10:13]
	s_setprio 0
	s_setprio 1
	v_mfma_f32_16x16x32_bf16 v[54:57], v[170:173], v[186:189], v[54:57]
	v_mfma_f32_16x16x32_bf16 v[46:49], v[178:181], v[186:189], v[46:49]
	v_mfma_f32_16x16x32_bf16 v[38:41], v[170:173], v[194:197], v[38:41]
	v_mfma_f32_16x16x32_bf16 v[30:33], v[178:181], v[194:197], v[30:33]
	v_mfma_f32_16x16x32_bf16 v[22:25], v[170:173], v[202:205], v[22:25]
	v_mfma_f32_16x16x32_bf16 v[14:17], v[178:181], v[202:205], v[14:17]
	v_mfma_f32_16x16x32_bf16 v[6:9], v[170:173], v[210:213], v[6:9]
	v_mfma_f32_16x16x32_bf16 v[2:5], v[178:181], v[210:213], v[2:5]
	v_mfma_f32_16x16x32_bf16 v[54:57], v[174:177], v[190:193], v[54:57]
	v_mfma_f32_16x16x32_bf16 v[46:49], v[182:185], v[190:193], v[46:49]
	v_mfma_f32_16x16x32_bf16 v[38:41], v[174:177], v[198:201], v[38:41]
	v_mfma_f32_16x16x32_bf16 v[30:33], v[182:185], v[198:201], v[30:33]
	v_mfma_f32_16x16x32_bf16 v[22:25], v[174:177], v[206:209], v[22:25]
	v_mfma_f32_16x16x32_bf16 v[14:17], v[182:185], v[206:209], v[14:17]
	v_mfma_f32_16x16x32_bf16 v[6:9], v[174:177], v[214:217], v[6:9]
	v_mfma_f32_16x16x32_bf16 v[2:5], v[182:185], v[214:217], v[2:5]
	s_setprio 0
	s_barrier
; #define PG8_STAGE(bufoff, gbase, voff) do { _Pragma("unroll") for (int _i = 0; _i < 2; ++_i) \
;         __builtin_amdgcn_global_load_lds((const unsigned*)((const char*)(gbase) + (voff)[_i]), (PG8_LAS unsigned*)(lds + (bufoff) + ldsw + _i * 8192), 16, 0, 0); } while (0)
; #define PG8_LDA(dst, b, h) do { _Pragma("unroll") for (int m = 0; m < 4; ++m) _Pragma("unroll") for (int k = 0; k < 2; ++k) dst[m][k] = *(const PG8_LAS bf16x8*)(lds + PG8_SA(b, h) + aoff + m * 2048 + k * 1024); } while (0)
; #define PG8_LDB(dst, b, h) do { _Pragma("unroll") for (int n = 0; n < 2; ++n) _Pragma("unroll") for (int k = 0; k < 2; ++k) dst[n][k] = *(const PG8_LAS bf16x8*)(lds + PG8_SB(b, h) + boff + n * 2048 + k * 1024); } while (0)
; #define PG8_MMA(ai, bj, At, Bt) do { __builtin_amdgcn_s_setprio(1); _Pragma("unroll") for (int m = 0; m < 4; ++m) _Pragma("unroll") for (int n = 0; n < 2; ++n) _Pragma("unroll") for (int k = 0; k < 2; ++k) \
;         acc[ai][bj][m][n] = __builtin_amdgcn_mfma_f32_16x16x32_bf16(Bt[n][k], At[m][k], acc[ai][bj][m][n], 0, 0, 0); __builtin_amdgcn_s_setprio(0); } while (0)
; #define PG8_WAIT_V(n) asm volatile("s_waitcnt vmcnt(" #n ")" ::: "memory")
; #define PG8_WAIT_L(n) asm volatile("s_waitcnt lgkmcnt(" #n ")" ::: "memory")
; #define PG8_BAR __builtin_amdgcn_s_barrier()
; template <class Epi, class Sched, bool ALIGN_EPI = false, bool SP2 = false>
; __device__ __forceinline__ void gemm_phase(PG8_LAS unsigned char* lds, const Gemm g, const Sched& S, const Epi& E) {
;     ...
;         for (int t = 0; t < nt; t += 2) {
;             const bool last = (t == nt - 2);
;             const char* a1 = cA + (size_t)(t + 1) * kstep;
;             const char* a2 = last ? nA : cA + (size_t)(t + 2) * kstep; const char* b2 = last ? nB : cB + (size_t)(t + 2) * kstep;
;             const char* a3 = a2 + kstep; const char* b3 = b2 + kstep;
;     ...
;             PG8_LDB(B0, 1, 0); PG8_LDB(B1, 1, 1); PG8_SCHED; PG8_LDA(At, 1, 0); PG8_STAGE(PG8_SA(0, 1), a2 + hstep, voffA);
;             PG8_WAIT_V(8); PG8_WAIT_L(0); PG8_BAR; PG8_MMA(0, 0, At, B0); PG8_MMA(0, 1, At, B1); PG8_BAR; PG8_SCHED;
;             PG8_LDA(At, 1, 1); PG8_STAGE(PG8_SB(1, 0), b3, voffB); PG8_STAGE(PG8_SB(1, 1), b3 + hstep, voffB); PG8_STAGE(PG8_SA(1, 0), a3, voffA);
;             PG8_WAIT_V(8); PG8_WAIT_L(0); PG8_BAR; PG8_MMA(1, 0, At, B0); PG8_MMA(1, 1, At, B1); PG8_BAR; PG8_SCHED;
	s_add_i32 s79, 0, 0x18000
	v_add_u32_e32 v153, s79, v148
	s_add_i32 s80, 0, 0x1c000
	ds_read_b128 v[154:157], v153
	ds_read_b128 v[158:161], v153 offset:1024
	ds_read_b128 v[162:165], v153 offset:2048
	ds_read_b128 v[166:169], v153 offset:3072
	v_add_u32_e32 v153, s80, v148
	ds_read_b128 v[170:173], v153
	ds_read_b128 v[174:177], v153 offset:1024
	ds_read_b128 v[178:181], v153 offset:2048
	ds_read_b128 v[182:185], v153 offset:3072
	s_add_u32 s4, s50, 0x80000
	s_addc_u32 s5, s51, 0
	s_mov_b32 m0, s39
	s_nop 0
	global_load_lds_dwordx4 v130, s[50:51]
	s_mov_b32 m0, s59
	s_nop 0
	global_load_lds_dwordx4 v134, s[50:51]
	s_mov_b32 m0, s60
	ds_read_b128 v[186:189], v152 offset:32768
	ds_read_b128 v[190:193], v152 offset:33792
	ds_read_b128 v[194:197], v152 offset:34816
	ds_read_b128 v[198:201], v152 offset:35840
	ds_read_b128 v[202:205], v152 offset:36864
	ds_read_b128 v[206:209], v152 offset:37888
	ds_read_b128 v[210:213], v152 offset:38912
	ds_read_b128 v[214:217], v152 offset:39936
	global_load_lds_dwordx4 v130, s[4:5]
	s_mov_b32 m0, s61
	s_nop 0
	global_load_lds_dwordx4 v134, s[4:5]
	s_waitcnt vmcnt(8)
	s_waitcnt lgkmcnt(0)
	s_barrier
	s_setprio 1
	s_waitcnt lgkmcnt(0)
	v_mfma_f32_16x16x32_bf16 v[126:129], v[154:157], v[186:189], v[126:129]
	v_mfma_f32_16x16x32_bf16 v[122:125], v[162:165], v[186:189], v[122:125]
	v_mfma_f32_16x16x32_bf16 v[114:117], v[154:157], v[194:197], v[114:117]
	v_mfma_f32_16x16x32_bf16 v[106:109], v[162:165], v[194:197], v[106:109]
	v_mfma_f32_16x16x32_bf16 v[98:101], v[154:157], v[202:205], v[98:101]
	v_mfma_f32_16x16x32_bf16 v[90:93], v[162:165], v[202:205], v[90:93]
	v_mfma_f32_16x16x32_bf16 v[82:85], v[154:157], v[210:213], v[82:85]
	v_mfma_f32_16x16x32_bf16 v[74:77], v[162:165], v[210:213], v[74:77]
	v_mfma_f32_16x16x32_bf16 v[126:129], v[158:161], v[190:193], v[126:129]
	v_mfma_f32_16x16x32_bf16 v[122:125], v[166:169], v[190:193], v[122:125]
	v_mfma_f32_16x16x32_bf16 v[114:117], v[158:161], v[198:201], v[114:117]
	v_mfma_f32_16x16x32_bf16 v[106:109], v[166:169], v[198:201], v[106:109]
	v_mfma_f32_16x16x32_bf16 v[98:101], v[158:161], v[206:209], v[98:101]
	v_mfma_f32_16x16x32_bf16 v[90:93], v[166:169], v[206:209], v[90:93]
	v_mfma_f32_16x16x32_bf16 v[82:85], v[158:161], v[214:217], v[82:85]
	v_mfma_f32_16x16x32_bf16 v[74:77], v[166:169], v[214:217], v[74:77]
	s_setprio 0
	s_setprio 1
	v_mfma_f32_16x16x32_bf16 v[118:121], v[170:173], v[186:189], v[118:121]
	v_mfma_f32_16x16x32_bf16 v[110:113], v[178:181], v[186:189], v[110:113]
	v_mfma_f32_16x16x32_bf16 v[102:105], v[170:173], v[194:197], v[102:105]
	v_mfma_f32_16x16x32_bf16 v[94:97], v[178:181], v[194:197], v[94:97]
	v_mfma_f32_16x16x32_bf16 v[86:89], v[170:173], v[202:205], v[86:89]
	v_mfma_f32_16x16x32_bf16 v[78:81], v[178:181], v[202:205], v[78:81]
	v_mfma_f32_16x16x32_bf16 v[70:73], v[170:173], v[210:213], v[70:73]
	v_mfma_f32_16x16x32_bf16 v[66:69], v[178:181], v[210:213], v[66:69]
	v_mfma_f32_16x16x32_bf16 v[118:121], v[174:177], v[190:193], v[118:121]
	v_mfma_f32_16x16x32_bf16 v[110:113], v[182:185], v[190:193], v[110:113]
	v_mfma_f32_16x16x32_bf16 v[102:105], v[174:177], v[198:201], v[102:105]
	v_mfma_f32_16x16x32_bf16 v[94:97], v[182:185], v[198:201], v[94:97]
	v_mfma_f32_16x16x32_bf16 v[86:89], v[174:177], v[206:209], v[86:89]
	v_mfma_f32_16x16x32_bf16 v[78:81], v[182:185], v[206:209], v[78:81]
	v_mfma_f32_16x16x32_bf16 v[70:73], v[174:177], v[214:217], v[70:73]
	v_mfma_f32_16x16x32_bf16 v[66:69], v[182:185], v[214:217], v[66:69]
	s_setprio 0
	s_barrier
	s_add_i32 s4, s79, s58
	s_add_i32 m0, s4, 0xffffff80
	ds_read_b128 v[186:189], v152 offset:49152
	ds_read_b128 v[190:193], v152 offset:50176
	ds_read_b128 v[194:197], v152 offset:51200
	ds_read_b128 v[198:201], v152 offset:52224
	ds_read_b128 v[202:205], v152 offset:53248
	ds_read_b128 v[206:209], v152 offset:54272
	ds_read_b128 v[210:213], v152 offset:55296
	ds_read_b128 v[214:217], v152 offset:56320
	global_load_lds_dwordx4 v132, s[48:49] offset:128
	s_add_i32 m0, s4, 0x1f80
	s_add_u32 s4, s48, 0x80080
	s_addc_u32 s5, s49, 0
	global_load_lds_dwordx4 v136, s[48:49] offset:128
	s_add_i32 s48, s80, s58
	s_mov_b32 m0, s48
	s_nop 0
	global_load_lds_dwordx4 v132, s[4:5]
	s_add_i32 m0, s48, 0x2000
	s_nop 0
	global_load_lds_dwordx4 v136, s[4:5]
	s_add_i32 m0, s63, 0xffffff80
	s_nop 0
	global_load_lds_dwordx4 v130, s[50:51] offset:128
	s_add_i32 m0, s64, 0xffffff80
	s_nop 0
	global_load_lds_dwordx4 v134, s[50:51] offset:128
	s_waitcnt vmcnt(8)
	s_waitcnt lgkmcnt(0)
	s_barrier
	s_setprio 1
	s_waitcnt lgkmcnt(0)
	v_mfma_f32_16x16x32_bf16 v[62:65], v[154:157], v[186:189], v[62:65]
	v_mfma_f32_16x16x32_bf16 v[58:61], v[162:165], v[186:189], v[58:61]
	v_mfma_f32_16x16x32_bf16 v[50:53], v[154:157], v[194:197], v[50:53]
	v_mfma_f32_16x16x32_bf16 v[42:45], v[162:165], v[194:197], v[42:45]
	v_mfma_f32_16x16x32_bf16 v[34:37], v[154:157], v[202:205], v[34:37]
	v_mfma_f32_16x16x32_bf16 v[26:29], v[162:165], v[202:205], v[26:29]
	v_mfma_f32_16x16x32_bf16 v[18:21], v[154:157], v[210:213], v[18:21]
	v_mfma_f32_16x16x32_bf16 v[10:13], v[162:165], v[210:213], v[10:13]
	v_mfma_f32_16x16x32_bf16 v[62:65], v[158:161], v[190:193], v[62:65]
	v_mfma_f32_16x16x32_bf16 v[58:61], v[166:169], v[190:193], v[58:61]
	v_mfma_f32_16x16x32_bf16 v[50:53], v[158:161], v[198:201], v[50:53]
	v_mfma_f32_16x16x32_bf16 v[42:45], v[166:169], v[198:201], v[42:45]
	v_mfma_f32_16x16x32_bf16 v[34:37], v[158:161], v[206:209], v[34:37]
	v_mfma_f32_16x16x32_bf16 v[26:29], v[166:169], v[206:209], v[26:29]
	v_mfma_f32_16x16x32_bf16 v[18:21], v[158:161], v[214:217], v[18:21]
	v_mfma_f32_16x16x32_bf16 v[10:13], v[166:169], v[214:217], v[10:13]
	s_setprio 0
	s_setprio 1
	v_mfma_f32_16x16x32_bf16 v[54:57], v[170:173], v[186:189], v[54:57]
	v_mfma_f32_16x16x32_bf16 v[46:49], v[178:181], v[186:189], v[46:49]
	v_mfma_f32_16x16x32_bf16 v[38:41], v[170:173], v[194:197], v[38:41]
	v_mfma_f32_16x16x32_bf16 v[30:33], v[178:181], v[194:197], v[30:33]
	v_mfma_f32_16x16x32_bf16 v[22:25], v[170:173], v[202:205], v[22:25]
	v_mfma_f32_16x16x32_bf16 v[14:17], v[178:181], v[202:205], v[14:17]
	v_mfma_f32_16x16x32_bf16 v[6:9], v[170:173], v[210:213], v[6:9]
	v_mfma_f32_16x16x32_bf16 v[2:5], v[178:181], v[210:213], v[2:5]
	v_mfma_f32_16x16x32_bf16 v[54:57], v[174:177], v[190:193], v[54:57]
	v_mfma_f32_16x16x32_bf16 v[46:49], v[182:185], v[190:193], v[46:49]
	v_mfma_f32_16x16x32_bf16 v[38:41], v[174:177], v[198:201], v[38:41]
	v_mfma_f32_16x16x32_bf16 v[30:33], v[182:185], v[198:201], v[30:33]
	v_mfma_f32_16x16x32_bf16 v[22:25], v[174:177], v[206:209], v[22:25]
	v_mfma_f32_16x16x32_bf16 v[14:17], v[182:185], v[206:209], v[14:17]
	v_mfma_f32_16x16x32_bf16 v[6:9], v[174:177], v[214:217], v[6:9]
	v_mfma_f32_16x16x32_bf16 v[2:5], v[182:185], v[214:217], v[2:5]
	s_setprio 0
	s_add_i32 s78, s78, 2
	s_add_u32 s40, s40, 0x100
	s_addc_u32 s41, s41, 0
	s_add_u32 s76, s76, 0x100
	s_addc_u32 s77, s77, 0
	s_cmp_gt_u32 s78, 29
	s_barrier
	s_cbranch_scc0 .LBB0_763
	s_and_b64 vcc, exec, s[20:21]
	s_cbranch_vccz .LBB0_766
	s_barrier

; #define PG8_STAGE(bufoff, gbase, voff) do { _Pragma("unroll") for (int _i = 0; _i < 2; ++_i) \
;         __builtin_amdgcn_global_load_lds((const unsigned*)((const char*)(gbase) + (voff)[_i]), (PG8_LAS unsigned*)(lds + (bufoff) + ldsw + _i * 8192), 16, 0, 0); } while (0)
; #define PG8_LDA(dst, b, h) do { _Pragma("unroll") for (int m = 0; m < 4; ++m) _Pragma("unroll") for (int k = 0; k < 2; ++k) dst[m][k] = *(const PG8_LAS bf16x8*)(lds + PG8_SA(b, h) + aoff + m * 2048 + k * 1024); } while (0)
; #define PG8_LDB(dst, b, h) do { _Pragma("unroll") for (int n = 0; n < 2; ++n) _Pragma("unroll") for (int k = 0; k < 2; ++k) dst[n][k] = *(const PG8_LAS bf16x8*)(lds + PG8_SB(b, h) + boff + n * 2048 + k * 1024); } while (0)
; #define PG8_MMA(ai, bj, At, Bt) do { __builtin_amdgcn_s_setprio(1); _Pragma("unroll") for (int m = 0; m < 4; ++m) _Pragma("unroll") for (int n = 0; n < 2; ++n) _Pragma("unroll") for (int k = 0; k < 2; ++k) \
;         acc[ai][bj][m][n] = __builtin_amdgcn_mfma_f32_16x16x32_bf16(Bt[n][k], At[m][k], acc[ai][bj][m][n], 0, 0, 0); __builtin_amdgcn_s_setprio(0); } while (0)
; #define PG8_WAIT_V(n) asm volatile("s_waitcnt vmcnt(" #n ")" ::: "memory")
; #define PG8_WAIT_L(n) asm volatile("s_waitcnt lgkmcnt(" #n ")" ::: "memory")
; #define PG8_BAR __builtin_amdgcn_s_barrier()
; #define PG8_SCHED __builtin_amdgcn_sched_barrier(0)
; template <class Epi, class Sched, bool ALIGN_EPI = false, bool SP2 = false>
; __device__ __forceinline__ void gemm_phase(PG8_LAS unsigned char* lds, const Gemm g, const Sched& S, const Epi& E) {
;     ...
;             PG8_LDB(B0, 0, 0); PG8_LDB(B1, 0, 1); PG8_SCHED; PG8_LDA(At, 0, 0); PG8_STAGE(PG8_SA(1, 1), a1 + hstep, voffA);
;             PG8_WAIT_V(8); PG8_WAIT_L(0); PG8_BAR; PG8_MMA(0, 0, At, B0); PG8_MMA(0, 1, At, B1); PG8_BAR; PG8_SCHED;
;             PG8_LDA(At, 0, 1); PG8_STAGE(PG8_SB(0, 0), b2, voffB); PG8_STAGE(PG8_SB(0, 1), b2 + hstep, voffB); PG8_STAGE(PG8_SA(0, 0), a2, voffA);
;             PG8_WAIT_V(8); PG8_WAIT_L(0); PG8_BAR; PG8_MMA(1, 0, At, B0); PG8_MMA(1, 1, At, B1); PG8_BAR; PG8_SCHED;
.LBB0_913:
	ds_read_b128 v[156:159], v152
	ds_read_b128 v[160:163], v152 offset:1024
	ds_read_b128 v[164:167], v152 offset:2048
	ds_read_b128 v[168:171], v152 offset:3072
	ds_read_b128 v[172:175], v153
	ds_read_b128 v[176:179], v153 offset:1024
	ds_read_b128 v[180:183], v153 offset:2048
	ds_read_b128 v[184:187], v153 offset:3072
	s_add_u32 s4, s34, 0xfff80080
	s_addc_u32 s5, s35, -1
	s_cmp_eq_u32 s69, 28
	s_cselect_b32 s39, s25, s5
	s_cselect_b32 s38, s65, s4
	s_cselect_b32 s37, s23, s68
	s_cselect_b32 s36, s66, s67
	s_add_i32 m0, s31, 0xc000
	ds_read_b128 v[188:191], v154
	ds_read_b128 v[192:195], v154 offset:1024
	ds_read_b128 v[196:199], v154 offset:2048
	ds_read_b128 v[200:203], v154 offset:3072
	ds_read_b128 v[204:207], v154 offset:4096
	ds_read_b128 v[208:211], v154 offset:5120
	ds_read_b128 v[212:215], v154 offset:6144
	ds_read_b128 v[216:219], v154 offset:7168
	global_load_lds_dwordx4 v138, s[34:35]
	s_add_i32 m0, s31, 0xe000
	s_nop 0
	global_load_lds_dwordx4 v140, s[34:35]
	s_waitcnt vmcnt(8)
	s_waitcnt lgkmcnt(0)
	s_barrier
	s_setprio 1
	s_waitcnt lgkmcnt(0)
	v_mfma_f32_16x16x32_bf16 v[126:129], v[156:159], v[188:191], v[126:129]
	v_mfma_f32_16x16x32_bf16 v[122:125], v[164:167], v[188:191], v[122:125]
	v_mfma_f32_16x16x32_bf16 v[110:113], v[156:159], v[196:199], v[110:113]
	v_mfma_f32_16x16x32_bf16 v[106:109], v[164:167], v[196:199], v[106:109]
	v_mfma_f32_16x16x32_bf16 v[94:97], v[156:159], v[204:207], v[94:97]
	v_mfma_f32_16x16x32_bf16 v[90:93], v[164:167], v[204:207], v[90:93]
	v_mfma_f32_16x16x32_bf16 v[78:81], v[156:159], v[212:215], v[78:81]
	v_mfma_f32_16x16x32_bf16 v[74:77], v[164:167], v[212:215], v[74:77]
	v_mfma_f32_16x16x32_bf16 v[126:129], v[160:163], v[192:195], v[126:129]
	v_mfma_f32_16x16x32_bf16 v[122:125], v[168:171], v[192:195], v[122:125]
	v_mfma_f32_16x16x32_bf16 v[110:113], v[160:163], v[200:203], v[110:113]
	v_mfma_f32_16x16x32_bf16 v[106:109], v[168:171], v[200:203], v[106:109]
	v_mfma_f32_16x16x32_bf16 v[94:97], v[160:163], v[208:211], v[94:97]
	v_mfma_f32_16x16x32_bf16 v[90:93], v[168:171], v[208:211], v[90:93]
	v_mfma_f32_16x16x32_bf16 v[78:81], v[160:163], v[216:219], v[78:81]
	v_mfma_f32_16x16x32_bf16 v[74:77], v[168:171], v[216:219], v[74:77]
	s_setprio 0
	s_setprio 1
	v_mfma_f32_16x16x32_bf16 v[118:121], v[172:175], v[188:191], v[118:121]
	v_mfma_f32_16x16x32_bf16 v[114:117], v[180:183], v[188:191], v[114:117]
	v_mfma_f32_16x16x32_bf16 v[102:105], v[172:175], v[196:199], v[102:105]
	v_mfma_f32_16x16x32_bf16 v[98:101], v[180:183], v[196:199], v[98:101]
	v_mfma_f32_16x16x32_bf16 v[86:89], v[172:175], v[204:207], v[86:89]
	v_mfma_f32_16x16x32_bf16 v[82:85], v[180:183], v[204:207], v[82:85]
	v_mfma_f32_16x16x32_bf16 v[70:73], v[172:175], v[212:215], v[70:73]
	v_mfma_f32_16x16x32_bf16 v[66:69], v[180:183], v[212:215], v[66:69]
	v_mfma_f32_16x16x32_bf16 v[118:121], v[176:179], v[192:195], v[118:121]
	v_mfma_f32_16x16x32_bf16 v[114:117], v[184:187], v[192:195], v[114:117]
	v_mfma_f32_16x16x32_bf16 v[102:105], v[176:179], v[200:203], v[102:105]
	v_mfma_f32_16x16x32_bf16 v[98:101], v[184:187], v[200:203], v[98:101]
	v_mfma_f32_16x16x32_bf16 v[86:89], v[176:179], v[208:211], v[86:89]
	v_mfma_f32_16x16x32_bf16 v[82:85], v[184:187], v[208:211], v[82:85]
	v_mfma_f32_16x16x32_bf16 v[70:73], v[176:179], v[216:219], v[70:73]
	v_mfma_f32_16x16x32_bf16 v[66:69], v[184:187], v[216:219], v[66:69]
	s_setprio 0
	s_barrier
	s_add_i32 s4, s61, s40
	s_mov_b32 m0, s4
	ds_read_b128 v[188:191], v154 offset:16384
	ds_read_b128 v[192:195], v154 offset:17408
	ds_read_b128 v[196:199], v154 offset:18432
	ds_read_b128 v[200:203], v154 offset:19456
	ds_read_b128 v[204:207], v154 offset:20480
	ds_read_b128 v[208:211], v154 offset:21504
	ds_read_b128 v[212:215], v154 offset:22528
	ds_read_b128 v[216:219], v154 offset:23552
	global_load_lds_dwordx4 v134, s[36:37]
	s_add_i32 m0, s4, 0x2000
	s_add_u32 s4, s36, 0x80000
	s_addc_u32 s5, s37, 0
	s_add_i32 s70, s62, s40
	global_load_lds_dwordx4 v130, s[36:37]
	s_mov_b32 m0, s70
	s_nop 0
	global_load_lds_dwordx4 v134, s[4:5]
	s_add_i32 m0, s70, 0x2000
	s_nop 0
	global_load_lds_dwordx4 v130, s[4:5]
	s_waitcnt vmcnt(6)
	s_waitcnt lgkmcnt(0)
	s_barrier
	s_setprio 1
	s_waitcnt lgkmcnt(0)
	v_mfma_f32_16x16x32_bf16 v[62:65], v[156:159], v[188:191], v[62:65]
	v_mfma_f32_16x16x32_bf16 v[58:61], v[164:167], v[188:191], v[58:61]
	v_mfma_f32_16x16x32_bf16 v[46:49], v[156:159], v[196:199], v[46:49]
	v_mfma_f32_16x16x32_bf16 v[42:45], v[164:167], v[196:199], v[42:45]
	v_mfma_f32_16x16x32_bf16 v[30:33], v[156:159], v[204:207], v[30:33]
	v_mfma_f32_16x16x32_bf16 v[26:29], v[164:167], v[204:207], v[26:29]
	v_mfma_f32_16x16x32_bf16 v[14:17], v[156:159], v[212:215], v[14:17]
	v_mfma_f32_16x16x32_bf16 v[10:13], v[164:167], v[212:215], v[10:13]
	v_mfma_f32_16x16x32_bf16 v[62:65], v[160:163], v[192:195], v[62:65]
	v_mfma_f32_16x16x32_bf16 v[58:61], v[168:171], v[192:195], v[58:61]
	v_mfma_f32_16x16x32_bf16 v[46:49], v[160:163], v[200:203], v[46:49]
	v_mfma_f32_16x16x32_bf16 v[42:45], v[168:171], v[200:203], v[42:45]
	v_mfma_f32_16x16x32_bf16 v[30:33], v[160:163], v[208:211], v[30:33]
	v_mfma_f32_16x16x32_bf16 v[26:29], v[168:171], v[208:211], v[26:29]
	v_mfma_f32_16x16x32_bf16 v[14:17], v[160:163], v[216:219], v[14:17]
	v_mfma_f32_16x16x32_bf16 v[10:13], v[168:171], v[216:219], v[10:13]
	s_setprio 0
	s_setprio 1
	v_mfma_f32_16x16x32_bf16 v[54:57], v[172:175], v[188:191], v[54:57]
	v_mfma_f32_16x16x32_bf16 v[50:53], v[180:183], v[188:191], v[50:53]
	v_mfma_f32_16x16x32_bf16 v[38:41], v[172:175], v[196:199], v[38:41]
	v_mfma_f32_16x16x32_bf16 v[34:37], v[180:183], v[196:199], v[34:37]
	v_mfma_f32_16x16x32_bf16 v[22:25], v[172:175], v[204:207], v[22:25]
	v_mfma_f32_16x16x32_bf16 v[18:21], v[180:183], v[204:207], v[18:21]
	v_mfma_f32_16x16x32_bf16 v[6:9], v[172:175], v[212:215], v[6:9]
	v_mfma_f32_16x16x32_bf16 v[2:5], v[180:183], v[212:215], v[2:5]
	v_mfma_f32_16x16x32_bf16 v[54:57], v[176:179], v[192:195], v[54:57]
	v_mfma_f32_16x16x32_bf16 v[50:53], v[184:187], v[192:195], v[50:53]
	v_mfma_f32_16x16x32_bf16 v[38:41], v[176:179], v[200:203], v[38:41]
	v_mfma_f32_16x16x32_bf16 v[34:37], v[184:187], v[200:203], v[34:37]
	v_mfma_f32_16x16x32_bf16 v[22:25], v[176:179], v[208:211], v[22:25]
	v_mfma_f32_16x16x32_bf16 v[18:21], v[184:187], v[208:211], v[18:21]
	v_mfma_f32_16x16x32_bf16 v[6:9], v[176:179], v[216:219], v[6:9]
	v_mfma_f32_16x16x32_bf16 v[2:5], v[184:187], v[216:219], v[2:5]
	s_setprio 0
	s_barrier
; #define PG8_STAGE(bufoff, gbase, voff) do { _Pragma("unroll") for (int _i = 0; _i < 2; ++_i) \
;         __builtin_amdgcn_global_load_lds((const unsigned*)((const char*)(gbase) + (voff)[_i]), (PG8_LAS unsigned*)(lds + (bufoff) + ldsw + _i * 8192), 16, 0, 0); } while (0)
; #define PG8_LDA(dst, b, h) do { _Pragma("unroll") for (int m = 0; m < 4; ++m) _Pragma("unroll") for (int k = 0; k < 2; ++k) dst[m][k] = *(const PG8_LAS bf16x8*)(lds + PG8_SA(b, h) + aoff + m * 2048 + k * 1024); } while (0)
; #define PG8_LDB(dst, b, h) do { _Pragma("unroll") for (int n = 0; n < 2; ++n) _Pragma("unroll") for (int k = 0; k < 2; ++k) dst[n][k] = *(const PG8_LAS bf16x8*)(lds + PG8_SB(b, h) + boff + n * 2048 + k * 1024); } while (0)
; #define PG8_MMA(ai, bj, At, Bt) do { __builtin_amdgcn_s_setprio(1); _Pragma("unroll") for (int m = 0; m < 4; ++m) _Pragma("unroll") for (int n = 0; n < 2; ++n) _Pragma("unroll") for (int k = 0; k < 2; ++k) \
;         acc[ai][bj][m][n] = __builtin_amdgcn_mfma_f32_16x16x32_bf16(Bt[n][k], At[m][k], acc[ai][bj][m][n], 0, 0, 0); __builtin_amdgcn_s_setprio(0); } while (0)
; #define PG8_WAIT_V(n) asm volatile("s_waitcnt vmcnt(" #n ")" ::: "memory")
; #define PG8_WAIT_L(n) asm volatile("s_waitcnt lgkmcnt(" #n ")" ::: "memory")
; #define PG8_BAR __builtin_amdgcn_s_barrier()
; template <class Epi, class Sched, bool ALIGN_EPI = false, bool SP2 = false>
; __device__ __forceinline__ void gemm_phase(PG8_LAS unsigned char* lds, const Gemm g, const Sched& S, const Epi& E) {
;     ...
;         for (int t = 0; t < nt; t += 2) {
;             const bool last = (t == nt - 2);
;             const char* a1 = cA + (size_t)(t + 1) * kstep;
;             const char* a2 = last ? nA : cA + (size_t)(t + 2) * kstep; const char* b2 = last ? nB : cB + (size_t)(t + 2) * kstep;
;             const char* a3 = a2 + kstep; const char* b3 = b2 + kstep;
;     ...
;             PG8_LDB(B0, 1, 0); PG8_LDB(B1, 1, 1); PG8_SCHED; PG8_LDA(At, 1, 0); PG8_STAGE(PG8_SA(0, 1), a2 + hstep, voffA);
;             PG8_WAIT_V(8); PG8_WAIT_L(0); PG8_BAR; PG8_MMA(0, 0, At, B0); PG8_MMA(0, 1, At, B1); PG8_BAR; PG8_SCHED;
;             PG8_LDA(At, 1, 1); PG8_STAGE(PG8_SB(1, 0), b3, voffB); PG8_STAGE(PG8_SB(1, 1), b3 + hstep, voffB); PG8_STAGE(PG8_SA(1, 0), a3, voffA);
;             PG8_WAIT_V(8); PG8_WAIT_L(0); PG8_BAR; PG8_MMA(1, 0, At, B0); PG8_MMA(1, 1, At, B1); PG8_BAR; PG8_SCHED;
	s_add_i32 s70, 0, 0x18000
	v_add_u32_e32 v155, s70, v150
	s_add_i32 s71, 0, 0x1c000
	ds_read_b128 v[156:159], v155
	ds_read_b128 v[160:163], v155 offset:1024
	ds_read_b128 v[164:167], v155 offset:2048
	ds_read_b128 v[168:171], v155 offset:3072
	v_add_u32_e32 v155, s71, v150
	ds_read_b128 v[172:175], v155
	ds_read_b128 v[176:179], v155 offset:1024
	ds_read_b128 v[180:183], v155 offset:2048
	ds_read_b128 v[184:187], v155 offset:3072
	s_add_u32 s4, s38, 0x80000
	s_addc_u32 s5, s39, 0
	s_mov_b32 m0, s31
	s_nop 0
	global_load_lds_dwordx4 v136, s[38:39]
	s_mov_b32 m0, s49
	s_nop 0
	global_load_lds_dwordx4 v132, s[38:39]
	s_mov_b32 m0, s50
	ds_read_b128 v[188:191], v154 offset:32768
	ds_read_b128 v[192:195], v154 offset:33792
	ds_read_b128 v[196:199], v154 offset:34816
	ds_read_b128 v[200:203], v154 offset:35840
	ds_read_b128 v[204:207], v154 offset:36864
	ds_read_b128 v[208:211], v154 offset:37888
	ds_read_b128 v[212:215], v154 offset:38912
	ds_read_b128 v[216:219], v154 offset:39936
	global_load_lds_dwordx4 v136, s[4:5]
	s_mov_b32 m0, s51
	s_nop 0
	global_load_lds_dwordx4 v132, s[4:5]
	s_waitcnt vmcnt(8)
	s_waitcnt lgkmcnt(0)
	s_barrier
	s_setprio 1
	s_waitcnt lgkmcnt(0)
	v_mfma_f32_16x16x32_bf16 v[126:129], v[156:159], v[188:191], v[126:129]
	v_mfma_f32_16x16x32_bf16 v[122:125], v[164:167], v[188:191], v[122:125]
	v_mfma_f32_16x16x32_bf16 v[110:113], v[156:159], v[196:199], v[110:113]
	v_mfma_f32_16x16x32_bf16 v[106:109], v[164:167], v[196:199], v[106:109]
	v_mfma_f32_16x16x32_bf16 v[94:97], v[156:159], v[204:207], v[94:97]
	v_mfma_f32_16x16x32_bf16 v[90:93], v[164:167], v[204:207], v[90:93]
	v_mfma_f32_16x16x32_bf16 v[78:81], v[156:159], v[212:215], v[78:81]
	v_mfma_f32_16x16x32_bf16 v[74:77], v[164:167], v[212:215], v[74:77]
	v_mfma_f32_16x16x32_bf16 v[126:129], v[160:163], v[192:195], v[126:129]
	v_mfma_f32_16x16x32_bf16 v[122:125], v[168:171], v[192:195], v[122:125]
	v_mfma_f32_16x16x32_bf16 v[110:113], v[160:163], v[200:203], v[110:113]
	v_mfma_f32_16x16x32_bf16 v[106:109], v[168:171], v[200:203], v[106:109]
	v_mfma_f32_16x16x32_bf16 v[94:97], v[160:163], v[208:211], v[94:97]
	v_mfma_f32_16x16x32_bf16 v[90:93], v[168:171], v[208:211], v[90:93]
	v_mfma_f32_16x16x32_bf16 v[78:81], v[160:163], v[216:219], v[78:81]
	v_mfma_f32_16x16x32_bf16 v[74:77], v[168:171], v[216:219], v[74:77]
	s_setprio 0
	s_setprio 1
	v_mfma_f32_16x16x32_bf16 v[118:121], v[172:175], v[188:191], v[118:121]
	v_mfma_f32_16x16x32_bf16 v[114:117], v[180:183], v[188:191], v[114:117]
	v_mfma_f32_16x16x32_bf16 v[102:105], v[172:175], v[196:199], v[102:105]
	v_mfma_f32_16x16x32_bf16 v[98:101], v[180:183], v[196:199], v[98:101]
	v_mfma_f32_16x16x32_bf16 v[86:89], v[172:175], v[204:207], v[86:89]
	v_mfma_f32_16x16x32_bf16 v[82:85], v[180:183], v[204:207], v[82:85]
	v_mfma_f32_16x16x32_bf16 v[70:73], v[172:175], v[212:215], v[70:73]
	v_mfma_f32_16x16x32_bf16 v[66:69], v[180:183], v[212:215], v[66:69]
	v_mfma_f32_16x16x32_bf16 v[118:121], v[176:179], v[192:195], v[118:121]
	v_mfma_f32_16x16x32_bf16 v[114:117], v[184:187], v[192:195], v[114:117]
	v_mfma_f32_16x16x32_bf16 v[102:105], v[176:179], v[200:203], v[102:105]
	v_mfma_f32_16x16x32_bf16 v[98:101], v[184:187], v[200:203], v[98:101]
	v_mfma_f32_16x16x32_bf16 v[86:89], v[176:179], v[208:211], v[86:89]
	v_mfma_f32_16x16x32_bf16 v[82:85], v[184:187], v[208:211], v[82:85]
	v_mfma_f32_16x16x32_bf16 v[70:73], v[176:179], v[216:219], v[70:73]
	v_mfma_f32_16x16x32_bf16 v[66:69], v[184:187], v[216:219], v[66:69]
	s_setprio 0
	s_barrier
	s_add_i32 s4, s70, s40
	s_add_i32 m0, s4, 0xffffff80
	ds_read_b128 v[188:191], v154 offset:49152
	ds_read_b128 v[192:195], v154 offset:50176
	ds_read_b128 v[196:199], v154 offset:51200
	ds_read_b128 v[200:203], v154 offset:52224
	ds_read_b128 v[204:207], v154 offset:53248
	ds_read_b128 v[208:211], v154 offset:54272
	ds_read_b128 v[212:215], v154 offset:55296
	ds_read_b128 v[216:219], v154 offset:56320
	global_load_lds_dwordx4 v134, s[36:37] offset:128
	s_add_i32 m0, s4, 0x1f80
	s_add_u32 s4, s36, 0x80080
	s_addc_u32 s5, s37, 0
	global_load_lds_dwordx4 v130, s[36:37] offset:128
	s_add_i32 s36, s71, s40
	s_mov_b32 m0, s36
	s_nop 0
	global_load_lds_dwordx4 v134, s[4:5]
	s_add_i32 m0, s36, 0x2000
	s_nop 0
	global_load_lds_dwordx4 v130, s[4:5]
	s_add_i32 m0, s53, 0xffffff80
	s_nop 0
	global_load_lds_dwordx4 v136, s[38:39] offset:128
	s_add_i32 m0, s58, 0xffffff80
	s_nop 0
	global_load_lds_dwordx4 v132, s[38:39] offset:128
	s_waitcnt vmcnt(8)
	s_waitcnt lgkmcnt(0)
	s_barrier
	s_setprio 1
	s_waitcnt lgkmcnt(0)
	v_mfma_f32_16x16x32_bf16 v[62:65], v[156:159], v[188:191], v[62:65]
	v_mfma_f32_16x16x32_bf16 v[58:61], v[164:167], v[188:191], v[58:61]
	v_mfma_f32_16x16x32_bf16 v[46:49], v[156:159], v[196:199], v[46:49]
	v_mfma_f32_16x16x32_bf16 v[42:45], v[164:167], v[196:199], v[42:45]
	v_mfma_f32_16x16x32_bf16 v[30:33], v[156:159], v[204:207], v[30:33]
	v_mfma_f32_16x16x32_bf16 v[26:29], v[164:167], v[204:207], v[26:29]
	v_mfma_f32_16x16x32_bf16 v[14:17], v[156:159], v[212:215], v[14:17]
	v_mfma_f32_16x16x32_bf16 v[10:13], v[164:167], v[212:215], v[10:13]
	v_mfma_f32_16x16x32_bf16 v[62:65], v[160:163], v[192:195], v[62:65]
	v_mfma_f32_16x16x32_bf16 v[58:61], v[168:171], v[192:195], v[58:61]
	v_mfma_f32_16x16x32_bf16 v[46:49], v[160:163], v[200:203], v[46:49]
	v_mfma_f32_16x16x32_bf16 v[42:45], v[168:171], v[200:203], v[42:45]
	v_mfma_f32_16x16x32_bf16 v[30:33], v[160:163], v[208:211], v[30:33]
	v_mfma_f32_16x16x32_bf16 v[26:29], v[168:171], v[208:211], v[26:29]
	v_mfma_f32_16x16x32_bf16 v[14:17], v[160:163], v[216:219], v[14:17]
	v_mfma_f32_16x16x32_bf16 v[10:13], v[168:171], v[216:219], v[10:13]
	s_setprio 0
	s_setprio 1
	v_mfma_f32_16x16x32_bf16 v[54:57], v[172:175], v[188:191], v[54:57]
	v_mfma_f32_16x16x32_bf16 v[50:53], v[180:183], v[188:191], v[50:53]
	v_mfma_f32_16x16x32_bf16 v[38:41], v[172:175], v[196:199], v[38:41]
	v_mfma_f32_16x16x32_bf16 v[34:37], v[180:183], v[196:199], v[34:37]
	v_mfma_f32_16x16x32_bf16 v[22:25], v[172:175], v[204:207], v[22:25]
	v_mfma_f32_16x16x32_bf16 v[18:21], v[180:183], v[204:207], v[18:21]
	v_mfma_f32_16x16x32_bf16 v[6:9], v[172:175], v[212:215], v[6:9]
	v_mfma_f32_16x16x32_bf16 v[2:5], v[180:183], v[212:215], v[2:5]
	v_mfma_f32_16x16x32_bf16 v[54:57], v[176:179], v[192:195], v[54:57]
	v_mfma_f32_16x16x32_bf16 v[50:53], v[184:187], v[192:195], v[50:53]
	v_mfma_f32_16x16x32_bf16 v[38:41], v[176:179], v[200:203], v[38:41]
	v_mfma_f32_16x16x32_bf16 v[34:37], v[184:187], v[200:203], v[34:37]
	v_mfma_f32_16x16x32_bf16 v[22:25], v[176:179], v[208:211], v[22:25]
	v_mfma_f32_16x16x32_bf16 v[18:21], v[184:187], v[208:211], v[18:21]
	v_mfma_f32_16x16x32_bf16 v[6:9], v[176:179], v[216:219], v[6:9]
	v_mfma_f32_16x16x32_bf16 v[2:5], v[184:187], v[216:219], v[2:5]
	s_setprio 0
	s_add_i32 s69, s69, 2
	s_add_u32 s34, s34, 0x100
	s_addc_u32 s35, s35, 0
	s_add_u32 s67, s67, 0x100
	s_addc_u32 s68, s68, 0
	s_cmp_gt_u32 s69, 29
	s_barrier
	s_cbranch_scc0 .LBB0_913
	s_and_b64 vcc, exec, s[20:21]
	s_cbranch_vccz .LBB0_916
	s_barrier

; #define PG8_STAGE(bufoff, gbase, voff) do { _Pragma("unroll") for (int _i = 0; _i < 2; ++_i) \
;         __builtin_amdgcn_global_load_lds((const unsigned*)((const char*)(gbase) + (voff)[_i]), (PG8_LAS unsigned*)(lds + (bufoff) + ldsw + _i * 8192), 16, 0, 0); } while (0)
; #define PG8_LDA(dst, b, h) do { _Pragma("unroll") for (int m = 0; m < 4; ++m) _Pragma("unroll") for (int k = 0; k < 2; ++k) dst[m][k] = *(const PG8_LAS bf16x8*)(lds + PG8_SA(b, h) + aoff + m * 2048 + k * 1024); } while (0)
; #define PG8_LDB(dst, b, h) do { _Pragma("unroll") for (int n = 0; n < 2; ++n) _Pragma("unroll") for (int k = 0; k < 2; ++k) dst[n][k] = *(const PG8_LAS bf16x8*)(lds + PG8_SB(b, h) + boff + n * 2048 + k * 1024); } while (0)
; #define PG8_MMA(ai, bj, At, Bt) do { __builtin_amdgcn_s_setprio(1); _Pragma("unroll") for (int m = 0; m < 4; ++m) _Pragma("unroll") for (int n = 0; n < 2; ++n) _Pragma("unroll") for (int k = 0; k < 2; ++k) \
;         acc[ai][bj][m][n] = __builtin_amdgcn_mfma_f32_16x16x32_bf16(Bt[n][k], At[m][k], acc[ai][bj][m][n], 0, 0, 0); __builtin_amdgcn_s_setprio(0); } while (0)
; #define PG8_WAIT_V(n) asm volatile("s_waitcnt vmcnt(" #n ")" ::: "memory")
; #define PG8_WAIT_L(n) asm volatile("s_waitcnt lgkmcnt(" #n ")" ::: "memory")
; #define PG8_BAR __builtin_amdgcn_s_barrier()
; #define PG8_SCHED __builtin_amdgcn_sched_barrier(0)
; template <class Epi, class Sched, bool ALIGN_EPI = false, bool SP2 = false>
; __device__ __forceinline__ void gemm_phase(PG8_LAS unsigned char* lds, const Gemm g, const Sched& S, const Epi& E) {
;     ...
;             PG8_LDB(B0, 0, 0); PG8_LDB(B1, 0, 1); PG8_SCHED; PG8_LDA(At, 0, 0); PG8_STAGE(PG8_SA(1, 1), a1 + hstep, voffA);
;             PG8_WAIT_V(8); PG8_WAIT_L(0); PG8_BAR; PG8_MMA(0, 0, At, B0); PG8_MMA(0, 1, At, B1); PG8_BAR; PG8_SCHED;
;             PG8_LDA(At, 0, 1); PG8_STAGE(PG8_SB(0, 0), b2, voffB); PG8_STAGE(PG8_SB(0, 1), b2 + hstep, voffB); PG8_STAGE(PG8_SA(0, 0), a2, voffA);
;             PG8_WAIT_V(8); PG8_WAIT_L(0); PG8_BAR; PG8_MMA(1, 0, At, B0); PG8_MMA(1, 1, At, B1); PG8_BAR; PG8_SCHED;
.LBB0_1017:
	ds_read_b128 v[154:157], v150
	ds_read_b128 v[158:161], v150 offset:1024
	ds_read_b128 v[162:165], v150 offset:2048
	ds_read_b128 v[166:169], v150 offset:3072
	ds_read_b128 v[170:173], v151
	ds_read_b128 v[174:177], v151 offset:1024
	ds_read_b128 v[178:181], v151 offset:2048
	ds_read_b128 v[182:185], v151 offset:3072
	s_add_u32 s34, s30, 0x100
	s_addc_u32 s35, s31, 0
	s_cmpk_eq_i32 s74, 0x54
	s_cselect_b32 s39, s9, s35
	s_cselect_b32 s38, s8, s34
	s_cselect_b32 s37, s29, s73
	s_cselect_b32 s36, s28, s72
	s_add_i32 m0, s49, 0xc000
	ds_read_b128 v[186:189], v152
	ds_read_b128 v[190:193], v152 offset:1024
	ds_read_b128 v[194:197], v152 offset:2048
	ds_read_b128 v[198:201], v152 offset:3072
	ds_read_b128 v[202:205], v152 offset:4096
	ds_read_b128 v[206:209], v152 offset:5120
	ds_read_b128 v[210:213], v152 offset:6144
	ds_read_b128 v[214:217], v152 offset:7168
	global_load_lds_dwordx4 v138, s[30:31]
	s_add_i32 m0, s49, 0xe000
	s_nop 0
	global_load_lds_dwordx4 v140, s[30:31]
	s_waitcnt vmcnt(8)
	s_waitcnt lgkmcnt(0)
	s_barrier
	s_setprio 1
	s_waitcnt lgkmcnt(0)
	v_mfma_f32_16x16x32_bf16 v[126:129], v[154:157], v[186:189], v[126:129]
	v_mfma_f32_16x16x32_bf16 v[122:125], v[162:165], v[186:189], v[122:125]
	v_mfma_f32_16x16x32_bf16 v[114:117], v[154:157], v[194:197], v[114:117]
	v_mfma_f32_16x16x32_bf16 v[106:109], v[162:165], v[194:197], v[106:109]
	v_mfma_f32_16x16x32_bf16 v[98:101], v[154:157], v[202:205], v[98:101]
	v_mfma_f32_16x16x32_bf16 v[90:93], v[162:165], v[202:205], v[90:93]
	v_mfma_f32_16x16x32_bf16 v[82:85], v[154:157], v[210:213], v[82:85]
	v_mfma_f32_16x16x32_bf16 v[74:77], v[162:165], v[210:213], v[74:77]
	v_mfma_f32_16x16x32_bf16 v[126:129], v[158:161], v[190:193], v[126:129]
	v_mfma_f32_16x16x32_bf16 v[122:125], v[166:169], v[190:193], v[122:125]
	v_mfma_f32_16x16x32_bf16 v[114:117], v[158:161], v[198:201], v[114:117]
	v_mfma_f32_16x16x32_bf16 v[106:109], v[166:169], v[198:201], v[106:109]
	v_mfma_f32_16x16x32_bf16 v[98:101], v[158:161], v[206:209], v[98:101]
	v_mfma_f32_16x16x32_bf16 v[90:93], v[166:169], v[206:209], v[90:93]
	v_mfma_f32_16x16x32_bf16 v[82:85], v[158:161], v[214:217], v[82:85]
	v_mfma_f32_16x16x32_bf16 v[74:77], v[166:169], v[214:217], v[74:77]
	s_setprio 0
	s_setprio 1
	v_mfma_f32_16x16x32_bf16 v[118:121], v[170:173], v[186:189], v[118:121]
	v_mfma_f32_16x16x32_bf16 v[110:113], v[178:181], v[186:189], v[110:113]
	v_mfma_f32_16x16x32_bf16 v[102:105], v[170:173], v[194:197], v[102:105]
	v_mfma_f32_16x16x32_bf16 v[94:97], v[178:181], v[194:197], v[94:97]
	v_mfma_f32_16x16x32_bf16 v[86:89], v[170:173], v[202:205], v[86:89]
	v_mfma_f32_16x16x32_bf16 v[78:81], v[178:181], v[202:205], v[78:81]
	v_mfma_f32_16x16x32_bf16 v[70:73], v[170:173], v[210:213], v[70:73]
	v_mfma_f32_16x16x32_bf16 v[66:69], v[178:181], v[210:213], v[66:69]
	v_mfma_f32_16x16x32_bf16 v[118:121], v[174:177], v[190:193], v[118:121]
	v_mfma_f32_16x16x32_bf16 v[110:113], v[182:185], v[190:193], v[110:113]
	v_mfma_f32_16x16x32_bf16 v[102:105], v[174:177], v[198:201], v[102:105]
	v_mfma_f32_16x16x32_bf16 v[94:97], v[182:185], v[198:201], v[94:97]
	v_mfma_f32_16x16x32_bf16 v[86:89], v[174:177], v[206:209], v[86:89]
	v_mfma_f32_16x16x32_bf16 v[78:81], v[182:185], v[206:209], v[78:81]
	v_mfma_f32_16x16x32_bf16 v[70:73], v[174:177], v[214:217], v[70:73]
	v_mfma_f32_16x16x32_bf16 v[66:69], v[182:185], v[214:217], v[66:69]
	s_setprio 0
	s_barrier
	s_add_i32 s4, s62, s48
	s_mov_b32 m0, s4
	ds_read_b128 v[186:189], v152 offset:16384
	ds_read_b128 v[190:193], v152 offset:17408
	ds_read_b128 v[194:197], v152 offset:18432
	ds_read_b128 v[198:201], v152 offset:19456
	ds_read_b128 v[202:205], v152 offset:20480
	ds_read_b128 v[206:209], v152 offset:21504
	ds_read_b128 v[210:213], v152 offset:22528
	ds_read_b128 v[214:217], v152 offset:23552
	global_load_lds_dwordx4 v132, s[36:37]
	s_add_i32 m0, s4, 0x2000
	s_add_u32 s4, s36, 0x160000
	s_addc_u32 s5, s37, 0
	s_add_i32 s30, s63, s48
	global_load_lds_dwordx4 v136, s[36:37]
	s_mov_b32 m0, s30
	s_nop 0
	global_load_lds_dwordx4 v132, s[4:5]
	s_add_i32 m0, s30, 0x2000
	s_nop 0
	global_load_lds_dwordx4 v136, s[4:5]
	s_waitcnt vmcnt(6)
	s_waitcnt lgkmcnt(0)
	s_barrier
	s_setprio 1
	s_waitcnt lgkmcnt(0)
	v_mfma_f32_16x16x32_bf16 v[62:65], v[154:157], v[186:189], v[62:65]
	v_mfma_f32_16x16x32_bf16 v[58:61], v[162:165], v[186:189], v[58:61]
	v_mfma_f32_16x16x32_bf16 v[50:53], v[154:157], v[194:197], v[50:53]
	v_mfma_f32_16x16x32_bf16 v[42:45], v[162:165], v[194:197], v[42:45]
	v_mfma_f32_16x16x32_bf16 v[34:37], v[154:157], v[202:205], v[34:37]
	v_mfma_f32_16x16x32_bf16 v[26:29], v[162:165], v[202:205], v[26:29]
	v_mfma_f32_16x16x32_bf16 v[18:21], v[154:157], v[210:213], v[18:21]
	v_mfma_f32_16x16x32_bf16 v[10:13], v[162:165], v[210:213], v[10:13]
	v_mfma_f32_16x16x32_bf16 v[62:65], v[158:161], v[190:193], v[62:65]
	v_mfma_f32_16x16x32_bf16 v[58:61], v[166:169], v[190:193], v[58:61]
	v_mfma_f32_16x16x32_bf16 v[50:53], v[158:161], v[198:201], v[50:53]
	v_mfma_f32_16x16x32_bf16 v[42:45], v[166:169], v[198:201], v[42:45]
	v_mfma_f32_16x16x32_bf16 v[34:37], v[158:161], v[206:209], v[34:37]
	v_mfma_f32_16x16x32_bf16 v[26:29], v[166:169], v[206:209], v[26:29]
	v_mfma_f32_16x16x32_bf16 v[18:21], v[158:161], v[214:217], v[18:21]
	v_mfma_f32_16x16x32_bf16 v[10:13], v[166:169], v[214:217], v[10:13]
	s_setprio 0
	s_setprio 1
	v_mfma_f32_16x16x32_bf16 v[54:57], v[170:173], v[186:189], v[54:57]
	v_mfma_f32_16x16x32_bf16 v[46:49], v[178:181], v[186:189], v[46:49]
	v_mfma_f32_16x16x32_bf16 v[38:41], v[170:173], v[194:197], v[38:41]
	v_mfma_f32_16x16x32_bf16 v[30:33], v[178:181], v[194:197], v[30:33]
	v_mfma_f32_16x16x32_bf16 v[22:25], v[170:173], v[202:205], v[22:25]
	v_mfma_f32_16x16x32_bf16 v[14:17], v[178:181], v[202:205], v[14:17]
	v_mfma_f32_16x16x32_bf16 v[6:9], v[170:173], v[210:213], v[6:9]
	v_mfma_f32_16x16x32_bf16 v[2:5], v[178:181], v[210:213], v[2:5]
	v_mfma_f32_16x16x32_bf16 v[54:57], v[174:177], v[190:193], v[54:57]
	v_mfma_f32_16x16x32_bf16 v[46:49], v[182:185], v[190:193], v[46:49]
	v_mfma_f32_16x16x32_bf16 v[38:41], v[174:177], v[198:201], v[38:41]
	v_mfma_f32_16x16x32_bf16 v[30:33], v[182:185], v[198:201], v[30:33]
	v_mfma_f32_16x16x32_bf16 v[22:25], v[174:177], v[206:209], v[22:25]
	v_mfma_f32_16x16x32_bf16 v[14:17], v[182:185], v[206:209], v[14:17]
	v_mfma_f32_16x16x32_bf16 v[6:9], v[174:177], v[214:217], v[6:9]
	v_mfma_f32_16x16x32_bf16 v[2:5], v[182:185], v[214:217], v[2:5]
	s_setprio 0
	s_barrier
; #define PG8_STAGE(bufoff, gbase, voff) do { _Pragma("unroll") for (int _i = 0; _i < 2; ++_i) \
;         __builtin_amdgcn_global_load_lds((const unsigned*)((const char*)(gbase) + (voff)[_i]), (PG8_LAS unsigned*)(lds + (bufoff) + ldsw + _i * 8192), 16, 0, 0); } while (0)
; #define PG8_LDA(dst, b, h) do { _Pragma("unroll") for (int m = 0; m < 4; ++m) _Pragma("unroll") for (int k = 0; k < 2; ++k) dst[m][k] = *(const PG8_LAS bf16x8*)(lds + PG8_SA(b, h) + aoff + m * 2048 + k * 1024); } while (0)
; #define PG8_LDB(dst, b, h) do { _Pragma("unroll") for (int n = 0; n < 2; ++n) _Pragma("unroll") for (int k = 0; k < 2; ++k) dst[n][k] = *(const PG8_LAS bf16x8*)(lds + PG8_SB(b, h) + boff + n * 2048 + k * 1024); } while (0)
; #define PG8_MMA(ai, bj, At, Bt) do { __builtin_amdgcn_s_setprio(1); _Pragma("unroll") for (int m = 0; m < 4; ++m) _Pragma("unroll") for (int n = 0; n < 2; ++n) _Pragma("unroll") for (int k = 0; k < 2; ++k) \
;         acc[ai][bj][m][n] = __builtin_amdgcn_mfma_f32_16x16x32_bf16(Bt[n][k], At[m][k], acc[ai][bj][m][n], 0, 0, 0); __builtin_amdgcn_s_setprio(0); } while (0)
; #define PG8_WAIT_V(n) asm volatile("s_waitcnt vmcnt(" #n ")" ::: "memory")
; #define PG8_WAIT_L(n) asm volatile("s_waitcnt lgkmcnt(" #n ")" ::: "memory")
; #define PG8_BAR __builtin_amdgcn_s_barrier()
; template <class Epi, class Sched, bool ALIGN_EPI = false, bool SP2 = false>
; __device__ __forceinline__ void gemm_phase(PG8_LAS unsigned char* lds, const Gemm g, const Sched& S, const Epi& E) {
;     ...
;         for (int t = 0; t < nt; t += 2) {
;             const bool last = (t == nt - 2);
;             const char* a1 = cA + (size_t)(t + 1) * kstep;
;             const char* a2 = last ? nA : cA + (size_t)(t + 2) * kstep; const char* b2 = last ? nB : cB + (size_t)(t + 2) * kstep;
;             const char* a3 = a2 + kstep; const char* b3 = b2 + kstep;
;     ...
;             PG8_LDB(B0, 1, 0); PG8_LDB(B1, 1, 1); PG8_SCHED; PG8_LDA(At, 1, 0); PG8_STAGE(PG8_SA(0, 1), a2 + hstep, voffA);
;             PG8_WAIT_V(8); PG8_WAIT_L(0); PG8_BAR; PG8_MMA(0, 0, At, B0); PG8_MMA(0, 1, At, B1); PG8_BAR; PG8_SCHED;
;             PG8_LDA(At, 1, 1); PG8_STAGE(PG8_SB(1, 0), b3, voffB); PG8_STAGE(PG8_SB(1, 1), b3 + hstep, voffB); PG8_STAGE(PG8_SA(1, 0), a3, voffA);
;             PG8_WAIT_V(8); PG8_WAIT_L(0); PG8_BAR; PG8_MMA(1, 0, At, B0); PG8_MMA(1, 1, At, B1); PG8_BAR; PG8_SCHED;
	s_add_i32 s30, 0, 0x18000
	v_add_u32_e32 v153, s30, v148
	s_add_i32 s31, 0, 0x1c000
	ds_read_b128 v[154:157], v153
	ds_read_b128 v[158:161], v153 offset:1024
	ds_read_b128 v[162:165], v153 offset:2048
	ds_read_b128 v[166:169], v153 offset:3072
	v_add_u32_e32 v153, s31, v148
	ds_read_b128 v[170:173], v153
	ds_read_b128 v[174:177], v153 offset:1024
	ds_read_b128 v[178:181], v153 offset:2048
	ds_read_b128 v[182:185], v153 offset:3072
	s_add_u32 s4, s38, 0x160000
	s_addc_u32 s5, s39, 0
	s_mov_b32 m0, s49
	s_nop 0
	global_load_lds_dwordx4 v130, s[38:39]
	s_mov_b32 m0, s50
	s_nop 0
	global_load_lds_dwordx4 v134, s[38:39]
	s_mov_b32 m0, s51
	ds_read_b128 v[186:189], v152 offset:32768
	ds_read_b128 v[190:193], v152 offset:33792
	ds_read_b128 v[194:197], v152 offset:34816
	ds_read_b128 v[198:201], v152 offset:35840
	ds_read_b128 v[202:205], v152 offset:36864
	ds_read_b128 v[206:209], v152 offset:37888
	ds_read_b128 v[210:213], v152 offset:38912
	ds_read_b128 v[214:217], v152 offset:39936
	global_load_lds_dwordx4 v130, s[4:5]
	s_mov_b32 m0, s52
	s_nop 0
	global_load_lds_dwordx4 v134, s[4:5]
	s_waitcnt vmcnt(8)
	s_waitcnt lgkmcnt(0)
	s_barrier
	s_setprio 1
	s_waitcnt lgkmcnt(0)
	v_mfma_f32_16x16x32_bf16 v[126:129], v[154:157], v[186:189], v[126:129]
	v_mfma_f32_16x16x32_bf16 v[122:125], v[162:165], v[186:189], v[122:125]
	v_mfma_f32_16x16x32_bf16 v[114:117], v[154:157], v[194:197], v[114:117]
	v_mfma_f32_16x16x32_bf16 v[106:109], v[162:165], v[194:197], v[106:109]
	v_mfma_f32_16x16x32_bf16 v[98:101], v[154:157], v[202:205], v[98:101]
	v_mfma_f32_16x16x32_bf16 v[90:93], v[162:165], v[202:205], v[90:93]
	v_mfma_f32_16x16x32_bf16 v[82:85], v[154:157], v[210:213], v[82:85]
	v_mfma_f32_16x16x32_bf16 v[74:77], v[162:165], v[210:213], v[74:77]
	v_mfma_f32_16x16x32_bf16 v[126:129], v[158:161], v[190:193], v[126:129]
	v_mfma_f32_16x16x32_bf16 v[122:125], v[166:169], v[190:193], v[122:125]
	v_mfma_f32_16x16x32_bf16 v[114:117], v[158:161], v[198:201], v[114:117]
	v_mfma_f32_16x16x32_bf16 v[106:109], v[166:169], v[198:201], v[106:109]
	v_mfma_f32_16x16x32_bf16 v[98:101], v[158:161], v[206:209], v[98:101]
	v_mfma_f32_16x16x32_bf16 v[90:93], v[166:169], v[206:209], v[90:93]
	v_mfma_f32_16x16x32_bf16 v[82:85], v[158:161], v[214:217], v[82:85]
	v_mfma_f32_16x16x32_bf16 v[74:77], v[166:169], v[214:217], v[74:77]
	s_setprio 0
	s_setprio 1
	v_mfma_f32_16x16x32_bf16 v[118:121], v[170:173], v[186:189], v[118:121]
	v_mfma_f32_16x16x32_bf16 v[110:113], v[178:181], v[186:189], v[110:113]
	v_mfma_f32_16x16x32_bf16 v[102:105], v[170:173], v[194:197], v[102:105]
	v_mfma_f32_16x16x32_bf16 v[94:97], v[178:181], v[194:197], v[94:97]
	v_mfma_f32_16x16x32_bf16 v[86:89], v[170:173], v[202:205], v[86:89]
	v_mfma_f32_16x16x32_bf16 v[78:81], v[178:181], v[202:205], v[78:81]
	v_mfma_f32_16x16x32_bf16 v[70:73], v[170:173], v[210:213], v[70:73]
	v_mfma_f32_16x16x32_bf16 v[66:69], v[178:181], v[210:213], v[66:69]
	v_mfma_f32_16x16x32_bf16 v[118:121], v[174:177], v[190:193], v[118:121]
	v_mfma_f32_16x16x32_bf16 v[110:113], v[182:185], v[190:193], v[110:113]
	v_mfma_f32_16x16x32_bf16 v[102:105], v[174:177], v[198:201], v[102:105]
	v_mfma_f32_16x16x32_bf16 v[94:97], v[182:185], v[198:201], v[94:97]
	v_mfma_f32_16x16x32_bf16 v[86:89], v[174:177], v[206:209], v[86:89]
	v_mfma_f32_16x16x32_bf16 v[78:81], v[182:185], v[206:209], v[78:81]
	v_mfma_f32_16x16x32_bf16 v[70:73], v[174:177], v[214:217], v[70:73]
	v_mfma_f32_16x16x32_bf16 v[66:69], v[182:185], v[214:217], v[66:69]
	s_setprio 0
	s_barrier
	s_add_i32 s4, s30, s48
	s_add_i32 m0, s4, 0xffffff80
	ds_read_b128 v[186:189], v152 offset:49152
	ds_read_b128 v[190:193], v152 offset:50176
	ds_read_b128 v[194:197], v152 offset:51200
	ds_read_b128 v[198:201], v152 offset:52224
	ds_read_b128 v[202:205], v152 offset:53248
	ds_read_b128 v[206:209], v152 offset:54272
	ds_read_b128 v[210:213], v152 offset:55296
	ds_read_b128 v[214:217], v152 offset:56320
	global_load_lds_dwordx4 v132, s[36:37] offset:128
	s_add_i32 m0, s4, 0x1f80
	s_add_u32 s4, s36, 0x160080
	s_addc_u32 s5, s37, 0
	s_add_i32 s30, s31, s48
	global_load_lds_dwordx4 v136, s[36:37] offset:128
	s_mov_b32 m0, s30
	s_nop 0
	global_load_lds_dwordx4 v132, s[4:5]
	s_add_i32 m0, s30, 0x2000
	s_nop 0
	global_load_lds_dwordx4 v136, s[4:5]
	s_add_i32 m0, s58, 0xffffff80
	s_nop 0
	global_load_lds_dwordx4 v130, s[38:39] offset:128
	s_add_i32 m0, s59, 0xffffff80
	s_nop 0
	global_load_lds_dwordx4 v134, s[38:39] offset:128
	s_waitcnt vmcnt(8)
	s_waitcnt lgkmcnt(0)
	s_barrier
	s_setprio 1
	s_waitcnt lgkmcnt(0)
	v_mfma_f32_16x16x32_bf16 v[62:65], v[154:157], v[186:189], v[62:65]
	v_mfma_f32_16x16x32_bf16 v[58:61], v[162:165], v[186:189], v[58:61]
	v_mfma_f32_16x16x32_bf16 v[50:53], v[154:157], v[194:197], v[50:53]
	v_mfma_f32_16x16x32_bf16 v[42:45], v[162:165], v[194:197], v[42:45]
	v_mfma_f32_16x16x32_bf16 v[34:37], v[154:157], v[202:205], v[34:37]
	v_mfma_f32_16x16x32_bf16 v[26:29], v[162:165], v[202:205], v[26:29]
	v_mfma_f32_16x16x32_bf16 v[18:21], v[154:157], v[210:213], v[18:21]
	v_mfma_f32_16x16x32_bf16 v[10:13], v[162:165], v[210:213], v[10:13]
	v_mfma_f32_16x16x32_bf16 v[62:65], v[158:161], v[190:193], v[62:65]
	v_mfma_f32_16x16x32_bf16 v[58:61], v[166:169], v[190:193], v[58:61]
	v_mfma_f32_16x16x32_bf16 v[50:53], v[158:161], v[198:201], v[50:53]
	v_mfma_f32_16x16x32_bf16 v[42:45], v[166:169], v[198:201], v[42:45]
	v_mfma_f32_16x16x32_bf16 v[34:37], v[158:161], v[206:209], v[34:37]
	v_mfma_f32_16x16x32_bf16 v[26:29], v[166:169], v[206:209], v[26:29]
	v_mfma_f32_16x16x32_bf16 v[18:21], v[158:161], v[214:217], v[18:21]
	v_mfma_f32_16x16x32_bf16 v[10:13], v[166:169], v[214:217], v[10:13]
	s_setprio 0
	s_setprio 1
	v_mfma_f32_16x16x32_bf16 v[54:57], v[170:173], v[186:189], v[54:57]
	v_mfma_f32_16x16x32_bf16 v[46:49], v[178:181], v[186:189], v[46:49]
	v_mfma_f32_16x16x32_bf16 v[38:41], v[170:173], v[194:197], v[38:41]
	v_mfma_f32_16x16x32_bf16 v[30:33], v[178:181], v[194:197], v[30:33]
	v_mfma_f32_16x16x32_bf16 v[22:25], v[170:173], v[202:205], v[22:25]
	v_mfma_f32_16x16x32_bf16 v[14:17], v[178:181], v[202:205], v[14:17]
	v_mfma_f32_16x16x32_bf16 v[6:9], v[170:173], v[210:213], v[6:9]
	v_mfma_f32_16x16x32_bf16 v[2:5], v[178:181], v[210:213], v[2:5]
	v_mfma_f32_16x16x32_bf16 v[54:57], v[174:177], v[190:193], v[54:57]
	v_mfma_f32_16x16x32_bf16 v[46:49], v[182:185], v[190:193], v[46:49]
	v_mfma_f32_16x16x32_bf16 v[38:41], v[174:177], v[198:201], v[38:41]
	v_mfma_f32_16x16x32_bf16 v[30:33], v[182:185], v[198:201], v[30:33]
	v_mfma_f32_16x16x32_bf16 v[22:25], v[174:177], v[206:209], v[22:25]
	v_mfma_f32_16x16x32_bf16 v[14:17], v[182:185], v[206:209], v[14:17]
	v_mfma_f32_16x16x32_bf16 v[6:9], v[174:177], v[214:217], v[6:9]
	v_mfma_f32_16x16x32_bf16 v[2:5], v[182:185], v[214:217], v[2:5]
	s_setprio 0
	s_add_i32 s74, s74, 2
	s_add_u32 s72, s72, 0x100
	s_addc_u32 s73, s73, 0
	s_cmpk_gt_u32 s74, 0x55
	s_mov_b64 s[30:31], s[34:35]
	s_barrier
	s_cbranch_scc0 .LBB0_1017
	s_and_b64 vcc, exec, s[18:19]
	s_cbranch_vccz .LBB0_1020
	s_barrier
